# non-temporal (nt) epilogue stores on the bf16-output GEMM phases (1, 8, 11, 17, 3, 14); otherwise identical to the previous best
# speedup vs baseline: 1.0499x; 1.0062x over previous
; DI void st_bf16x4(bf16_t* o, f32x4 v) { u32x2 q; q.x = pack2(v[0], v[1]); q.y = pack2(v[2], v[3]); *(u32x2*)o = q; }
; template <class Epi>
; DI void gemm_tile(char* smem, const bf16_t* __restrict__ A0, int lda0, int ksplit, const bf16_t* __restrict__ A1, int lda1,
;                   const bf16_t* __restrict__ Bt, int K, int row0, int col0, const Epi& epi, int tid) {
;     ...
; #pragma unroll
;   for (int m = 0; m < 8; ++m)
; #pragma unroll
;     for (int n = 0; n < 4; ++n) epi(row0 + wr * 128 + m * 16 + fr, col0 + wc * 64 + n * 16 + fq * 4, acc[m][n]);
;   DI void operator()(int row, int col, f32x4 v) const {
;     if (col < n0) st_bf16x4(o0 + (size_t)row * ld0 + col, v);
;     else { const int c = col - n0; if (c < n1) st_bf16x4(o1 + (size_t)row * ld1 + c, v); }
;   }
.Lg1_epi:
	s_nop 7
	s_nop 7
	s_cmpk_ge_u32 s24, 1792
	s_cbranch_scc1 .Lg1_eo1
	s_mul_i32 s23, s25, 3584
	s_lshl_b32 s22, s24, 1
	s_add_u32 s23, s23, s22
	s_add_u32 s23, s23, 0x7800000
	s_add_u32 s4, s92, s23
	s_addc_u32 s5, s93, 0
	v_cvt_pk_bf16_f32 v128, v0, v1
	v_cvt_pk_bf16_f32 v129, v2, v3
	ds_write_b64 v236, v[128:129]
	v_cvt_pk_bf16_f32 v130, v4, v5
	v_cvt_pk_bf16_f32 v131, v6, v7
	ds_write_b64 v236, v[130:131] offset:32
	v_cvt_pk_bf16_f32 v132, v8, v9
	v_cvt_pk_bf16_f32 v133, v10, v11
	ds_write_b64 v236, v[132:133] offset:64
	v_cvt_pk_bf16_f32 v134, v12, v13
	v_cvt_pk_bf16_f32 v135, v14, v15
	ds_write_b64 v236, v[134:135] offset:96
	v_cvt_pk_bf16_f32 v136, v16, v17
	v_cvt_pk_bf16_f32 v137, v18, v19
	ds_write_b64 v236, v[136:137] offset:2304
	v_cvt_pk_bf16_f32 v138, v20, v21
	v_cvt_pk_bf16_f32 v139, v22, v23
	ds_write_b64 v236, v[138:139] offset:2336
	v_cvt_pk_bf16_f32 v140, v24, v25
	v_cvt_pk_bf16_f32 v141, v26, v27
	ds_write_b64 v236, v[140:141] offset:2368
	v_cvt_pk_bf16_f32 v142, v28, v29
	v_cvt_pk_bf16_f32 v143, v30, v31
	ds_write_b64 v236, v[142:143] offset:2400
	v_cvt_pk_bf16_f32 v144, v32, v33
	v_cvt_pk_bf16_f32 v145, v34, v35
	ds_write_b64 v236, v[144:145] offset:4608
	v_cvt_pk_bf16_f32 v146, v36, v37
	v_cvt_pk_bf16_f32 v147, v38, v39
	ds_write_b64 v236, v[146:147] offset:4640
	v_cvt_pk_bf16_f32 v148, v40, v41
	v_cvt_pk_bf16_f32 v149, v42, v43
	ds_write_b64 v236, v[148:149] offset:4672
	v_cvt_pk_bf16_f32 v150, v44, v45
	v_cvt_pk_bf16_f32 v151, v46, v47
	ds_write_b64 v236, v[150:151] offset:4704
	v_cvt_pk_bf16_f32 v152, v48, v49
	v_cvt_pk_bf16_f32 v153, v50, v51
	ds_write_b64 v236, v[152:153] offset:6912
	v_cvt_pk_bf16_f32 v154, v52, v53
	v_cvt_pk_bf16_f32 v155, v54, v55
	ds_write_b64 v236, v[154:155] offset:6944
	v_cvt_pk_bf16_f32 v156, v56, v57
	v_cvt_pk_bf16_f32 v157, v58, v59
	ds_write_b64 v236, v[156:157] offset:6976
	v_cvt_pk_bf16_f32 v158, v60, v61
	v_cvt_pk_bf16_f32 v159, v62, v63
	ds_write_b64 v236, v[158:159] offset:7008
	v_cvt_pk_bf16_f32 v128, v64, v65
	v_cvt_pk_bf16_f32 v129, v66, v67
	ds_write_b64 v236, v[128:129] offset:9216
	v_cvt_pk_bf16_f32 v130, v68, v69
	v_cvt_pk_bf16_f32 v131, v70, v71
	ds_write_b64 v236, v[130:131] offset:9248
	v_cvt_pk_bf16_f32 v132, v72, v73
	v_cvt_pk_bf16_f32 v133, v74, v75
	ds_write_b64 v236, v[132:133] offset:9280
	v_cvt_pk_bf16_f32 v134, v76, v77
	v_cvt_pk_bf16_f32 v135, v78, v79
	ds_write_b64 v236, v[134:135] offset:9312
	v_cvt_pk_bf16_f32 v136, v80, v81
	v_cvt_pk_bf16_f32 v137, v82, v83
	ds_write_b64 v236, v[136:137] offset:11520
	v_cvt_pk_bf16_f32 v138, v84, v85
	v_cvt_pk_bf16_f32 v139, v86, v87
	ds_write_b64 v236, v[138:139] offset:11552
	v_cvt_pk_bf16_f32 v140, v88, v89
	v_cvt_pk_bf16_f32 v141, v90, v91
	ds_write_b64 v236, v[140:141] offset:11584
	v_cvt_pk_bf16_f32 v142, v92, v93
	v_cvt_pk_bf16_f32 v143, v94, v95
	ds_write_b64 v236, v[142:143] offset:11616
	v_cvt_pk_bf16_f32 v144, v96, v97
	v_cvt_pk_bf16_f32 v145, v98, v99
	ds_write_b64 v236, v[144:145] offset:13824
	v_cvt_pk_bf16_f32 v146, v100, v101
	v_cvt_pk_bf16_f32 v147, v102, v103
	ds_write_b64 v236, v[146:147] offset:13856
	v_cvt_pk_bf16_f32 v148, v104, v105
	v_cvt_pk_bf16_f32 v149, v106, v107
	ds_write_b64 v236, v[148:149] offset:13888
	v_cvt_pk_bf16_f32 v150, v108, v109
	v_cvt_pk_bf16_f32 v151, v110, v111
	ds_write_b64 v236, v[150:151] offset:13920
	v_cvt_pk_bf16_f32 v152, v112, v113
	v_cvt_pk_bf16_f32 v153, v114, v115
	ds_write_b64 v236, v[152:153] offset:16128
	v_cvt_pk_bf16_f32 v154, v116, v117
	v_cvt_pk_bf16_f32 v155, v118, v119
	ds_write_b64 v236, v[154:155] offset:16160
	v_cvt_pk_bf16_f32 v156, v120, v121
	v_cvt_pk_bf16_f32 v157, v122, v123
	ds_write_b64 v236, v[156:157] offset:16192
	v_cvt_pk_bf16_f32 v158, v124, v125
	v_cvt_pk_bf16_f32 v159, v126, v127
	ds_write_b64 v236, v[158:159] offset:16224
	s_waitcnt lgkmcnt(0)
	ds_read_b128 v[128:131], v237
	ds_read_b128 v[132:135], v237 offset:1152
	ds_read_b128 v[136:139], v237 offset:2304
	ds_read_b128 v[140:143], v237 offset:3456
	ds_read_b128 v[144:147], v237 offset:4608
	ds_read_b128 v[148:151], v237 offset:5760
	ds_read_b128 v[152:155], v237 offset:6912
	ds_read_b128 v[156:159], v237 offset:8064
	ds_read_b128 v[160:163], v237 offset:9216
	ds_read_b128 v[164:167], v237 offset:10368
	ds_read_b128 v[168:171], v237 offset:11520
	ds_read_b128 v[172:175], v237 offset:12672
	ds_read_b128 v[176:179], v237 offset:13824
	ds_read_b128 v[180:183], v237 offset:14976
	ds_read_b128 v[184:187], v237 offset:16128
	ds_read_b128 v[188:191], v237 offset:17280
	s_waitcnt lgkmcnt(15)
	global_store_dwordx4 v238, v[128:131], s[4:5] nt
	s_add_u32 s4, s4, 0x7000
	s_addc_u32 s5, s5, 0
	s_waitcnt lgkmcnt(14)
	global_store_dwordx4 v238, v[132:135], s[4:5] nt
	s_add_u32 s4, s4, 0x7000
	s_addc_u32 s5, s5, 0
	s_waitcnt lgkmcnt(13)
	global_store_dwordx4 v238, v[136:139], s[4:5] nt
	s_add_u32 s4, s4, 0x7000
	s_addc_u32 s5, s5, 0
	s_waitcnt lgkmcnt(12)
	global_store_dwordx4 v238, v[140:143], s[4:5] nt
	s_add_u32 s4, s4, 0x7000
	s_addc_u32 s5, s5, 0
	s_waitcnt lgkmcnt(11)
	global_store_dwordx4 v238, v[144:147], s[4:5] nt
	s_add_u32 s4, s4, 0x7000
	s_addc_u32 s5, s5, 0
	s_waitcnt lgkmcnt(10)
	global_store_dwordx4 v238, v[148:151], s[4:5] nt
	s_add_u32 s4, s4, 0x7000
	s_addc_u32 s5, s5, 0
	s_waitcnt lgkmcnt(9)
	global_store_dwordx4 v238, v[152:155], s[4:5] nt
	s_add_u32 s4, s4, 0x7000
	s_addc_u32 s5, s5, 0
	s_waitcnt lgkmcnt(8)
	global_store_dwordx4 v238, v[156:159], s[4:5] nt
	s_add_u32 s4, s4, 0x7000
	s_addc_u32 s5, s5, 0
	s_waitcnt lgkmcnt(7)
	global_store_dwordx4 v238, v[160:163], s[4:5] nt
	s_add_u32 s4, s4, 0x7000
	s_addc_u32 s5, s5, 0
	s_waitcnt lgkmcnt(6)
	global_store_dwordx4 v238, v[164:167], s[4:5] nt
	s_add_u32 s4, s4, 0x7000
	s_addc_u32 s5, s5, 0
	s_waitcnt lgkmcnt(5)
	global_store_dwordx4 v238, v[168:171], s[4:5] nt
	s_add_u32 s4, s4, 0x7000
	s_addc_u32 s5, s5, 0
	s_waitcnt lgkmcnt(4)
	global_store_dwordx4 v238, v[172:175], s[4:5] nt
	s_add_u32 s4, s4, 0x7000
	s_addc_u32 s5, s5, 0
	s_waitcnt lgkmcnt(3)
	global_store_dwordx4 v238, v[176:179], s[4:5] nt
	s_add_u32 s4, s4, 0x7000
	s_addc_u32 s5, s5, 0
	s_waitcnt lgkmcnt(2)
	global_store_dwordx4 v238, v[180:183], s[4:5] nt
	s_add_u32 s4, s4, 0x7000
	s_addc_u32 s5, s5, 0
	s_waitcnt lgkmcnt(1)
	global_store_dwordx4 v238, v[184:187], s[4:5] nt
	s_add_u32 s4, s4, 0x7000
	s_addc_u32 s5, s5, 0
	s_waitcnt lgkmcnt(0)
	global_store_dwordx4 v238, v[188:191], s[4:5] nt
	s_nop 1
	s_branch .Lg1_enext
; DI void st_bf16x4(bf16_t* o, f32x4 v) { u32x2 q; q.x = pack2(v[0], v[1]); q.y = pack2(v[2], v[3]); *(u32x2*)o = q; }
; template <class Epi>
; DI void gemm_tile(char* smem, const bf16_t* __restrict__ A0, int lda0, int ksplit, const bf16_t* __restrict__ A1, int lda1,
;                   const bf16_t* __restrict__ Bt, int K, int row0, int col0, const Epi& epi, int tid) {
;     ...
; #pragma unroll
;   for (int m = 0; m < 8; ++m)
; #pragma unroll
;     for (int n = 0; n < 4; ++n) epi(row0 + wr * 128 + m * 16 + fr, col0 + wc * 64 + n * 16 + fq * 4, acc[m][n]);
;   DI void operator()(int row, int col, f32x4 v) const {
;     if (col < n0) st_bf16x4(o0 + (size_t)row * ld0 + col, v);
;     else { const int c = col - n0; if (c < n1) st_bf16x4(o1 + (size_t)row * ld1 + c, v); }
;   }
.Lg1_eo1:
	s_mul_i32 s23, s25, 5184
	s_sub_u32 s22, s24, 1792
	s_lshl_b32 s22, s22, 1
	s_add_u32 s23, s23, s22
	s_add_u32 s23, s23, 0xe800000
	s_add_u32 s4, s92, s23
	s_addc_u32 s5, s93, 0
	v_cvt_pk_bf16_f32 v128, v0, v1
	v_cvt_pk_bf16_f32 v129, v2, v3
	ds_write_b64 v236, v[128:129]
	v_cvt_pk_bf16_f32 v130, v4, v5
	v_cvt_pk_bf16_f32 v131, v6, v7
	ds_write_b64 v236, v[130:131] offset:32
	v_cvt_pk_bf16_f32 v132, v8, v9
	v_cvt_pk_bf16_f32 v133, v10, v11
	ds_write_b64 v236, v[132:133] offset:64
	v_cvt_pk_bf16_f32 v134, v12, v13
	v_cvt_pk_bf16_f32 v135, v14, v15
	ds_write_b64 v236, v[134:135] offset:96
	v_cvt_pk_bf16_f32 v136, v16, v17
	v_cvt_pk_bf16_f32 v137, v18, v19
	ds_write_b64 v236, v[136:137] offset:2304
	v_cvt_pk_bf16_f32 v138, v20, v21
	v_cvt_pk_bf16_f32 v139, v22, v23
	ds_write_b64 v236, v[138:139] offset:2336
	v_cvt_pk_bf16_f32 v140, v24, v25
	v_cvt_pk_bf16_f32 v141, v26, v27
	ds_write_b64 v236, v[140:141] offset:2368
	v_cvt_pk_bf16_f32 v142, v28, v29
	v_cvt_pk_bf16_f32 v143, v30, v31
	ds_write_b64 v236, v[142:143] offset:2400
	v_cvt_pk_bf16_f32 v144, v32, v33
	v_cvt_pk_bf16_f32 v145, v34, v35
	ds_write_b64 v236, v[144:145] offset:4608
	v_cvt_pk_bf16_f32 v146, v36, v37
	v_cvt_pk_bf16_f32 v147, v38, v39
	ds_write_b64 v236, v[146:147] offset:4640
	v_cvt_pk_bf16_f32 v148, v40, v41
	v_cvt_pk_bf16_f32 v149, v42, v43
	ds_write_b64 v236, v[148:149] offset:4672
	v_cvt_pk_bf16_f32 v150, v44, v45
	v_cvt_pk_bf16_f32 v151, v46, v47
	ds_write_b64 v236, v[150:151] offset:4704
	v_cvt_pk_bf16_f32 v152, v48, v49
	v_cvt_pk_bf16_f32 v153, v50, v51
	ds_write_b64 v236, v[152:153] offset:6912
	v_cvt_pk_bf16_f32 v154, v52, v53
	v_cvt_pk_bf16_f32 v155, v54, v55
	ds_write_b64 v236, v[154:155] offset:6944
	v_cvt_pk_bf16_f32 v156, v56, v57
	v_cvt_pk_bf16_f32 v157, v58, v59
	ds_write_b64 v236, v[156:157] offset:6976
	v_cvt_pk_bf16_f32 v158, v60, v61
	v_cvt_pk_bf16_f32 v159, v62, v63
	ds_write_b64 v236, v[158:159] offset:7008
	v_cvt_pk_bf16_f32 v128, v64, v65
	v_cvt_pk_bf16_f32 v129, v66, v67
	ds_write_b64 v236, v[128:129] offset:9216
	v_cvt_pk_bf16_f32 v130, v68, v69
	v_cvt_pk_bf16_f32 v131, v70, v71
	ds_write_b64 v236, v[130:131] offset:9248
	v_cvt_pk_bf16_f32 v132, v72, v73
	v_cvt_pk_bf16_f32 v133, v74, v75
	ds_write_b64 v236, v[132:133] offset:9280
	v_cvt_pk_bf16_f32 v134, v76, v77
	v_cvt_pk_bf16_f32 v135, v78, v79
	ds_write_b64 v236, v[134:135] offset:9312
	v_cvt_pk_bf16_f32 v136, v80, v81
	v_cvt_pk_bf16_f32 v137, v82, v83
	ds_write_b64 v236, v[136:137] offset:11520
	v_cvt_pk_bf16_f32 v138, v84, v85
	v_cvt_pk_bf16_f32 v139, v86, v87
	ds_write_b64 v236, v[138:139] offset:11552
	v_cvt_pk_bf16_f32 v140, v88, v89
	v_cvt_pk_bf16_f32 v141, v90, v91
	ds_write_b64 v236, v[140:141] offset:11584
	v_cvt_pk_bf16_f32 v142, v92, v93
	v_cvt_pk_bf16_f32 v143, v94, v95
	ds_write_b64 v236, v[142:143] offset:11616
	v_cvt_pk_bf16_f32 v144, v96, v97
	v_cvt_pk_bf16_f32 v145, v98, v99
	ds_write_b64 v236, v[144:145] offset:13824
	v_cvt_pk_bf16_f32 v146, v100, v101
	v_cvt_pk_bf16_f32 v147, v102, v103
	ds_write_b64 v236, v[146:147] offset:13856
	v_cvt_pk_bf16_f32 v148, v104, v105
	v_cvt_pk_bf16_f32 v149, v106, v107
	ds_write_b64 v236, v[148:149] offset:13888
	v_cvt_pk_bf16_f32 v150, v108, v109
	v_cvt_pk_bf16_f32 v151, v110, v111
	ds_write_b64 v236, v[150:151] offset:13920
	v_cvt_pk_bf16_f32 v152, v112, v113
	v_cvt_pk_bf16_f32 v153, v114, v115
	ds_write_b64 v236, v[152:153] offset:16128
	v_cvt_pk_bf16_f32 v154, v116, v117
	v_cvt_pk_bf16_f32 v155, v118, v119
	ds_write_b64 v236, v[154:155] offset:16160
	v_cvt_pk_bf16_f32 v156, v120, v121
	v_cvt_pk_bf16_f32 v157, v122, v123
	ds_write_b64 v236, v[156:157] offset:16192
	v_cvt_pk_bf16_f32 v158, v124, v125
	v_cvt_pk_bf16_f32 v159, v126, v127
	ds_write_b64 v236, v[158:159] offset:16224
	s_waitcnt lgkmcnt(0)
	ds_read_b128 v[128:131], v237
	ds_read_b128 v[132:135], v237 offset:1152
	ds_read_b128 v[136:139], v237 offset:2304
	ds_read_b128 v[140:143], v237 offset:3456
	ds_read_b128 v[144:147], v237 offset:4608
	ds_read_b128 v[148:151], v237 offset:5760
	ds_read_b128 v[152:155], v237 offset:6912
	ds_read_b128 v[156:159], v237 offset:8064
	ds_read_b128 v[160:163], v237 offset:9216
	ds_read_b128 v[164:167], v237 offset:10368
	ds_read_b128 v[168:171], v237 offset:11520
	ds_read_b128 v[172:175], v237 offset:12672
	ds_read_b128 v[176:179], v237 offset:13824
	ds_read_b128 v[180:183], v237 offset:14976
	ds_read_b128 v[184:187], v237 offset:16128
	ds_read_b128 v[188:191], v237 offset:17280
	s_sub_u32 s22, s24, 1792
	s_sub_u32 s22, 2592, s22
	v_cmp_gt_i32_e32 vcc, s22, v248
	s_and_saveexec_b64 s[2:3], vcc
	s_waitcnt lgkmcnt(15)
	global_store_dwordx4 v239, v[128:131], s[4:5] nt
	s_add_u32 s4, s4, 0xa200
	s_addc_u32 s5, s5, 0
	s_waitcnt lgkmcnt(14)
	global_store_dwordx4 v239, v[132:135], s[4:5] nt
	s_add_u32 s4, s4, 0xa200
	s_addc_u32 s5, s5, 0
	s_waitcnt lgkmcnt(13)
	global_store_dwordx4 v239, v[136:139], s[4:5] nt
	s_add_u32 s4, s4, 0xa200
	s_addc_u32 s5, s5, 0
	s_waitcnt lgkmcnt(12)
	global_store_dwordx4 v239, v[140:143], s[4:5] nt
	s_add_u32 s4, s4, 0xa200
	s_addc_u32 s5, s5, 0
	s_waitcnt lgkmcnt(11)
	global_store_dwordx4 v239, v[144:147], s[4:5] nt
	s_add_u32 s4, s4, 0xa200
	s_addc_u32 s5, s5, 0
	s_waitcnt lgkmcnt(10)
	global_store_dwordx4 v239, v[148:151], s[4:5] nt
	s_add_u32 s4, s4, 0xa200
	s_addc_u32 s5, s5, 0
	s_waitcnt lgkmcnt(9)
	global_store_dwordx4 v239, v[152:155], s[4:5] nt
	s_add_u32 s4, s4, 0xa200
	s_addc_u32 s5, s5, 0
	s_waitcnt lgkmcnt(8)
	global_store_dwordx4 v239, v[156:159], s[4:5] nt
	s_add_u32 s4, s4, 0xa200
	s_addc_u32 s5, s5, 0
	s_waitcnt lgkmcnt(7)
	global_store_dwordx4 v239, v[160:163], s[4:5] nt
	s_add_u32 s4, s4, 0xa200
	s_addc_u32 s5, s5, 0
	s_waitcnt lgkmcnt(6)
	global_store_dwordx4 v239, v[164:167], s[4:5] nt
	s_add_u32 s4, s4, 0xa200
	s_addc_u32 s5, s5, 0
	s_waitcnt lgkmcnt(5)
	global_store_dwordx4 v239, v[168:171], s[4:5] nt
	s_add_u32 s4, s4, 0xa200
	s_addc_u32 s5, s5, 0
	s_waitcnt lgkmcnt(4)
	global_store_dwordx4 v239, v[172:175], s[4:5] nt
	s_add_u32 s4, s4, 0xa200
	s_addc_u32 s5, s5, 0
	s_waitcnt lgkmcnt(3)
	global_store_dwordx4 v239, v[176:179], s[4:5] nt
	s_add_u32 s4, s4, 0xa200
	s_addc_u32 s5, s5, 0
	s_waitcnt lgkmcnt(2)
	global_store_dwordx4 v239, v[180:183], s[4:5] nt
	s_add_u32 s4, s4, 0xa200
	s_addc_u32 s5, s5, 0
	s_waitcnt lgkmcnt(1)
	global_store_dwordx4 v239, v[184:187], s[4:5] nt
	s_add_u32 s4, s4, 0xa200
	s_addc_u32 s5, s5, 0
	s_waitcnt lgkmcnt(0)
	global_store_dwordx4 v239, v[188:191], s[4:5] nt
	s_or_b64 exec, exec, s[2:3]
	s_nop 1

; DI void phase_rw_small_gemms(const Ctx& c, char* smem) {
;     ...
;   gemm_phase(smem, sm, 256, 1 << 30, sm, 256, W2, 64, 4, EpiSmall{0, p.rw_w0, E0}, tid);
.Lg3a_epi:
	s_nop 7
	s_nop 7
	s_mul_i32 s27, s29, 1024
	s_lshl_b32 s26, s28, 1
	s_add_u32 s27, s27, s26
	s_add_u32 s27, s27, 0x7800000
	s_add_u32 s4, s92, s27
	s_addc_u32 s5, s93, 0
	s_lshl_b32 s27, s28, 2
	s_add_u32 s27, s27, 0x0
	s_add_u32 s2, s6, s27
	s_addc_u32 s3, s7, 0
	global_load_dwordx4 v[192:195], v235, s[2:3] offset:0
	global_load_dwordx4 v[196:199], v235, s[2:3] offset:64
	global_load_dwordx4 v[200:203], v235, s[2:3] offset:128
	global_load_dwordx4 v[204:207], v235, s[2:3] offset:192
	s_waitcnt vmcnt(0)
	v_add_f32_e32 v0, v0, v192
	v_add_f32_e32 v1, v1, v193
	v_add_f32_e32 v2, v2, v194
	v_add_f32_e32 v3, v3, v195
	v_mul_f32_e32 v0, 0xbfb8aa3b, v0
	v_mul_f32_e32 v1, 0xbfb8aa3b, v1
	v_mul_f32_e32 v2, 0xbfb8aa3b, v2
	v_mul_f32_e32 v3, 0xbfb8aa3b, v3
	v_exp_f32_e32 v0, v0
	v_exp_f32_e32 v1, v1
	v_exp_f32_e32 v2, v2
	v_exp_f32_e32 v3, v3
	s_nop 0
	v_add_f32_e32 v0, 1.0, v0
	v_add_f32_e32 v1, 1.0, v1
	v_add_f32_e32 v2, 1.0, v2
	v_add_f32_e32 v3, 1.0, v3
	v_rcp_f32_e32 v0, v0
	v_rcp_f32_e32 v1, v1
	v_rcp_f32_e32 v2, v2
	v_rcp_f32_e32 v3, v3
	s_nop 0
	v_mul_f32_e32 v0, 0x3f1b4598, v0
	v_mul_f32_e32 v1, 0x3f1b4598, v1
	v_mul_f32_e32 v2, 0x3f1b4598, v2
	v_mul_f32_e32 v3, 0x3f1b4598, v3
	v_cvt_pk_bf16_f32 v128, v0, v1
	v_cvt_pk_bf16_f32 v129, v2, v3
	ds_write_b64 v236, v[128:129]
	v_add_f32_e32 v4, v4, v196
	v_add_f32_e32 v5, v5, v197
	v_add_f32_e32 v6, v6, v198
	v_add_f32_e32 v7, v7, v199
	v_mul_f32_e32 v4, 0xbfb8aa3b, v4
	v_mul_f32_e32 v5, 0xbfb8aa3b, v5
	v_mul_f32_e32 v6, 0xbfb8aa3b, v6
	v_mul_f32_e32 v7, 0xbfb8aa3b, v7
	v_exp_f32_e32 v4, v4
	v_exp_f32_e32 v5, v5
	v_exp_f32_e32 v6, v6
	v_exp_f32_e32 v7, v7
	s_nop 0
	v_add_f32_e32 v4, 1.0, v4
	v_add_f32_e32 v5, 1.0, v5
	v_add_f32_e32 v6, 1.0, v6
	v_add_f32_e32 v7, 1.0, v7
	v_rcp_f32_e32 v4, v4
	v_rcp_f32_e32 v5, v5
	v_rcp_f32_e32 v6, v6
	v_rcp_f32_e32 v7, v7
	s_nop 0
	v_mul_f32_e32 v4, 0x3f1b4598, v4
	v_mul_f32_e32 v5, 0x3f1b4598, v5
	v_mul_f32_e32 v6, 0x3f1b4598, v6
	v_mul_f32_e32 v7, 0x3f1b4598, v7
	v_cvt_pk_bf16_f32 v130, v4, v5
	v_cvt_pk_bf16_f32 v131, v6, v7
	ds_write_b64 v236, v[130:131] offset:32
	v_add_f32_e32 v8, v8, v200
	v_add_f32_e32 v9, v9, v201
	v_add_f32_e32 v10, v10, v202
	v_add_f32_e32 v11, v11, v203
	v_mul_f32_e32 v8, 0xbfb8aa3b, v8
	v_mul_f32_e32 v9, 0xbfb8aa3b, v9
	v_mul_f32_e32 v10, 0xbfb8aa3b, v10
	v_mul_f32_e32 v11, 0xbfb8aa3b, v11
	v_exp_f32_e32 v8, v8
	v_exp_f32_e32 v9, v9
	v_exp_f32_e32 v10, v10
	v_exp_f32_e32 v11, v11
	s_nop 0
	v_add_f32_e32 v8, 1.0, v8
	v_add_f32_e32 v9, 1.0, v9
	v_add_f32_e32 v10, 1.0, v10
	v_add_f32_e32 v11, 1.0, v11
	v_rcp_f32_e32 v8, v8
	v_rcp_f32_e32 v9, v9
	v_rcp_f32_e32 v10, v10
	v_rcp_f32_e32 v11, v11
	s_nop 0
	v_mul_f32_e32 v8, 0x3f1b4598, v8
	v_mul_f32_e32 v9, 0x3f1b4598, v9
	v_mul_f32_e32 v10, 0x3f1b4598, v10
	v_mul_f32_e32 v11, 0x3f1b4598, v11
	v_cvt_pk_bf16_f32 v132, v8, v9
	v_cvt_pk_bf16_f32 v133, v10, v11
	ds_write_b64 v236, v[132:133] offset:64
	v_add_f32_e32 v12, v12, v204
	v_add_f32_e32 v13, v13, v205
	v_add_f32_e32 v14, v14, v206
	v_add_f32_e32 v15, v15, v207
	v_mul_f32_e32 v12, 0xbfb8aa3b, v12
	v_mul_f32_e32 v13, 0xbfb8aa3b, v13
	v_mul_f32_e32 v14, 0xbfb8aa3b, v14
	v_mul_f32_e32 v15, 0xbfb8aa3b, v15
	v_exp_f32_e32 v12, v12
	v_exp_f32_e32 v13, v13
	v_exp_f32_e32 v14, v14
	v_exp_f32_e32 v15, v15
	s_nop 0
	v_add_f32_e32 v12, 1.0, v12
	v_add_f32_e32 v13, 1.0, v13
	v_add_f32_e32 v14, 1.0, v14
	v_add_f32_e32 v15, 1.0, v15
	v_rcp_f32_e32 v12, v12
	v_rcp_f32_e32 v13, v13
	v_rcp_f32_e32 v14, v14
	v_rcp_f32_e32 v15, v15
	s_nop 0
	v_mul_f32_e32 v12, 0x3f1b4598, v12
	v_mul_f32_e32 v13, 0x3f1b4598, v13
	v_mul_f32_e32 v14, 0x3f1b4598, v14
	v_mul_f32_e32 v15, 0x3f1b4598, v15
	v_cvt_pk_bf16_f32 v134, v12, v13
	v_cvt_pk_bf16_f32 v135, v14, v15
	ds_write_b64 v236, v[134:135] offset:96
	v_add_f32_e32 v16, v16, v192
	v_add_f32_e32 v17, v17, v193
	v_add_f32_e32 v18, v18, v194
	v_add_f32_e32 v19, v19, v195
	v_mul_f32_e32 v16, 0xbfb8aa3b, v16
	v_mul_f32_e32 v17, 0xbfb8aa3b, v17
	v_mul_f32_e32 v18, 0xbfb8aa3b, v18
	v_mul_f32_e32 v19, 0xbfb8aa3b, v19
	v_exp_f32_e32 v16, v16
	v_exp_f32_e32 v17, v17
	v_exp_f32_e32 v18, v18
	v_exp_f32_e32 v19, v19
	s_nop 0
	v_add_f32_e32 v16, 1.0, v16
	v_add_f32_e32 v17, 1.0, v17
	v_add_f32_e32 v18, 1.0, v18
	v_add_f32_e32 v19, 1.0, v19
	v_rcp_f32_e32 v16, v16
	v_rcp_f32_e32 v17, v17
	v_rcp_f32_e32 v18, v18
	v_rcp_f32_e32 v19, v19
	s_nop 0
	v_mul_f32_e32 v16, 0x3f1b4598, v16
	v_mul_f32_e32 v17, 0x3f1b4598, v17
	v_mul_f32_e32 v18, 0x3f1b4598, v18
	v_mul_f32_e32 v19, 0x3f1b4598, v19
	v_cvt_pk_bf16_f32 v136, v16, v17
	v_cvt_pk_bf16_f32 v137, v18, v19
	ds_write_b64 v236, v[136:137] offset:2304
	v_add_f32_e32 v20, v20, v196
	v_add_f32_e32 v21, v21, v197
	v_add_f32_e32 v22, v22, v198
	v_add_f32_e32 v23, v23, v199
	v_mul_f32_e32 v20, 0xbfb8aa3b, v20
	v_mul_f32_e32 v21, 0xbfb8aa3b, v21
	v_mul_f32_e32 v22, 0xbfb8aa3b, v22
	v_mul_f32_e32 v23, 0xbfb8aa3b, v23
	v_exp_f32_e32 v20, v20
	v_exp_f32_e32 v21, v21
	v_exp_f32_e32 v22, v22
	v_exp_f32_e32 v23, v23
	s_nop 0
	v_add_f32_e32 v20, 1.0, v20
	v_add_f32_e32 v21, 1.0, v21
	v_add_f32_e32 v22, 1.0, v22
	v_add_f32_e32 v23, 1.0, v23
	v_rcp_f32_e32 v20, v20
	v_rcp_f32_e32 v21, v21
	v_rcp_f32_e32 v22, v22
	v_rcp_f32_e32 v23, v23
	s_nop 0
	v_mul_f32_e32 v20, 0x3f1b4598, v20
	v_mul_f32_e32 v21, 0x3f1b4598, v21
	v_mul_f32_e32 v22, 0x3f1b4598, v22
	v_mul_f32_e32 v23, 0x3f1b4598, v23
	v_cvt_pk_bf16_f32 v138, v20, v21
	v_cvt_pk_bf16_f32 v139, v22, v23
	ds_write_b64 v236, v[138:139] offset:2336
	v_add_f32_e32 v24, v24, v200
	v_add_f32_e32 v25, v25, v201
	v_add_f32_e32 v26, v26, v202
	v_add_f32_e32 v27, v27, v203
	v_mul_f32_e32 v24, 0xbfb8aa3b, v24
	v_mul_f32_e32 v25, 0xbfb8aa3b, v25
	v_mul_f32_e32 v26, 0xbfb8aa3b, v26
	v_mul_f32_e32 v27, 0xbfb8aa3b, v27
	v_exp_f32_e32 v24, v24
	v_exp_f32_e32 v25, v25
	v_exp_f32_e32 v26, v26
	v_exp_f32_e32 v27, v27
	s_nop 0
	v_add_f32_e32 v24, 1.0, v24
	v_add_f32_e32 v25, 1.0, v25
	v_add_f32_e32 v26, 1.0, v26
	v_add_f32_e32 v27, 1.0, v27
	v_rcp_f32_e32 v24, v24
	v_rcp_f32_e32 v25, v25
	v_rcp_f32_e32 v26, v26
	v_rcp_f32_e32 v27, v27
	s_nop 0
	v_mul_f32_e32 v24, 0x3f1b4598, v24
	v_mul_f32_e32 v25, 0x3f1b4598, v25
	v_mul_f32_e32 v26, 0x3f1b4598, v26
	v_mul_f32_e32 v27, 0x3f1b4598, v27
	v_cvt_pk_bf16_f32 v140, v24, v25
	v_cvt_pk_bf16_f32 v141, v26, v27
	ds_write_b64 v236, v[140:141] offset:2368
	v_add_f32_e32 v28, v28, v204
	v_add_f32_e32 v29, v29, v205
	v_add_f32_e32 v30, v30, v206
	v_add_f32_e32 v31, v31, v207
	v_mul_f32_e32 v28, 0xbfb8aa3b, v28
	v_mul_f32_e32 v29, 0xbfb8aa3b, v29
	v_mul_f32_e32 v30, 0xbfb8aa3b, v30
	v_mul_f32_e32 v31, 0xbfb8aa3b, v31
	v_exp_f32_e32 v28, v28
	v_exp_f32_e32 v29, v29
	v_exp_f32_e32 v30, v30
	v_exp_f32_e32 v31, v31
	s_nop 0
	v_add_f32_e32 v28, 1.0, v28
	v_add_f32_e32 v29, 1.0, v29
	v_add_f32_e32 v30, 1.0, v30
	v_add_f32_e32 v31, 1.0, v31
	v_rcp_f32_e32 v28, v28
	v_rcp_f32_e32 v29, v29
	v_rcp_f32_e32 v30, v30
	v_rcp_f32_e32 v31, v31
	s_nop 0
	v_mul_f32_e32 v28, 0x3f1b4598, v28
	v_mul_f32_e32 v29, 0x3f1b4598, v29
	v_mul_f32_e32 v30, 0x3f1b4598, v30
	v_mul_f32_e32 v31, 0x3f1b4598, v31
	v_cvt_pk_bf16_f32 v142, v28, v29
	v_cvt_pk_bf16_f32 v143, v30, v31
	ds_write_b64 v236, v[142:143] offset:2400
	v_add_f32_e32 v32, v32, v192
	v_add_f32_e32 v33, v33, v193
	v_add_f32_e32 v34, v34, v194
	v_add_f32_e32 v35, v35, v195
	v_mul_f32_e32 v32, 0xbfb8aa3b, v32
	v_mul_f32_e32 v33, 0xbfb8aa3b, v33
	v_mul_f32_e32 v34, 0xbfb8aa3b, v34
	v_mul_f32_e32 v35, 0xbfb8aa3b, v35
	v_exp_f32_e32 v32, v32
	v_exp_f32_e32 v33, v33
	v_exp_f32_e32 v34, v34
	v_exp_f32_e32 v35, v35
	s_nop 0
	v_add_f32_e32 v32, 1.0, v32
	v_add_f32_e32 v33, 1.0, v33
	v_add_f32_e32 v34, 1.0, v34
	v_add_f32_e32 v35, 1.0, v35
	v_rcp_f32_e32 v32, v32
	v_rcp_f32_e32 v33, v33
	v_rcp_f32_e32 v34, v34
	v_rcp_f32_e32 v35, v35
	s_nop 0
	v_mul_f32_e32 v32, 0x3f1b4598, v32
	v_mul_f32_e32 v33, 0x3f1b4598, v33
	v_mul_f32_e32 v34, 0x3f1b4598, v34
	v_mul_f32_e32 v35, 0x3f1b4598, v35
	v_cvt_pk_bf16_f32 v144, v32, v33
	v_cvt_pk_bf16_f32 v145, v34, v35
	ds_write_b64 v236, v[144:145] offset:4608
	v_add_f32_e32 v36, v36, v196
	v_add_f32_e32 v37, v37, v197
	v_add_f32_e32 v38, v38, v198
	v_add_f32_e32 v39, v39, v199
	v_mul_f32_e32 v36, 0xbfb8aa3b, v36
	v_mul_f32_e32 v37, 0xbfb8aa3b, v37
	v_mul_f32_e32 v38, 0xbfb8aa3b, v38
	v_mul_f32_e32 v39, 0xbfb8aa3b, v39
	v_exp_f32_e32 v36, v36
	v_exp_f32_e32 v37, v37
	v_exp_f32_e32 v38, v38
	v_exp_f32_e32 v39, v39
	s_nop 0
	v_add_f32_e32 v36, 1.0, v36
	v_add_f32_e32 v37, 1.0, v37
	v_add_f32_e32 v38, 1.0, v38
	v_add_f32_e32 v39, 1.0, v39
	v_rcp_f32_e32 v36, v36
	v_rcp_f32_e32 v37, v37
	v_rcp_f32_e32 v38, v38
	v_rcp_f32_e32 v39, v39
	s_nop 0
	v_mul_f32_e32 v36, 0x3f1b4598, v36
	v_mul_f32_e32 v37, 0x3f1b4598, v37
	v_mul_f32_e32 v38, 0x3f1b4598, v38
	v_mul_f32_e32 v39, 0x3f1b4598, v39
	v_cvt_pk_bf16_f32 v146, v36, v37
	v_cvt_pk_bf16_f32 v147, v38, v39
	ds_write_b64 v236, v[146:147] offset:4640
	v_add_f32_e32 v40, v40, v200
	v_add_f32_e32 v41, v41, v201
	v_add_f32_e32 v42, v42, v202
	v_add_f32_e32 v43, v43, v203
	v_mul_f32_e32 v40, 0xbfb8aa3b, v40
	v_mul_f32_e32 v41, 0xbfb8aa3b, v41
	v_mul_f32_e32 v42, 0xbfb8aa3b, v42
	v_mul_f32_e32 v43, 0xbfb8aa3b, v43
	v_exp_f32_e32 v40, v40
	v_exp_f32_e32 v41, v41
	v_exp_f32_e32 v42, v42
	v_exp_f32_e32 v43, v43
	s_nop 0
	v_add_f32_e32 v40, 1.0, v40
	v_add_f32_e32 v41, 1.0, v41
	v_add_f32_e32 v42, 1.0, v42
	v_add_f32_e32 v43, 1.0, v43
	v_rcp_f32_e32 v40, v40
	v_rcp_f32_e32 v41, v41
	v_rcp_f32_e32 v42, v42
	v_rcp_f32_e32 v43, v43
	s_nop 0
	v_mul_f32_e32 v40, 0x3f1b4598, v40
	v_mul_f32_e32 v41, 0x3f1b4598, v41
	v_mul_f32_e32 v42, 0x3f1b4598, v42
	v_mul_f32_e32 v43, 0x3f1b4598, v43
	v_cvt_pk_bf16_f32 v148, v40, v41
	v_cvt_pk_bf16_f32 v149, v42, v43
	ds_write_b64 v236, v[148:149] offset:4672
	v_add_f32_e32 v44, v44, v204
	v_add_f32_e32 v45, v45, v205
	v_add_f32_e32 v46, v46, v206
	v_add_f32_e32 v47, v47, v207
	v_mul_f32_e32 v44, 0xbfb8aa3b, v44
	v_mul_f32_e32 v45, 0xbfb8aa3b, v45
	v_mul_f32_e32 v46, 0xbfb8aa3b, v46
	v_mul_f32_e32 v47, 0xbfb8aa3b, v47
	v_exp_f32_e32 v44, v44
	v_exp_f32_e32 v45, v45
	v_exp_f32_e32 v46, v46
	v_exp_f32_e32 v47, v47
	s_nop 0
	v_add_f32_e32 v44, 1.0, v44
	v_add_f32_e32 v45, 1.0, v45
	v_add_f32_e32 v46, 1.0, v46
	v_add_f32_e32 v47, 1.0, v47
	v_rcp_f32_e32 v44, v44
	v_rcp_f32_e32 v45, v45
	v_rcp_f32_e32 v46, v46
	v_rcp_f32_e32 v47, v47
	s_nop 0
	v_mul_f32_e32 v44, 0x3f1b4598, v44
	v_mul_f32_e32 v45, 0x3f1b4598, v45
	v_mul_f32_e32 v46, 0x3f1b4598, v46
	v_mul_f32_e32 v47, 0x3f1b4598, v47
	v_cvt_pk_bf16_f32 v150, v44, v45
	v_cvt_pk_bf16_f32 v151, v46, v47
	ds_write_b64 v236, v[150:151] offset:4704
	v_add_f32_e32 v48, v48, v192
	v_add_f32_e32 v49, v49, v193
	v_add_f32_e32 v50, v50, v194
	v_add_f32_e32 v51, v51, v195
	v_mul_f32_e32 v48, 0xbfb8aa3b, v48
	v_mul_f32_e32 v49, 0xbfb8aa3b, v49
	v_mul_f32_e32 v50, 0xbfb8aa3b, v50
	v_mul_f32_e32 v51, 0xbfb8aa3b, v51
	v_exp_f32_e32 v48, v48
	v_exp_f32_e32 v49, v49
	v_exp_f32_e32 v50, v50
	v_exp_f32_e32 v51, v51
	s_nop 0
	v_add_f32_e32 v48, 1.0, v48
	v_add_f32_e32 v49, 1.0, v49
	v_add_f32_e32 v50, 1.0, v50
	v_add_f32_e32 v51, 1.0, v51
	v_rcp_f32_e32 v48, v48
	v_rcp_f32_e32 v49, v49
	v_rcp_f32_e32 v50, v50
	v_rcp_f32_e32 v51, v51
	s_nop 0
	v_mul_f32_e32 v48, 0x3f1b4598, v48
	v_mul_f32_e32 v49, 0x3f1b4598, v49
	v_mul_f32_e32 v50, 0x3f1b4598, v50
	v_mul_f32_e32 v51, 0x3f1b4598, v51
	v_cvt_pk_bf16_f32 v152, v48, v49
	v_cvt_pk_bf16_f32 v153, v50, v51
	ds_write_b64 v236, v[152:153] offset:6912
	v_add_f32_e32 v52, v52, v196
	v_add_f32_e32 v53, v53, v197
	v_add_f32_e32 v54, v54, v198
	v_add_f32_e32 v55, v55, v199
	v_mul_f32_e32 v52, 0xbfb8aa3b, v52
	v_mul_f32_e32 v53, 0xbfb8aa3b, v53
	v_mul_f32_e32 v54, 0xbfb8aa3b, v54
	v_mul_f32_e32 v55, 0xbfb8aa3b, v55
	v_exp_f32_e32 v52, v52
	v_exp_f32_e32 v53, v53
	v_exp_f32_e32 v54, v54
	v_exp_f32_e32 v55, v55
	s_nop 0
	v_add_f32_e32 v52, 1.0, v52
	v_add_f32_e32 v53, 1.0, v53
	v_add_f32_e32 v54, 1.0, v54
	v_add_f32_e32 v55, 1.0, v55
	v_rcp_f32_e32 v52, v52
	v_rcp_f32_e32 v53, v53
	v_rcp_f32_e32 v54, v54
	v_rcp_f32_e32 v55, v55
	s_nop 0
	v_mul_f32_e32 v52, 0x3f1b4598, v52
	v_mul_f32_e32 v53, 0x3f1b4598, v53
	v_mul_f32_e32 v54, 0x3f1b4598, v54
	v_mul_f32_e32 v55, 0x3f1b4598, v55
	v_cvt_pk_bf16_f32 v154, v52, v53
	v_cvt_pk_bf16_f32 v155, v54, v55
	ds_write_b64 v236, v[154:155] offset:6944
	v_add_f32_e32 v56, v56, v200
	v_add_f32_e32 v57, v57, v201
	v_add_f32_e32 v58, v58, v202
	v_add_f32_e32 v59, v59, v203
	v_mul_f32_e32 v56, 0xbfb8aa3b, v56
	v_mul_f32_e32 v57, 0xbfb8aa3b, v57
	v_mul_f32_e32 v58, 0xbfb8aa3b, v58
	v_mul_f32_e32 v59, 0xbfb8aa3b, v59
	v_exp_f32_e32 v56, v56
	v_exp_f32_e32 v57, v57
	v_exp_f32_e32 v58, v58
	v_exp_f32_e32 v59, v59
	s_nop 0
	v_add_f32_e32 v56, 1.0, v56
	v_add_f32_e32 v57, 1.0, v57
	v_add_f32_e32 v58, 1.0, v58
	v_add_f32_e32 v59, 1.0, v59
	v_rcp_f32_e32 v56, v56
	v_rcp_f32_e32 v57, v57
	v_rcp_f32_e32 v58, v58
	v_rcp_f32_e32 v59, v59
	s_nop 0
	v_mul_f32_e32 v56, 0x3f1b4598, v56
	v_mul_f32_e32 v57, 0x3f1b4598, v57
	v_mul_f32_e32 v58, 0x3f1b4598, v58
	v_mul_f32_e32 v59, 0x3f1b4598, v59
	v_cvt_pk_bf16_f32 v156, v56, v57
	v_cvt_pk_bf16_f32 v157, v58, v59
	ds_write_b64 v236, v[156:157] offset:6976
	v_add_f32_e32 v60, v60, v204
	v_add_f32_e32 v61, v61, v205
	v_add_f32_e32 v62, v62, v206
	v_add_f32_e32 v63, v63, v207
	v_mul_f32_e32 v60, 0xbfb8aa3b, v60
	v_mul_f32_e32 v61, 0xbfb8aa3b, v61
	v_mul_f32_e32 v62, 0xbfb8aa3b, v62
	v_mul_f32_e32 v63, 0xbfb8aa3b, v63
	v_exp_f32_e32 v60, v60
	v_exp_f32_e32 v61, v61
	v_exp_f32_e32 v62, v62
	v_exp_f32_e32 v63, v63
	s_nop 0
	v_add_f32_e32 v60, 1.0, v60
	v_add_f32_e32 v61, 1.0, v61
	v_add_f32_e32 v62, 1.0, v62
	v_add_f32_e32 v63, 1.0, v63
	v_rcp_f32_e32 v60, v60
	v_rcp_f32_e32 v61, v61
	v_rcp_f32_e32 v62, v62
	v_rcp_f32_e32 v63, v63
	s_nop 0
	v_mul_f32_e32 v60, 0x3f1b4598, v60
	v_mul_f32_e32 v61, 0x3f1b4598, v61
	v_mul_f32_e32 v62, 0x3f1b4598, v62
	v_mul_f32_e32 v63, 0x3f1b4598, v63
	v_cvt_pk_bf16_f32 v158, v60, v61
	v_cvt_pk_bf16_f32 v159, v62, v63
	ds_write_b64 v236, v[158:159] offset:7008
	v_add_f32_e32 v64, v64, v192
	v_add_f32_e32 v65, v65, v193
	v_add_f32_e32 v66, v66, v194
	v_add_f32_e32 v67, v67, v195
	v_mul_f32_e32 v64, 0xbfb8aa3b, v64
	v_mul_f32_e32 v65, 0xbfb8aa3b, v65
	v_mul_f32_e32 v66, 0xbfb8aa3b, v66
	v_mul_f32_e32 v67, 0xbfb8aa3b, v67
	v_exp_f32_e32 v64, v64
	v_exp_f32_e32 v65, v65
	v_exp_f32_e32 v66, v66
	v_exp_f32_e32 v67, v67
	s_nop 0
	v_add_f32_e32 v64, 1.0, v64
	v_add_f32_e32 v65, 1.0, v65
	v_add_f32_e32 v66, 1.0, v66
	v_add_f32_e32 v67, 1.0, v67
	v_rcp_f32_e32 v64, v64
	v_rcp_f32_e32 v65, v65
	v_rcp_f32_e32 v66, v66
	v_rcp_f32_e32 v67, v67
	s_nop 0
	v_mul_f32_e32 v64, 0x3f1b4598, v64
	v_mul_f32_e32 v65, 0x3f1b4598, v65
	v_mul_f32_e32 v66, 0x3f1b4598, v66
	v_mul_f32_e32 v67, 0x3f1b4598, v67
	v_cvt_pk_bf16_f32 v128, v64, v65
	v_cvt_pk_bf16_f32 v129, v66, v67
	ds_write_b64 v236, v[128:129] offset:9216
	v_add_f32_e32 v68, v68, v196
	v_add_f32_e32 v69, v69, v197
	v_add_f32_e32 v70, v70, v198
	v_add_f32_e32 v71, v71, v199
	v_mul_f32_e32 v68, 0xbfb8aa3b, v68
	v_mul_f32_e32 v69, 0xbfb8aa3b, v69
	v_mul_f32_e32 v70, 0xbfb8aa3b, v70
	v_mul_f32_e32 v71, 0xbfb8aa3b, v71
	v_exp_f32_e32 v68, v68
	v_exp_f32_e32 v69, v69
	v_exp_f32_e32 v70, v70
	v_exp_f32_e32 v71, v71
	s_nop 0
	v_add_f32_e32 v68, 1.0, v68
	v_add_f32_e32 v69, 1.0, v69
	v_add_f32_e32 v70, 1.0, v70
	v_add_f32_e32 v71, 1.0, v71
	v_rcp_f32_e32 v68, v68
	v_rcp_f32_e32 v69, v69
	v_rcp_f32_e32 v70, v70
	v_rcp_f32_e32 v71, v71
	s_nop 0
	v_mul_f32_e32 v68, 0x3f1b4598, v68
	v_mul_f32_e32 v69, 0x3f1b4598, v69
	v_mul_f32_e32 v70, 0x3f1b4598, v70
	v_mul_f32_e32 v71, 0x3f1b4598, v71
	v_cvt_pk_bf16_f32 v130, v68, v69
	v_cvt_pk_bf16_f32 v131, v70, v71
	ds_write_b64 v236, v[130:131] offset:9248
	v_add_f32_e32 v72, v72, v200
	v_add_f32_e32 v73, v73, v201
	v_add_f32_e32 v74, v74, v202
	v_add_f32_e32 v75, v75, v203
	v_mul_f32_e32 v72, 0xbfb8aa3b, v72
	v_mul_f32_e32 v73, 0xbfb8aa3b, v73
	v_mul_f32_e32 v74, 0xbfb8aa3b, v74
	v_mul_f32_e32 v75, 0xbfb8aa3b, v75
	v_exp_f32_e32 v72, v72
	v_exp_f32_e32 v73, v73
	v_exp_f32_e32 v74, v74
	v_exp_f32_e32 v75, v75
	s_nop 0
	v_add_f32_e32 v72, 1.0, v72
	v_add_f32_e32 v73, 1.0, v73
	v_add_f32_e32 v74, 1.0, v74
	v_add_f32_e32 v75, 1.0, v75
	v_rcp_f32_e32 v72, v72
	v_rcp_f32_e32 v73, v73
	v_rcp_f32_e32 v74, v74
	v_rcp_f32_e32 v75, v75
	s_nop 0
	v_mul_f32_e32 v72, 0x3f1b4598, v72
	v_mul_f32_e32 v73, 0x3f1b4598, v73
	v_mul_f32_e32 v74, 0x3f1b4598, v74
	v_mul_f32_e32 v75, 0x3f1b4598, v75
	v_cvt_pk_bf16_f32 v132, v72, v73
	v_cvt_pk_bf16_f32 v133, v74, v75
	ds_write_b64 v236, v[132:133] offset:9280
	v_add_f32_e32 v76, v76, v204
	v_add_f32_e32 v77, v77, v205
	v_add_f32_e32 v78, v78, v206
	v_add_f32_e32 v79, v79, v207
	v_mul_f32_e32 v76, 0xbfb8aa3b, v76
	v_mul_f32_e32 v77, 0xbfb8aa3b, v77
	v_mul_f32_e32 v78, 0xbfb8aa3b, v78
	v_mul_f32_e32 v79, 0xbfb8aa3b, v79
	v_exp_f32_e32 v76, v76
	v_exp_f32_e32 v77, v77
	v_exp_f32_e32 v78, v78
	v_exp_f32_e32 v79, v79
	s_nop 0
	v_add_f32_e32 v76, 1.0, v76
	v_add_f32_e32 v77, 1.0, v77
	v_add_f32_e32 v78, 1.0, v78
	v_add_f32_e32 v79, 1.0, v79
	v_rcp_f32_e32 v76, v76
	v_rcp_f32_e32 v77, v77
	v_rcp_f32_e32 v78, v78
	v_rcp_f32_e32 v79, v79
	s_nop 0
	v_mul_f32_e32 v76, 0x3f1b4598, v76
	v_mul_f32_e32 v77, 0x3f1b4598, v77
	v_mul_f32_e32 v78, 0x3f1b4598, v78
	v_mul_f32_e32 v79, 0x3f1b4598, v79
	v_cvt_pk_bf16_f32 v134, v76, v77
	v_cvt_pk_bf16_f32 v135, v78, v79
	ds_write_b64 v236, v[134:135] offset:9312
	v_add_f32_e32 v80, v80, v192
	v_add_f32_e32 v81, v81, v193
	v_add_f32_e32 v82, v82, v194
	v_add_f32_e32 v83, v83, v195
	v_mul_f32_e32 v80, 0xbfb8aa3b, v80
	v_mul_f32_e32 v81, 0xbfb8aa3b, v81
	v_mul_f32_e32 v82, 0xbfb8aa3b, v82
	v_mul_f32_e32 v83, 0xbfb8aa3b, v83
	v_exp_f32_e32 v80, v80
	v_exp_f32_e32 v81, v81
	v_exp_f32_e32 v82, v82
	v_exp_f32_e32 v83, v83
	s_nop 0
	v_add_f32_e32 v80, 1.0, v80
	v_add_f32_e32 v81, 1.0, v81
	v_add_f32_e32 v82, 1.0, v82
	v_add_f32_e32 v83, 1.0, v83
	v_rcp_f32_e32 v80, v80
	v_rcp_f32_e32 v81, v81
	v_rcp_f32_e32 v82, v82
	v_rcp_f32_e32 v83, v83
	s_nop 0
	v_mul_f32_e32 v80, 0x3f1b4598, v80
	v_mul_f32_e32 v81, 0x3f1b4598, v81
	v_mul_f32_e32 v82, 0x3f1b4598, v82
	v_mul_f32_e32 v83, 0x3f1b4598, v83
	v_cvt_pk_bf16_f32 v136, v80, v81
	v_cvt_pk_bf16_f32 v137, v82, v83
	ds_write_b64 v236, v[136:137] offset:11520
	v_add_f32_e32 v84, v84, v196
	v_add_f32_e32 v85, v85, v197
	v_add_f32_e32 v86, v86, v198
	v_add_f32_e32 v87, v87, v199
	v_mul_f32_e32 v84, 0xbfb8aa3b, v84
	v_mul_f32_e32 v85, 0xbfb8aa3b, v85
	v_mul_f32_e32 v86, 0xbfb8aa3b, v86
	v_mul_f32_e32 v87, 0xbfb8aa3b, v87
	v_exp_f32_e32 v84, v84
	v_exp_f32_e32 v85, v85
	v_exp_f32_e32 v86, v86
	v_exp_f32_e32 v87, v87
	s_nop 0
	v_add_f32_e32 v84, 1.0, v84
	v_add_f32_e32 v85, 1.0, v85
	v_add_f32_e32 v86, 1.0, v86
	v_add_f32_e32 v87, 1.0, v87
	v_rcp_f32_e32 v84, v84
	v_rcp_f32_e32 v85, v85
	v_rcp_f32_e32 v86, v86
	v_rcp_f32_e32 v87, v87
	s_nop 0
	v_mul_f32_e32 v84, 0x3f1b4598, v84
	v_mul_f32_e32 v85, 0x3f1b4598, v85
	v_mul_f32_e32 v86, 0x3f1b4598, v86
	v_mul_f32_e32 v87, 0x3f1b4598, v87
	v_cvt_pk_bf16_f32 v138, v84, v85
	v_cvt_pk_bf16_f32 v139, v86, v87
	ds_write_b64 v236, v[138:139] offset:11552
	v_add_f32_e32 v88, v88, v200
	v_add_f32_e32 v89, v89, v201
	v_add_f32_e32 v90, v90, v202
	v_add_f32_e32 v91, v91, v203
	v_mul_f32_e32 v88, 0xbfb8aa3b, v88
	v_mul_f32_e32 v89, 0xbfb8aa3b, v89
	v_mul_f32_e32 v90, 0xbfb8aa3b, v90
	v_mul_f32_e32 v91, 0xbfb8aa3b, v91
	v_exp_f32_e32 v88, v88
	v_exp_f32_e32 v89, v89
	v_exp_f32_e32 v90, v90
	v_exp_f32_e32 v91, v91
	s_nop 0
	v_add_f32_e32 v88, 1.0, v88
	v_add_f32_e32 v89, 1.0, v89
	v_add_f32_e32 v90, 1.0, v90
	v_add_f32_e32 v91, 1.0, v91
	v_rcp_f32_e32 v88, v88
	v_rcp_f32_e32 v89, v89
	v_rcp_f32_e32 v90, v90
	v_rcp_f32_e32 v91, v91
	s_nop 0
	v_mul_f32_e32 v88, 0x3f1b4598, v88
	v_mul_f32_e32 v89, 0x3f1b4598, v89
	v_mul_f32_e32 v90, 0x3f1b4598, v90
	v_mul_f32_e32 v91, 0x3f1b4598, v91
	v_cvt_pk_bf16_f32 v140, v88, v89
	v_cvt_pk_bf16_f32 v141, v90, v91
	ds_write_b64 v236, v[140:141] offset:11584
	v_add_f32_e32 v92, v92, v204
	v_add_f32_e32 v93, v93, v205
	v_add_f32_e32 v94, v94, v206
	v_add_f32_e32 v95, v95, v207
	v_mul_f32_e32 v92, 0xbfb8aa3b, v92
	v_mul_f32_e32 v93, 0xbfb8aa3b, v93
	v_mul_f32_e32 v94, 0xbfb8aa3b, v94
	v_mul_f32_e32 v95, 0xbfb8aa3b, v95
	v_exp_f32_e32 v92, v92
	v_exp_f32_e32 v93, v93
	v_exp_f32_e32 v94, v94
	v_exp_f32_e32 v95, v95
	s_nop 0
	v_add_f32_e32 v92, 1.0, v92
	v_add_f32_e32 v93, 1.0, v93
	v_add_f32_e32 v94, 1.0, v94
	v_add_f32_e32 v95, 1.0, v95
	v_rcp_f32_e32 v92, v92
	v_rcp_f32_e32 v93, v93
	v_rcp_f32_e32 v94, v94
	v_rcp_f32_e32 v95, v95
	s_nop 0
	v_mul_f32_e32 v92, 0x3f1b4598, v92
	v_mul_f32_e32 v93, 0x3f1b4598, v93
	v_mul_f32_e32 v94, 0x3f1b4598, v94
	v_mul_f32_e32 v95, 0x3f1b4598, v95
	v_cvt_pk_bf16_f32 v142, v92, v93
	v_cvt_pk_bf16_f32 v143, v94, v95
	ds_write_b64 v236, v[142:143] offset:11616
	v_add_f32_e32 v96, v96, v192
	v_add_f32_e32 v97, v97, v193
	v_add_f32_e32 v98, v98, v194
	v_add_f32_e32 v99, v99, v195
	v_mul_f32_e32 v96, 0xbfb8aa3b, v96
	v_mul_f32_e32 v97, 0xbfb8aa3b, v97
	v_mul_f32_e32 v98, 0xbfb8aa3b, v98
	v_mul_f32_e32 v99, 0xbfb8aa3b, v99
	v_exp_f32_e32 v96, v96
	v_exp_f32_e32 v97, v97
	v_exp_f32_e32 v98, v98
	v_exp_f32_e32 v99, v99
	s_nop 0
	v_add_f32_e32 v96, 1.0, v96
	v_add_f32_e32 v97, 1.0, v97
	v_add_f32_e32 v98, 1.0, v98
	v_add_f32_e32 v99, 1.0, v99
	v_rcp_f32_e32 v96, v96
	v_rcp_f32_e32 v97, v97
	v_rcp_f32_e32 v98, v98
	v_rcp_f32_e32 v99, v99
	s_nop 0
	v_mul_f32_e32 v96, 0x3f1b4598, v96
	v_mul_f32_e32 v97, 0x3f1b4598, v97
	v_mul_f32_e32 v98, 0x3f1b4598, v98
	v_mul_f32_e32 v99, 0x3f1b4598, v99
	v_cvt_pk_bf16_f32 v144, v96, v97
	v_cvt_pk_bf16_f32 v145, v98, v99
	ds_write_b64 v236, v[144:145] offset:13824
	v_add_f32_e32 v100, v100, v196
	v_add_f32_e32 v101, v101, v197
	v_add_f32_e32 v102, v102, v198
	v_add_f32_e32 v103, v103, v199
	v_mul_f32_e32 v100, 0xbfb8aa3b, v100
	v_mul_f32_e32 v101, 0xbfb8aa3b, v101
	v_mul_f32_e32 v102, 0xbfb8aa3b, v102
	v_mul_f32_e32 v103, 0xbfb8aa3b, v103
	v_exp_f32_e32 v100, v100
	v_exp_f32_e32 v101, v101
	v_exp_f32_e32 v102, v102
	v_exp_f32_e32 v103, v103
	s_nop 0
	v_add_f32_e32 v100, 1.0, v100
	v_add_f32_e32 v101, 1.0, v101
	v_add_f32_e32 v102, 1.0, v102
	v_add_f32_e32 v103, 1.0, v103
	v_rcp_f32_e32 v100, v100
	v_rcp_f32_e32 v101, v101
	v_rcp_f32_e32 v102, v102
	v_rcp_f32_e32 v103, v103
	s_nop 0
	v_mul_f32_e32 v100, 0x3f1b4598, v100
	v_mul_f32_e32 v101, 0x3f1b4598, v101
	v_mul_f32_e32 v102, 0x3f1b4598, v102
	v_mul_f32_e32 v103, 0x3f1b4598, v103
	v_cvt_pk_bf16_f32 v146, v100, v101
	v_cvt_pk_bf16_f32 v147, v102, v103
	ds_write_b64 v236, v[146:147] offset:13856
	v_add_f32_e32 v104, v104, v200
	v_add_f32_e32 v105, v105, v201
	v_add_f32_e32 v106, v106, v202
	v_add_f32_e32 v107, v107, v203
	v_mul_f32_e32 v104, 0xbfb8aa3b, v104
	v_mul_f32_e32 v105, 0xbfb8aa3b, v105
	v_mul_f32_e32 v106, 0xbfb8aa3b, v106
	v_mul_f32_e32 v107, 0xbfb8aa3b, v107
	v_exp_f32_e32 v104, v104
	v_exp_f32_e32 v105, v105
	v_exp_f32_e32 v106, v106
	v_exp_f32_e32 v107, v107
	s_nop 0
	v_add_f32_e32 v104, 1.0, v104
	v_add_f32_e32 v105, 1.0, v105
	v_add_f32_e32 v106, 1.0, v106
	v_add_f32_e32 v107, 1.0, v107
	v_rcp_f32_e32 v104, v104
	v_rcp_f32_e32 v105, v105
	v_rcp_f32_e32 v106, v106
	v_rcp_f32_e32 v107, v107
	s_nop 0
	v_mul_f32_e32 v104, 0x3f1b4598, v104
	v_mul_f32_e32 v105, 0x3f1b4598, v105
	v_mul_f32_e32 v106, 0x3f1b4598, v106
	v_mul_f32_e32 v107, 0x3f1b4598, v107
	v_cvt_pk_bf16_f32 v148, v104, v105
	v_cvt_pk_bf16_f32 v149, v106, v107
	ds_write_b64 v236, v[148:149] offset:13888
	v_add_f32_e32 v108, v108, v204
	v_add_f32_e32 v109, v109, v205
	v_add_f32_e32 v110, v110, v206
	v_add_f32_e32 v111, v111, v207
	v_mul_f32_e32 v108, 0xbfb8aa3b, v108
	v_mul_f32_e32 v109, 0xbfb8aa3b, v109
	v_mul_f32_e32 v110, 0xbfb8aa3b, v110
	v_mul_f32_e32 v111, 0xbfb8aa3b, v111
	v_exp_f32_e32 v108, v108
	v_exp_f32_e32 v109, v109
	v_exp_f32_e32 v110, v110
	v_exp_f32_e32 v111, v111
	s_nop 0
	v_add_f32_e32 v108, 1.0, v108
	v_add_f32_e32 v109, 1.0, v109
	v_add_f32_e32 v110, 1.0, v110
	v_add_f32_e32 v111, 1.0, v111
	v_rcp_f32_e32 v108, v108
	v_rcp_f32_e32 v109, v109
	v_rcp_f32_e32 v110, v110
	v_rcp_f32_e32 v111, v111
	s_nop 0
	v_mul_f32_e32 v108, 0x3f1b4598, v108
	v_mul_f32_e32 v109, 0x3f1b4598, v109
	v_mul_f32_e32 v110, 0x3f1b4598, v110
	v_mul_f32_e32 v111, 0x3f1b4598, v111
	v_cvt_pk_bf16_f32 v150, v108, v109
	v_cvt_pk_bf16_f32 v151, v110, v111
	ds_write_b64 v236, v[150:151] offset:13920
	v_add_f32_e32 v112, v112, v192
	v_add_f32_e32 v113, v113, v193
	v_add_f32_e32 v114, v114, v194
	v_add_f32_e32 v115, v115, v195
	v_mul_f32_e32 v112, 0xbfb8aa3b, v112
	v_mul_f32_e32 v113, 0xbfb8aa3b, v113
	v_mul_f32_e32 v114, 0xbfb8aa3b, v114
	v_mul_f32_e32 v115, 0xbfb8aa3b, v115
	v_exp_f32_e32 v112, v112
	v_exp_f32_e32 v113, v113
	v_exp_f32_e32 v114, v114
	v_exp_f32_e32 v115, v115
	s_nop 0
	v_add_f32_e32 v112, 1.0, v112
	v_add_f32_e32 v113, 1.0, v113
	v_add_f32_e32 v114, 1.0, v114
	v_add_f32_e32 v115, 1.0, v115
	v_rcp_f32_e32 v112, v112
	v_rcp_f32_e32 v113, v113
	v_rcp_f32_e32 v114, v114
	v_rcp_f32_e32 v115, v115
	s_nop 0
	v_mul_f32_e32 v112, 0x3f1b4598, v112
	v_mul_f32_e32 v113, 0x3f1b4598, v113
	v_mul_f32_e32 v114, 0x3f1b4598, v114
	v_mul_f32_e32 v115, 0x3f1b4598, v115
	v_cvt_pk_bf16_f32 v152, v112, v113
	v_cvt_pk_bf16_f32 v153, v114, v115
	ds_write_b64 v236, v[152:153] offset:16128
	v_add_f32_e32 v116, v116, v196
	v_add_f32_e32 v117, v117, v197
	v_add_f32_e32 v118, v118, v198
	v_add_f32_e32 v119, v119, v199
	v_mul_f32_e32 v116, 0xbfb8aa3b, v116
	v_mul_f32_e32 v117, 0xbfb8aa3b, v117
	v_mul_f32_e32 v118, 0xbfb8aa3b, v118
	v_mul_f32_e32 v119, 0xbfb8aa3b, v119
	v_exp_f32_e32 v116, v116
	v_exp_f32_e32 v117, v117
	v_exp_f32_e32 v118, v118
	v_exp_f32_e32 v119, v119
	s_nop 0
	v_add_f32_e32 v116, 1.0, v116
	v_add_f32_e32 v117, 1.0, v117
	v_add_f32_e32 v118, 1.0, v118
	v_add_f32_e32 v119, 1.0, v119
	v_rcp_f32_e32 v116, v116
	v_rcp_f32_e32 v117, v117
	v_rcp_f32_e32 v118, v118
	v_rcp_f32_e32 v119, v119
	s_nop 0
	v_mul_f32_e32 v116, 0x3f1b4598, v116
	v_mul_f32_e32 v117, 0x3f1b4598, v117
	v_mul_f32_e32 v118, 0x3f1b4598, v118
	v_mul_f32_e32 v119, 0x3f1b4598, v119
	v_cvt_pk_bf16_f32 v154, v116, v117
	v_cvt_pk_bf16_f32 v155, v118, v119
	ds_write_b64 v236, v[154:155] offset:16160
	v_add_f32_e32 v120, v120, v200
	v_add_f32_e32 v121, v121, v201
	v_add_f32_e32 v122, v122, v202
	v_add_f32_e32 v123, v123, v203
	v_mul_f32_e32 v120, 0xbfb8aa3b, v120
	v_mul_f32_e32 v121, 0xbfb8aa3b, v121
	v_mul_f32_e32 v122, 0xbfb8aa3b, v122
	v_mul_f32_e32 v123, 0xbfb8aa3b, v123
	v_exp_f32_e32 v120, v120
	v_exp_f32_e32 v121, v121
	v_exp_f32_e32 v122, v122
	v_exp_f32_e32 v123, v123
	s_nop 0
	v_add_f32_e32 v120, 1.0, v120
	v_add_f32_e32 v121, 1.0, v121
	v_add_f32_e32 v122, 1.0, v122
	v_add_f32_e32 v123, 1.0, v123
	v_rcp_f32_e32 v120, v120
	v_rcp_f32_e32 v121, v121
	v_rcp_f32_e32 v122, v122
	v_rcp_f32_e32 v123, v123
	s_nop 0
	v_mul_f32_e32 v120, 0x3f1b4598, v120
	v_mul_f32_e32 v121, 0x3f1b4598, v121
	v_mul_f32_e32 v122, 0x3f1b4598, v122
	v_mul_f32_e32 v123, 0x3f1b4598, v123
	v_cvt_pk_bf16_f32 v156, v120, v121
	v_cvt_pk_bf16_f32 v157, v122, v123
	ds_write_b64 v236, v[156:157] offset:16192
	v_add_f32_e32 v124, v124, v204
	v_add_f32_e32 v125, v125, v205
	v_add_f32_e32 v126, v126, v206
	v_add_f32_e32 v127, v127, v207
	v_mul_f32_e32 v124, 0xbfb8aa3b, v124
	v_mul_f32_e32 v125, 0xbfb8aa3b, v125
	v_mul_f32_e32 v126, 0xbfb8aa3b, v126
	v_mul_f32_e32 v127, 0xbfb8aa3b, v127
	v_exp_f32_e32 v124, v124
	v_exp_f32_e32 v125, v125
	v_exp_f32_e32 v126, v126
	v_exp_f32_e32 v127, v127
	s_nop 0
	v_add_f32_e32 v124, 1.0, v124
	v_add_f32_e32 v125, 1.0, v125
	v_add_f32_e32 v126, 1.0, v126
	v_add_f32_e32 v127, 1.0, v127
	v_rcp_f32_e32 v124, v124
	v_rcp_f32_e32 v125, v125
	v_rcp_f32_e32 v126, v126
	v_rcp_f32_e32 v127, v127
	s_nop 0
	v_mul_f32_e32 v124, 0x3f1b4598, v124
	v_mul_f32_e32 v125, 0x3f1b4598, v125
	v_mul_f32_e32 v126, 0x3f1b4598, v126
	v_mul_f32_e32 v127, 0x3f1b4598, v127
	v_cvt_pk_bf16_f32 v158, v124, v125
	v_cvt_pk_bf16_f32 v159, v126, v127
	ds_write_b64 v236, v[158:159] offset:16224
	s_waitcnt lgkmcnt(0)
; template <class Epi>
; DI void gemm_tile(char* smem, const bf16_t* __restrict__ A0, int lda0, int ksplit, const bf16_t* __restrict__ A1, int lda1,
;                   const bf16_t* __restrict__ Bt, int K, int row0, int col0, const Epi& epi, int tid) {
;     ...
; #pragma unroll
;   for (int m = 0; m < 8; ++m)
; #pragma unroll
;     for (int n = 0; n < 4; ++n) epi(row0 + wr * 128 + m * 16 + fr, col0 + wc * 64 + n * 16 + fq * 4, acc[m][n]);
	ds_read_b128 v[128:131], v237
	ds_read_b128 v[132:135], v237 offset:1152
	ds_read_b128 v[136:139], v237 offset:2304
	ds_read_b128 v[140:143], v237 offset:3456
	ds_read_b128 v[144:147], v237 offset:4608
	ds_read_b128 v[148:151], v237 offset:5760
	ds_read_b128 v[152:155], v237 offset:6912
	ds_read_b128 v[156:159], v237 offset:8064
	ds_read_b128 v[160:163], v237 offset:9216
	ds_read_b128 v[164:167], v237 offset:10368
	ds_read_b128 v[168:171], v237 offset:11520
	ds_read_b128 v[172:175], v237 offset:12672
	ds_read_b128 v[176:179], v237 offset:13824
	ds_read_b128 v[180:183], v237 offset:14976
	ds_read_b128 v[184:187], v237 offset:16128
	ds_read_b128 v[188:191], v237 offset:17280
	s_waitcnt lgkmcnt(15)
	global_store_dwordx4 v238, v[128:131], s[4:5] nt
	s_add_u32 s4, s4, 0x2000
	s_addc_u32 s5, s5, 0
	s_waitcnt lgkmcnt(14)
	global_store_dwordx4 v238, v[132:135], s[4:5] nt
	s_add_u32 s4, s4, 0x2000
	s_addc_u32 s5, s5, 0
	s_waitcnt lgkmcnt(13)
	global_store_dwordx4 v238, v[136:139], s[4:5] nt
	s_add_u32 s4, s4, 0x2000
	s_addc_u32 s5, s5, 0
	s_waitcnt lgkmcnt(12)
	global_store_dwordx4 v238, v[140:143], s[4:5] nt
	s_add_u32 s4, s4, 0x2000
	s_addc_u32 s5, s5, 0
	s_waitcnt lgkmcnt(11)
	global_store_dwordx4 v238, v[144:147], s[4:5] nt
	s_add_u32 s4, s4, 0x2000
	s_addc_u32 s5, s5, 0
	s_waitcnt lgkmcnt(10)
	global_store_dwordx4 v238, v[148:151], s[4:5] nt
	s_add_u32 s4, s4, 0x2000
	s_addc_u32 s5, s5, 0
	s_waitcnt lgkmcnt(9)
	global_store_dwordx4 v238, v[152:155], s[4:5] nt
	s_add_u32 s4, s4, 0x2000
	s_addc_u32 s5, s5, 0
	s_waitcnt lgkmcnt(8)
	global_store_dwordx4 v238, v[156:159], s[4:5] nt
	s_add_u32 s4, s4, 0x2000
	s_addc_u32 s5, s5, 0
	s_waitcnt lgkmcnt(7)
	global_store_dwordx4 v238, v[160:163], s[4:5] nt
	s_add_u32 s4, s4, 0x2000
	s_addc_u32 s5, s5, 0
	s_waitcnt lgkmcnt(6)
	global_store_dwordx4 v238, v[164:167], s[4:5] nt
	s_add_u32 s4, s4, 0x2000
	s_addc_u32 s5, s5, 0
	s_waitcnt lgkmcnt(5)
	global_store_dwordx4 v238, v[168:171], s[4:5] nt
	s_add_u32 s4, s4, 0x2000
	s_addc_u32 s5, s5, 0
	s_waitcnt lgkmcnt(4)
	global_store_dwordx4 v238, v[172:175], s[4:5] nt
	s_add_u32 s4, s4, 0x2000
	s_addc_u32 s5, s5, 0
	s_waitcnt lgkmcnt(3)
	global_store_dwordx4 v238, v[176:179], s[4:5] nt
	s_add_u32 s4, s4, 0x2000
	s_addc_u32 s5, s5, 0
	s_waitcnt lgkmcnt(2)
	global_store_dwordx4 v238, v[180:183], s[4:5] nt
	s_add_u32 s4, s4, 0x2000
	s_addc_u32 s5, s5, 0
	s_waitcnt lgkmcnt(1)
	global_store_dwordx4 v238, v[184:187], s[4:5] nt
	s_add_u32 s4, s4, 0x2000
	s_addc_u32 s5, s5, 0
	s_waitcnt lgkmcnt(0)
	global_store_dwordx4 v238, v[188:191], s[4:5] nt
	s_nop 1
	s_add_u32 s15, s15, 64
	s_branch .Lg3a_tile

; DI void phase_rw_small_gemms(const Ctx& c, char* smem) {
;     ...
;   gemm_phase(smem, sm, 256, 1 << 30, sm, 256, W2 + 512 * 64, 64, 4, EpiSmall{0, p.rw_w0 + 512, E1}, tid);
.Lg3b_epi:
	s_nop 7
	s_nop 7
	s_mul_i32 s27, s29, 1024
	s_lshl_b32 s26, s28, 1
	s_add_u32 s27, s27, s26
	s_add_u32 s27, s27, 0x9800000
	s_add_u32 s4, s92, s27
	s_addc_u32 s5, s93, 0
	s_lshl_b32 s27, s28, 2
	s_add_u32 s27, s27, 0x800
	s_add_u32 s2, s6, s27
	s_addc_u32 s3, s7, 0
	global_load_dwordx4 v[192:195], v235, s[2:3] offset:0
	global_load_dwordx4 v[196:199], v235, s[2:3] offset:64
	global_load_dwordx4 v[200:203], v235, s[2:3] offset:128
	global_load_dwordx4 v[204:207], v235, s[2:3] offset:192
	s_waitcnt vmcnt(0)
	v_add_f32_e32 v0, v0, v192
	v_add_f32_e32 v1, v1, v193
	v_add_f32_e32 v2, v2, v194
	v_add_f32_e32 v3, v3, v195
	v_mul_f32_e32 v0, 0xbfb8aa3b, v0
	v_mul_f32_e32 v1, 0xbfb8aa3b, v1
	v_mul_f32_e32 v2, 0xbfb8aa3b, v2
	v_mul_f32_e32 v3, 0xbfb8aa3b, v3
	v_exp_f32_e32 v0, v0
	v_exp_f32_e32 v1, v1
	v_exp_f32_e32 v2, v2
	v_exp_f32_e32 v3, v3
	s_nop 0
	v_add_f32_e32 v0, 1.0, v0
	v_add_f32_e32 v1, 1.0, v1
	v_add_f32_e32 v2, 1.0, v2
	v_add_f32_e32 v3, 1.0, v3
	v_rcp_f32_e32 v0, v0
	v_rcp_f32_e32 v1, v1
	v_rcp_f32_e32 v2, v2
	v_rcp_f32_e32 v3, v3
	s_nop 0
	v_mul_f32_e32 v0, 0x3f1b4598, v0
	v_mul_f32_e32 v1, 0x3f1b4598, v1
	v_mul_f32_e32 v2, 0x3f1b4598, v2
	v_mul_f32_e32 v3, 0x3f1b4598, v3
	v_cvt_pk_bf16_f32 v128, v0, v1
	v_cvt_pk_bf16_f32 v129, v2, v3
	ds_write_b64 v236, v[128:129]
	v_add_f32_e32 v4, v4, v196
	v_add_f32_e32 v5, v5, v197
	v_add_f32_e32 v6, v6, v198
	v_add_f32_e32 v7, v7, v199
	v_mul_f32_e32 v4, 0xbfb8aa3b, v4
	v_mul_f32_e32 v5, 0xbfb8aa3b, v5
	v_mul_f32_e32 v6, 0xbfb8aa3b, v6
	v_mul_f32_e32 v7, 0xbfb8aa3b, v7
	v_exp_f32_e32 v4, v4
	v_exp_f32_e32 v5, v5
	v_exp_f32_e32 v6, v6
	v_exp_f32_e32 v7, v7
	s_nop 0
	v_add_f32_e32 v4, 1.0, v4
	v_add_f32_e32 v5, 1.0, v5
	v_add_f32_e32 v6, 1.0, v6
	v_add_f32_e32 v7, 1.0, v7
	v_rcp_f32_e32 v4, v4
	v_rcp_f32_e32 v5, v5
	v_rcp_f32_e32 v6, v6
	v_rcp_f32_e32 v7, v7
	s_nop 0
	v_mul_f32_e32 v4, 0x3f1b4598, v4
	v_mul_f32_e32 v5, 0x3f1b4598, v5
	v_mul_f32_e32 v6, 0x3f1b4598, v6
	v_mul_f32_e32 v7, 0x3f1b4598, v7
	v_cvt_pk_bf16_f32 v130, v4, v5
	v_cvt_pk_bf16_f32 v131, v6, v7
	ds_write_b64 v236, v[130:131] offset:32
	v_add_f32_e32 v8, v8, v200
	v_add_f32_e32 v9, v9, v201
	v_add_f32_e32 v10, v10, v202
	v_add_f32_e32 v11, v11, v203
	v_mul_f32_e32 v8, 0xbfb8aa3b, v8
	v_mul_f32_e32 v9, 0xbfb8aa3b, v9
	v_mul_f32_e32 v10, 0xbfb8aa3b, v10
	v_mul_f32_e32 v11, 0xbfb8aa3b, v11
	v_exp_f32_e32 v8, v8
	v_exp_f32_e32 v9, v9
	v_exp_f32_e32 v10, v10
	v_exp_f32_e32 v11, v11
	s_nop 0
	v_add_f32_e32 v8, 1.0, v8
	v_add_f32_e32 v9, 1.0, v9
	v_add_f32_e32 v10, 1.0, v10
	v_add_f32_e32 v11, 1.0, v11
	v_rcp_f32_e32 v8, v8
	v_rcp_f32_e32 v9, v9
	v_rcp_f32_e32 v10, v10
	v_rcp_f32_e32 v11, v11
	s_nop 0
	v_mul_f32_e32 v8, 0x3f1b4598, v8
	v_mul_f32_e32 v9, 0x3f1b4598, v9
	v_mul_f32_e32 v10, 0x3f1b4598, v10
	v_mul_f32_e32 v11, 0x3f1b4598, v11
	v_cvt_pk_bf16_f32 v132, v8, v9
	v_cvt_pk_bf16_f32 v133, v10, v11
	ds_write_b64 v236, v[132:133] offset:64
	v_add_f32_e32 v12, v12, v204
	v_add_f32_e32 v13, v13, v205
	v_add_f32_e32 v14, v14, v206
	v_add_f32_e32 v15, v15, v207
	v_mul_f32_e32 v12, 0xbfb8aa3b, v12
	v_mul_f32_e32 v13, 0xbfb8aa3b, v13
	v_mul_f32_e32 v14, 0xbfb8aa3b, v14
	v_mul_f32_e32 v15, 0xbfb8aa3b, v15
	v_exp_f32_e32 v12, v12
	v_exp_f32_e32 v13, v13
	v_exp_f32_e32 v14, v14
	v_exp_f32_e32 v15, v15
	s_nop 0
	v_add_f32_e32 v12, 1.0, v12
	v_add_f32_e32 v13, 1.0, v13
	v_add_f32_e32 v14, 1.0, v14
	v_add_f32_e32 v15, 1.0, v15
	v_rcp_f32_e32 v12, v12
	v_rcp_f32_e32 v13, v13
	v_rcp_f32_e32 v14, v14
	v_rcp_f32_e32 v15, v15
	s_nop 0
	v_mul_f32_e32 v12, 0x3f1b4598, v12
	v_mul_f32_e32 v13, 0x3f1b4598, v13
	v_mul_f32_e32 v14, 0x3f1b4598, v14
	v_mul_f32_e32 v15, 0x3f1b4598, v15
	v_cvt_pk_bf16_f32 v134, v12, v13
	v_cvt_pk_bf16_f32 v135, v14, v15
	ds_write_b64 v236, v[134:135] offset:96
	v_add_f32_e32 v16, v16, v192
	v_add_f32_e32 v17, v17, v193
	v_add_f32_e32 v18, v18, v194
	v_add_f32_e32 v19, v19, v195
	v_mul_f32_e32 v16, 0xbfb8aa3b, v16
	v_mul_f32_e32 v17, 0xbfb8aa3b, v17
	v_mul_f32_e32 v18, 0xbfb8aa3b, v18
	v_mul_f32_e32 v19, 0xbfb8aa3b, v19
	v_exp_f32_e32 v16, v16
	v_exp_f32_e32 v17, v17
	v_exp_f32_e32 v18, v18
	v_exp_f32_e32 v19, v19
	s_nop 0
	v_add_f32_e32 v16, 1.0, v16
	v_add_f32_e32 v17, 1.0, v17
	v_add_f32_e32 v18, 1.0, v18
	v_add_f32_e32 v19, 1.0, v19
	v_rcp_f32_e32 v16, v16
	v_rcp_f32_e32 v17, v17
	v_rcp_f32_e32 v18, v18
	v_rcp_f32_e32 v19, v19
	s_nop 0
	v_mul_f32_e32 v16, 0x3f1b4598, v16
	v_mul_f32_e32 v17, 0x3f1b4598, v17
	v_mul_f32_e32 v18, 0x3f1b4598, v18
	v_mul_f32_e32 v19, 0x3f1b4598, v19
	v_cvt_pk_bf16_f32 v136, v16, v17
	v_cvt_pk_bf16_f32 v137, v18, v19
	ds_write_b64 v236, v[136:137] offset:2304
	v_add_f32_e32 v20, v20, v196
	v_add_f32_e32 v21, v21, v197
	v_add_f32_e32 v22, v22, v198
	v_add_f32_e32 v23, v23, v199
	v_mul_f32_e32 v20, 0xbfb8aa3b, v20
	v_mul_f32_e32 v21, 0xbfb8aa3b, v21
	v_mul_f32_e32 v22, 0xbfb8aa3b, v22
	v_mul_f32_e32 v23, 0xbfb8aa3b, v23
	v_exp_f32_e32 v20, v20
	v_exp_f32_e32 v21, v21
	v_exp_f32_e32 v22, v22
	v_exp_f32_e32 v23, v23
	s_nop 0
	v_add_f32_e32 v20, 1.0, v20
	v_add_f32_e32 v21, 1.0, v21
	v_add_f32_e32 v22, 1.0, v22
	v_add_f32_e32 v23, 1.0, v23
	v_rcp_f32_e32 v20, v20
	v_rcp_f32_e32 v21, v21
	v_rcp_f32_e32 v22, v22
	v_rcp_f32_e32 v23, v23
	s_nop 0
	v_mul_f32_e32 v20, 0x3f1b4598, v20
	v_mul_f32_e32 v21, 0x3f1b4598, v21
	v_mul_f32_e32 v22, 0x3f1b4598, v22
	v_mul_f32_e32 v23, 0x3f1b4598, v23
	v_cvt_pk_bf16_f32 v138, v20, v21
	v_cvt_pk_bf16_f32 v139, v22, v23
	ds_write_b64 v236, v[138:139] offset:2336
	v_add_f32_e32 v24, v24, v200
	v_add_f32_e32 v25, v25, v201
	v_add_f32_e32 v26, v26, v202
	v_add_f32_e32 v27, v27, v203
	v_mul_f32_e32 v24, 0xbfb8aa3b, v24
	v_mul_f32_e32 v25, 0xbfb8aa3b, v25
	v_mul_f32_e32 v26, 0xbfb8aa3b, v26
	v_mul_f32_e32 v27, 0xbfb8aa3b, v27
	v_exp_f32_e32 v24, v24
	v_exp_f32_e32 v25, v25
	v_exp_f32_e32 v26, v26
	v_exp_f32_e32 v27, v27
	s_nop 0
	v_add_f32_e32 v24, 1.0, v24
	v_add_f32_e32 v25, 1.0, v25
	v_add_f32_e32 v26, 1.0, v26
	v_add_f32_e32 v27, 1.0, v27
	v_rcp_f32_e32 v24, v24
	v_rcp_f32_e32 v25, v25
	v_rcp_f32_e32 v26, v26
	v_rcp_f32_e32 v27, v27
	s_nop 0
	v_mul_f32_e32 v24, 0x3f1b4598, v24
	v_mul_f32_e32 v25, 0x3f1b4598, v25
	v_mul_f32_e32 v26, 0x3f1b4598, v26
	v_mul_f32_e32 v27, 0x3f1b4598, v27
	v_cvt_pk_bf16_f32 v140, v24, v25
	v_cvt_pk_bf16_f32 v141, v26, v27
	ds_write_b64 v236, v[140:141] offset:2368
	v_add_f32_e32 v28, v28, v204
	v_add_f32_e32 v29, v29, v205
	v_add_f32_e32 v30, v30, v206
	v_add_f32_e32 v31, v31, v207
	v_mul_f32_e32 v28, 0xbfb8aa3b, v28
	v_mul_f32_e32 v29, 0xbfb8aa3b, v29
	v_mul_f32_e32 v30, 0xbfb8aa3b, v30
	v_mul_f32_e32 v31, 0xbfb8aa3b, v31
	v_exp_f32_e32 v28, v28
	v_exp_f32_e32 v29, v29
	v_exp_f32_e32 v30, v30
	v_exp_f32_e32 v31, v31
	s_nop 0
	v_add_f32_e32 v28, 1.0, v28
	v_add_f32_e32 v29, 1.0, v29
	v_add_f32_e32 v30, 1.0, v30
	v_add_f32_e32 v31, 1.0, v31
	v_rcp_f32_e32 v28, v28
	v_rcp_f32_e32 v29, v29
	v_rcp_f32_e32 v30, v30
	v_rcp_f32_e32 v31, v31
	s_nop 0
	v_mul_f32_e32 v28, 0x3f1b4598, v28
	v_mul_f32_e32 v29, 0x3f1b4598, v29
	v_mul_f32_e32 v30, 0x3f1b4598, v30
	v_mul_f32_e32 v31, 0x3f1b4598, v31
	v_cvt_pk_bf16_f32 v142, v28, v29
	v_cvt_pk_bf16_f32 v143, v30, v31
	ds_write_b64 v236, v[142:143] offset:2400
	v_add_f32_e32 v32, v32, v192
	v_add_f32_e32 v33, v33, v193
	v_add_f32_e32 v34, v34, v194
	v_add_f32_e32 v35, v35, v195
	v_mul_f32_e32 v32, 0xbfb8aa3b, v32
	v_mul_f32_e32 v33, 0xbfb8aa3b, v33
	v_mul_f32_e32 v34, 0xbfb8aa3b, v34
	v_mul_f32_e32 v35, 0xbfb8aa3b, v35
	v_exp_f32_e32 v32, v32
	v_exp_f32_e32 v33, v33
	v_exp_f32_e32 v34, v34
	v_exp_f32_e32 v35, v35
	s_nop 0
	v_add_f32_e32 v32, 1.0, v32
	v_add_f32_e32 v33, 1.0, v33
	v_add_f32_e32 v34, 1.0, v34
	v_add_f32_e32 v35, 1.0, v35
	v_rcp_f32_e32 v32, v32
	v_rcp_f32_e32 v33, v33
	v_rcp_f32_e32 v34, v34
	v_rcp_f32_e32 v35, v35
	s_nop 0
	v_mul_f32_e32 v32, 0x3f1b4598, v32
	v_mul_f32_e32 v33, 0x3f1b4598, v33
	v_mul_f32_e32 v34, 0x3f1b4598, v34
	v_mul_f32_e32 v35, 0x3f1b4598, v35
	v_cvt_pk_bf16_f32 v144, v32, v33
	v_cvt_pk_bf16_f32 v145, v34, v35
	ds_write_b64 v236, v[144:145] offset:4608
	v_add_f32_e32 v36, v36, v196
	v_add_f32_e32 v37, v37, v197
	v_add_f32_e32 v38, v38, v198
	v_add_f32_e32 v39, v39, v199
	v_mul_f32_e32 v36, 0xbfb8aa3b, v36
	v_mul_f32_e32 v37, 0xbfb8aa3b, v37
	v_mul_f32_e32 v38, 0xbfb8aa3b, v38
	v_mul_f32_e32 v39, 0xbfb8aa3b, v39
	v_exp_f32_e32 v36, v36
	v_exp_f32_e32 v37, v37
	v_exp_f32_e32 v38, v38
	v_exp_f32_e32 v39, v39
	s_nop 0
	v_add_f32_e32 v36, 1.0, v36
	v_add_f32_e32 v37, 1.0, v37
	v_add_f32_e32 v38, 1.0, v38
	v_add_f32_e32 v39, 1.0, v39
	v_rcp_f32_e32 v36, v36
	v_rcp_f32_e32 v37, v37
	v_rcp_f32_e32 v38, v38
	v_rcp_f32_e32 v39, v39
	s_nop 0
	v_mul_f32_e32 v36, 0x3f1b4598, v36
	v_mul_f32_e32 v37, 0x3f1b4598, v37
	v_mul_f32_e32 v38, 0x3f1b4598, v38
	v_mul_f32_e32 v39, 0x3f1b4598, v39
	v_cvt_pk_bf16_f32 v146, v36, v37
	v_cvt_pk_bf16_f32 v147, v38, v39
	ds_write_b64 v236, v[146:147] offset:4640
	v_add_f32_e32 v40, v40, v200
	v_add_f32_e32 v41, v41, v201
	v_add_f32_e32 v42, v42, v202
	v_add_f32_e32 v43, v43, v203
	v_mul_f32_e32 v40, 0xbfb8aa3b, v40
	v_mul_f32_e32 v41, 0xbfb8aa3b, v41
	v_mul_f32_e32 v42, 0xbfb8aa3b, v42
	v_mul_f32_e32 v43, 0xbfb8aa3b, v43
	v_exp_f32_e32 v40, v40
	v_exp_f32_e32 v41, v41
	v_exp_f32_e32 v42, v42
	v_exp_f32_e32 v43, v43
	s_nop 0
	v_add_f32_e32 v40, 1.0, v40
	v_add_f32_e32 v41, 1.0, v41
	v_add_f32_e32 v42, 1.0, v42
	v_add_f32_e32 v43, 1.0, v43
	v_rcp_f32_e32 v40, v40
	v_rcp_f32_e32 v41, v41
	v_rcp_f32_e32 v42, v42
	v_rcp_f32_e32 v43, v43
	s_nop 0
	v_mul_f32_e32 v40, 0x3f1b4598, v40
	v_mul_f32_e32 v41, 0x3f1b4598, v41
	v_mul_f32_e32 v42, 0x3f1b4598, v42
	v_mul_f32_e32 v43, 0x3f1b4598, v43
	v_cvt_pk_bf16_f32 v148, v40, v41
	v_cvt_pk_bf16_f32 v149, v42, v43
	ds_write_b64 v236, v[148:149] offset:4672
	v_add_f32_e32 v44, v44, v204
	v_add_f32_e32 v45, v45, v205
	v_add_f32_e32 v46, v46, v206
	v_add_f32_e32 v47, v47, v207
	v_mul_f32_e32 v44, 0xbfb8aa3b, v44
	v_mul_f32_e32 v45, 0xbfb8aa3b, v45
	v_mul_f32_e32 v46, 0xbfb8aa3b, v46
	v_mul_f32_e32 v47, 0xbfb8aa3b, v47
	v_exp_f32_e32 v44, v44
	v_exp_f32_e32 v45, v45
	v_exp_f32_e32 v46, v46
	v_exp_f32_e32 v47, v47
	s_nop 0
	v_add_f32_e32 v44, 1.0, v44
	v_add_f32_e32 v45, 1.0, v45
	v_add_f32_e32 v46, 1.0, v46
	v_add_f32_e32 v47, 1.0, v47
	v_rcp_f32_e32 v44, v44
	v_rcp_f32_e32 v45, v45
	v_rcp_f32_e32 v46, v46
	v_rcp_f32_e32 v47, v47
	s_nop 0
	v_mul_f32_e32 v44, 0x3f1b4598, v44
	v_mul_f32_e32 v45, 0x3f1b4598, v45
	v_mul_f32_e32 v46, 0x3f1b4598, v46
	v_mul_f32_e32 v47, 0x3f1b4598, v47
	v_cvt_pk_bf16_f32 v150, v44, v45
	v_cvt_pk_bf16_f32 v151, v46, v47
	ds_write_b64 v236, v[150:151] offset:4704
	v_add_f32_e32 v48, v48, v192
	v_add_f32_e32 v49, v49, v193
	v_add_f32_e32 v50, v50, v194
	v_add_f32_e32 v51, v51, v195
	v_mul_f32_e32 v48, 0xbfb8aa3b, v48
	v_mul_f32_e32 v49, 0xbfb8aa3b, v49
	v_mul_f32_e32 v50, 0xbfb8aa3b, v50
	v_mul_f32_e32 v51, 0xbfb8aa3b, v51
	v_exp_f32_e32 v48, v48
	v_exp_f32_e32 v49, v49
	v_exp_f32_e32 v50, v50
	v_exp_f32_e32 v51, v51
	s_nop 0
	v_add_f32_e32 v48, 1.0, v48
	v_add_f32_e32 v49, 1.0, v49
	v_add_f32_e32 v50, 1.0, v50
	v_add_f32_e32 v51, 1.0, v51
	v_rcp_f32_e32 v48, v48
	v_rcp_f32_e32 v49, v49
	v_rcp_f32_e32 v50, v50
	v_rcp_f32_e32 v51, v51
	s_nop 0
	v_mul_f32_e32 v48, 0x3f1b4598, v48
	v_mul_f32_e32 v49, 0x3f1b4598, v49
	v_mul_f32_e32 v50, 0x3f1b4598, v50
	v_mul_f32_e32 v51, 0x3f1b4598, v51
	v_cvt_pk_bf16_f32 v152, v48, v49
	v_cvt_pk_bf16_f32 v153, v50, v51
	ds_write_b64 v236, v[152:153] offset:6912
	v_add_f32_e32 v52, v52, v196
	v_add_f32_e32 v53, v53, v197
	v_add_f32_e32 v54, v54, v198
	v_add_f32_e32 v55, v55, v199
	v_mul_f32_e32 v52, 0xbfb8aa3b, v52
	v_mul_f32_e32 v53, 0xbfb8aa3b, v53
	v_mul_f32_e32 v54, 0xbfb8aa3b, v54
	v_mul_f32_e32 v55, 0xbfb8aa3b, v55
	v_exp_f32_e32 v52, v52
	v_exp_f32_e32 v53, v53
	v_exp_f32_e32 v54, v54
	v_exp_f32_e32 v55, v55
	s_nop 0
	v_add_f32_e32 v52, 1.0, v52
	v_add_f32_e32 v53, 1.0, v53
	v_add_f32_e32 v54, 1.0, v54
	v_add_f32_e32 v55, 1.0, v55
	v_rcp_f32_e32 v52, v52
	v_rcp_f32_e32 v53, v53
	v_rcp_f32_e32 v54, v54
	v_rcp_f32_e32 v55, v55
	s_nop 0
	v_mul_f32_e32 v52, 0x3f1b4598, v52
	v_mul_f32_e32 v53, 0x3f1b4598, v53
	v_mul_f32_e32 v54, 0x3f1b4598, v54
	v_mul_f32_e32 v55, 0x3f1b4598, v55
	v_cvt_pk_bf16_f32 v154, v52, v53
	v_cvt_pk_bf16_f32 v155, v54, v55
	ds_write_b64 v236, v[154:155] offset:6944
	v_add_f32_e32 v56, v56, v200
	v_add_f32_e32 v57, v57, v201
	v_add_f32_e32 v58, v58, v202
	v_add_f32_e32 v59, v59, v203
	v_mul_f32_e32 v56, 0xbfb8aa3b, v56
	v_mul_f32_e32 v57, 0xbfb8aa3b, v57
	v_mul_f32_e32 v58, 0xbfb8aa3b, v58
	v_mul_f32_e32 v59, 0xbfb8aa3b, v59
	v_exp_f32_e32 v56, v56
	v_exp_f32_e32 v57, v57
	v_exp_f32_e32 v58, v58
	v_exp_f32_e32 v59, v59
	s_nop 0
	v_add_f32_e32 v56, 1.0, v56
	v_add_f32_e32 v57, 1.0, v57
	v_add_f32_e32 v58, 1.0, v58
	v_add_f32_e32 v59, 1.0, v59
	v_rcp_f32_e32 v56, v56
	v_rcp_f32_e32 v57, v57
	v_rcp_f32_e32 v58, v58
	v_rcp_f32_e32 v59, v59
	s_nop 0
	v_mul_f32_e32 v56, 0x3f1b4598, v56
	v_mul_f32_e32 v57, 0x3f1b4598, v57
	v_mul_f32_e32 v58, 0x3f1b4598, v58
	v_mul_f32_e32 v59, 0x3f1b4598, v59
	v_cvt_pk_bf16_f32 v156, v56, v57
	v_cvt_pk_bf16_f32 v157, v58, v59
	ds_write_b64 v236, v[156:157] offset:6976
	v_add_f32_e32 v60, v60, v204
	v_add_f32_e32 v61, v61, v205
	v_add_f32_e32 v62, v62, v206
	v_add_f32_e32 v63, v63, v207
	v_mul_f32_e32 v60, 0xbfb8aa3b, v60
	v_mul_f32_e32 v61, 0xbfb8aa3b, v61
	v_mul_f32_e32 v62, 0xbfb8aa3b, v62
	v_mul_f32_e32 v63, 0xbfb8aa3b, v63
	v_exp_f32_e32 v60, v60
	v_exp_f32_e32 v61, v61
	v_exp_f32_e32 v62, v62
	v_exp_f32_e32 v63, v63
	s_nop 0
	v_add_f32_e32 v60, 1.0, v60
	v_add_f32_e32 v61, 1.0, v61
	v_add_f32_e32 v62, 1.0, v62
	v_add_f32_e32 v63, 1.0, v63
	v_rcp_f32_e32 v60, v60
	v_rcp_f32_e32 v61, v61
	v_rcp_f32_e32 v62, v62
	v_rcp_f32_e32 v63, v63
	s_nop 0
	v_mul_f32_e32 v60, 0x3f1b4598, v60
	v_mul_f32_e32 v61, 0x3f1b4598, v61
	v_mul_f32_e32 v62, 0x3f1b4598, v62
	v_mul_f32_e32 v63, 0x3f1b4598, v63
	v_cvt_pk_bf16_f32 v158, v60, v61
	v_cvt_pk_bf16_f32 v159, v62, v63
	ds_write_b64 v236, v[158:159] offset:7008
	v_add_f32_e32 v64, v64, v192
	v_add_f32_e32 v65, v65, v193
	v_add_f32_e32 v66, v66, v194
	v_add_f32_e32 v67, v67, v195
	v_mul_f32_e32 v64, 0xbfb8aa3b, v64
	v_mul_f32_e32 v65, 0xbfb8aa3b, v65
	v_mul_f32_e32 v66, 0xbfb8aa3b, v66
	v_mul_f32_e32 v67, 0xbfb8aa3b, v67
	v_exp_f32_e32 v64, v64
	v_exp_f32_e32 v65, v65
	v_exp_f32_e32 v66, v66
	v_exp_f32_e32 v67, v67
	s_nop 0
	v_add_f32_e32 v64, 1.0, v64
	v_add_f32_e32 v65, 1.0, v65
	v_add_f32_e32 v66, 1.0, v66
	v_add_f32_e32 v67, 1.0, v67
	v_rcp_f32_e32 v64, v64
	v_rcp_f32_e32 v65, v65
	v_rcp_f32_e32 v66, v66
	v_rcp_f32_e32 v67, v67
	s_nop 0
	v_mul_f32_e32 v64, 0x3f1b4598, v64
	v_mul_f32_e32 v65, 0x3f1b4598, v65
	v_mul_f32_e32 v66, 0x3f1b4598, v66
	v_mul_f32_e32 v67, 0x3f1b4598, v67
	v_cvt_pk_bf16_f32 v128, v64, v65
	v_cvt_pk_bf16_f32 v129, v66, v67
	ds_write_b64 v236, v[128:129] offset:9216
	v_add_f32_e32 v68, v68, v196
	v_add_f32_e32 v69, v69, v197
	v_add_f32_e32 v70, v70, v198
	v_add_f32_e32 v71, v71, v199
	v_mul_f32_e32 v68, 0xbfb8aa3b, v68
	v_mul_f32_e32 v69, 0xbfb8aa3b, v69
	v_mul_f32_e32 v70, 0xbfb8aa3b, v70
	v_mul_f32_e32 v71, 0xbfb8aa3b, v71
	v_exp_f32_e32 v68, v68
	v_exp_f32_e32 v69, v69
	v_exp_f32_e32 v70, v70
	v_exp_f32_e32 v71, v71
	s_nop 0
	v_add_f32_e32 v68, 1.0, v68
	v_add_f32_e32 v69, 1.0, v69
	v_add_f32_e32 v70, 1.0, v70
	v_add_f32_e32 v71, 1.0, v71
	v_rcp_f32_e32 v68, v68
	v_rcp_f32_e32 v69, v69
	v_rcp_f32_e32 v70, v70
	v_rcp_f32_e32 v71, v71
	s_nop 0
	v_mul_f32_e32 v68, 0x3f1b4598, v68
	v_mul_f32_e32 v69, 0x3f1b4598, v69
	v_mul_f32_e32 v70, 0x3f1b4598, v70
	v_mul_f32_e32 v71, 0x3f1b4598, v71
	v_cvt_pk_bf16_f32 v130, v68, v69
	v_cvt_pk_bf16_f32 v131, v70, v71
	ds_write_b64 v236, v[130:131] offset:9248
	v_add_f32_e32 v72, v72, v200
	v_add_f32_e32 v73, v73, v201
	v_add_f32_e32 v74, v74, v202
	v_add_f32_e32 v75, v75, v203
	v_mul_f32_e32 v72, 0xbfb8aa3b, v72
	v_mul_f32_e32 v73, 0xbfb8aa3b, v73
	v_mul_f32_e32 v74, 0xbfb8aa3b, v74
	v_mul_f32_e32 v75, 0xbfb8aa3b, v75
	v_exp_f32_e32 v72, v72
	v_exp_f32_e32 v73, v73
	v_exp_f32_e32 v74, v74
	v_exp_f32_e32 v75, v75
	s_nop 0
	v_add_f32_e32 v72, 1.0, v72
	v_add_f32_e32 v73, 1.0, v73
	v_add_f32_e32 v74, 1.0, v74
	v_add_f32_e32 v75, 1.0, v75
	v_rcp_f32_e32 v72, v72
	v_rcp_f32_e32 v73, v73
	v_rcp_f32_e32 v74, v74
	v_rcp_f32_e32 v75, v75
	s_nop 0
	v_mul_f32_e32 v72, 0x3f1b4598, v72
	v_mul_f32_e32 v73, 0x3f1b4598, v73
	v_mul_f32_e32 v74, 0x3f1b4598, v74
	v_mul_f32_e32 v75, 0x3f1b4598, v75
	v_cvt_pk_bf16_f32 v132, v72, v73
	v_cvt_pk_bf16_f32 v133, v74, v75
	ds_write_b64 v236, v[132:133] offset:9280
	v_add_f32_e32 v76, v76, v204
	v_add_f32_e32 v77, v77, v205
	v_add_f32_e32 v78, v78, v206
	v_add_f32_e32 v79, v79, v207
	v_mul_f32_e32 v76, 0xbfb8aa3b, v76
	v_mul_f32_e32 v77, 0xbfb8aa3b, v77
	v_mul_f32_e32 v78, 0xbfb8aa3b, v78
	v_mul_f32_e32 v79, 0xbfb8aa3b, v79
	v_exp_f32_e32 v76, v76
	v_exp_f32_e32 v77, v77
	v_exp_f32_e32 v78, v78
	v_exp_f32_e32 v79, v79
	s_nop 0
	v_add_f32_e32 v76, 1.0, v76
	v_add_f32_e32 v77, 1.0, v77
	v_add_f32_e32 v78, 1.0, v78
	v_add_f32_e32 v79, 1.0, v79
	v_rcp_f32_e32 v76, v76
	v_rcp_f32_e32 v77, v77
	v_rcp_f32_e32 v78, v78
	v_rcp_f32_e32 v79, v79
	s_nop 0
	v_mul_f32_e32 v76, 0x3f1b4598, v76
	v_mul_f32_e32 v77, 0x3f1b4598, v77
	v_mul_f32_e32 v78, 0x3f1b4598, v78
	v_mul_f32_e32 v79, 0x3f1b4598, v79
	v_cvt_pk_bf16_f32 v134, v76, v77
	v_cvt_pk_bf16_f32 v135, v78, v79
	ds_write_b64 v236, v[134:135] offset:9312
	v_add_f32_e32 v80, v80, v192
	v_add_f32_e32 v81, v81, v193
	v_add_f32_e32 v82, v82, v194
	v_add_f32_e32 v83, v83, v195
	v_mul_f32_e32 v80, 0xbfb8aa3b, v80
	v_mul_f32_e32 v81, 0xbfb8aa3b, v81
	v_mul_f32_e32 v82, 0xbfb8aa3b, v82
	v_mul_f32_e32 v83, 0xbfb8aa3b, v83
	v_exp_f32_e32 v80, v80
	v_exp_f32_e32 v81, v81
	v_exp_f32_e32 v82, v82
	v_exp_f32_e32 v83, v83
	s_nop 0
	v_add_f32_e32 v80, 1.0, v80
	v_add_f32_e32 v81, 1.0, v81
	v_add_f32_e32 v82, 1.0, v82
	v_add_f32_e32 v83, 1.0, v83
	v_rcp_f32_e32 v80, v80
	v_rcp_f32_e32 v81, v81
	v_rcp_f32_e32 v82, v82
	v_rcp_f32_e32 v83, v83
	s_nop 0
	v_mul_f32_e32 v80, 0x3f1b4598, v80
	v_mul_f32_e32 v81, 0x3f1b4598, v81
	v_mul_f32_e32 v82, 0x3f1b4598, v82
	v_mul_f32_e32 v83, 0x3f1b4598, v83
	v_cvt_pk_bf16_f32 v136, v80, v81
	v_cvt_pk_bf16_f32 v137, v82, v83
	ds_write_b64 v236, v[136:137] offset:11520
	v_add_f32_e32 v84, v84, v196
	v_add_f32_e32 v85, v85, v197
	v_add_f32_e32 v86, v86, v198
	v_add_f32_e32 v87, v87, v199
	v_mul_f32_e32 v84, 0xbfb8aa3b, v84
	v_mul_f32_e32 v85, 0xbfb8aa3b, v85
	v_mul_f32_e32 v86, 0xbfb8aa3b, v86
	v_mul_f32_e32 v87, 0xbfb8aa3b, v87
	v_exp_f32_e32 v84, v84
	v_exp_f32_e32 v85, v85
	v_exp_f32_e32 v86, v86
	v_exp_f32_e32 v87, v87
	s_nop 0
	v_add_f32_e32 v84, 1.0, v84
	v_add_f32_e32 v85, 1.0, v85
	v_add_f32_e32 v86, 1.0, v86
	v_add_f32_e32 v87, 1.0, v87
	v_rcp_f32_e32 v84, v84
	v_rcp_f32_e32 v85, v85
	v_rcp_f32_e32 v86, v86
	v_rcp_f32_e32 v87, v87
	s_nop 0
	v_mul_f32_e32 v84, 0x3f1b4598, v84
	v_mul_f32_e32 v85, 0x3f1b4598, v85
	v_mul_f32_e32 v86, 0x3f1b4598, v86
	v_mul_f32_e32 v87, 0x3f1b4598, v87
	v_cvt_pk_bf16_f32 v138, v84, v85
	v_cvt_pk_bf16_f32 v139, v86, v87
	ds_write_b64 v236, v[138:139] offset:11552
	v_add_f32_e32 v88, v88, v200
	v_add_f32_e32 v89, v89, v201
	v_add_f32_e32 v90, v90, v202
	v_add_f32_e32 v91, v91, v203
	v_mul_f32_e32 v88, 0xbfb8aa3b, v88
	v_mul_f32_e32 v89, 0xbfb8aa3b, v89
	v_mul_f32_e32 v90, 0xbfb8aa3b, v90
	v_mul_f32_e32 v91, 0xbfb8aa3b, v91
	v_exp_f32_e32 v88, v88
	v_exp_f32_e32 v89, v89
	v_exp_f32_e32 v90, v90
	v_exp_f32_e32 v91, v91
	s_nop 0
	v_add_f32_e32 v88, 1.0, v88
	v_add_f32_e32 v89, 1.0, v89
	v_add_f32_e32 v90, 1.0, v90
	v_add_f32_e32 v91, 1.0, v91
	v_rcp_f32_e32 v88, v88
	v_rcp_f32_e32 v89, v89
	v_rcp_f32_e32 v90, v90
	v_rcp_f32_e32 v91, v91
	s_nop 0
	v_mul_f32_e32 v88, 0x3f1b4598, v88
	v_mul_f32_e32 v89, 0x3f1b4598, v89
	v_mul_f32_e32 v90, 0x3f1b4598, v90
	v_mul_f32_e32 v91, 0x3f1b4598, v91
	v_cvt_pk_bf16_f32 v140, v88, v89
	v_cvt_pk_bf16_f32 v141, v90, v91
	ds_write_b64 v236, v[140:141] offset:11584
	v_add_f32_e32 v92, v92, v204
	v_add_f32_e32 v93, v93, v205
	v_add_f32_e32 v94, v94, v206
	v_add_f32_e32 v95, v95, v207
	v_mul_f32_e32 v92, 0xbfb8aa3b, v92
	v_mul_f32_e32 v93, 0xbfb8aa3b, v93
	v_mul_f32_e32 v94, 0xbfb8aa3b, v94
	v_mul_f32_e32 v95, 0xbfb8aa3b, v95
	v_exp_f32_e32 v92, v92
	v_exp_f32_e32 v93, v93
	v_exp_f32_e32 v94, v94
	v_exp_f32_e32 v95, v95
	s_nop 0
	v_add_f32_e32 v92, 1.0, v92
	v_add_f32_e32 v93, 1.0, v93
	v_add_f32_e32 v94, 1.0, v94
	v_add_f32_e32 v95, 1.0, v95
	v_rcp_f32_e32 v92, v92
	v_rcp_f32_e32 v93, v93
	v_rcp_f32_e32 v94, v94
	v_rcp_f32_e32 v95, v95
	s_nop 0
	v_mul_f32_e32 v92, 0x3f1b4598, v92
	v_mul_f32_e32 v93, 0x3f1b4598, v93
	v_mul_f32_e32 v94, 0x3f1b4598, v94
	v_mul_f32_e32 v95, 0x3f1b4598, v95
	v_cvt_pk_bf16_f32 v142, v92, v93
	v_cvt_pk_bf16_f32 v143, v94, v95
	ds_write_b64 v236, v[142:143] offset:11616
	v_add_f32_e32 v96, v96, v192
	v_add_f32_e32 v97, v97, v193
	v_add_f32_e32 v98, v98, v194
	v_add_f32_e32 v99, v99, v195
	v_mul_f32_e32 v96, 0xbfb8aa3b, v96
	v_mul_f32_e32 v97, 0xbfb8aa3b, v97
	v_mul_f32_e32 v98, 0xbfb8aa3b, v98
	v_mul_f32_e32 v99, 0xbfb8aa3b, v99
	v_exp_f32_e32 v96, v96
	v_exp_f32_e32 v97, v97
	v_exp_f32_e32 v98, v98
	v_exp_f32_e32 v99, v99
	s_nop 0
	v_add_f32_e32 v96, 1.0, v96
	v_add_f32_e32 v97, 1.0, v97
	v_add_f32_e32 v98, 1.0, v98
	v_add_f32_e32 v99, 1.0, v99
	v_rcp_f32_e32 v96, v96
	v_rcp_f32_e32 v97, v97
	v_rcp_f32_e32 v98, v98
	v_rcp_f32_e32 v99, v99
	s_nop 0
	v_mul_f32_e32 v96, 0x3f1b4598, v96
	v_mul_f32_e32 v97, 0x3f1b4598, v97
	v_mul_f32_e32 v98, 0x3f1b4598, v98
	v_mul_f32_e32 v99, 0x3f1b4598, v99
	v_cvt_pk_bf16_f32 v144, v96, v97
	v_cvt_pk_bf16_f32 v145, v98, v99
	ds_write_b64 v236, v[144:145] offset:13824
	v_add_f32_e32 v100, v100, v196
	v_add_f32_e32 v101, v101, v197
	v_add_f32_e32 v102, v102, v198
	v_add_f32_e32 v103, v103, v199
	v_mul_f32_e32 v100, 0xbfb8aa3b, v100
	v_mul_f32_e32 v101, 0xbfb8aa3b, v101
	v_mul_f32_e32 v102, 0xbfb8aa3b, v102
	v_mul_f32_e32 v103, 0xbfb8aa3b, v103
	v_exp_f32_e32 v100, v100
	v_exp_f32_e32 v101, v101
	v_exp_f32_e32 v102, v102
	v_exp_f32_e32 v103, v103
	s_nop 0
	v_add_f32_e32 v100, 1.0, v100
	v_add_f32_e32 v101, 1.0, v101
	v_add_f32_e32 v102, 1.0, v102
	v_add_f32_e32 v103, 1.0, v103
	v_rcp_f32_e32 v100, v100
	v_rcp_f32_e32 v101, v101
	v_rcp_f32_e32 v102, v102
	v_rcp_f32_e32 v103, v103
	s_nop 0
	v_mul_f32_e32 v100, 0x3f1b4598, v100
	v_mul_f32_e32 v101, 0x3f1b4598, v101
	v_mul_f32_e32 v102, 0x3f1b4598, v102
	v_mul_f32_e32 v103, 0x3f1b4598, v103
	v_cvt_pk_bf16_f32 v146, v100, v101
	v_cvt_pk_bf16_f32 v147, v102, v103
	ds_write_b64 v236, v[146:147] offset:13856
	v_add_f32_e32 v104, v104, v200
	v_add_f32_e32 v105, v105, v201
	v_add_f32_e32 v106, v106, v202
	v_add_f32_e32 v107, v107, v203
	v_mul_f32_e32 v104, 0xbfb8aa3b, v104
	v_mul_f32_e32 v105, 0xbfb8aa3b, v105
	v_mul_f32_e32 v106, 0xbfb8aa3b, v106
	v_mul_f32_e32 v107, 0xbfb8aa3b, v107
	v_exp_f32_e32 v104, v104
	v_exp_f32_e32 v105, v105
	v_exp_f32_e32 v106, v106
	v_exp_f32_e32 v107, v107
	s_nop 0
	v_add_f32_e32 v104, 1.0, v104
	v_add_f32_e32 v105, 1.0, v105
	v_add_f32_e32 v106, 1.0, v106
	v_add_f32_e32 v107, 1.0, v107
	v_rcp_f32_e32 v104, v104
	v_rcp_f32_e32 v105, v105
	v_rcp_f32_e32 v106, v106
	v_rcp_f32_e32 v107, v107
	s_nop 0
	v_mul_f32_e32 v104, 0x3f1b4598, v104
	v_mul_f32_e32 v105, 0x3f1b4598, v105
	v_mul_f32_e32 v106, 0x3f1b4598, v106
	v_mul_f32_e32 v107, 0x3f1b4598, v107
	v_cvt_pk_bf16_f32 v148, v104, v105
	v_cvt_pk_bf16_f32 v149, v106, v107
	ds_write_b64 v236, v[148:149] offset:13888
	v_add_f32_e32 v108, v108, v204
	v_add_f32_e32 v109, v109, v205
	v_add_f32_e32 v110, v110, v206
	v_add_f32_e32 v111, v111, v207
	v_mul_f32_e32 v108, 0xbfb8aa3b, v108
	v_mul_f32_e32 v109, 0xbfb8aa3b, v109
	v_mul_f32_e32 v110, 0xbfb8aa3b, v110
	v_mul_f32_e32 v111, 0xbfb8aa3b, v111
	v_exp_f32_e32 v108, v108
	v_exp_f32_e32 v109, v109
	v_exp_f32_e32 v110, v110
	v_exp_f32_e32 v111, v111
	s_nop 0
	v_add_f32_e32 v108, 1.0, v108
	v_add_f32_e32 v109, 1.0, v109
	v_add_f32_e32 v110, 1.0, v110
	v_add_f32_e32 v111, 1.0, v111
	v_rcp_f32_e32 v108, v108
	v_rcp_f32_e32 v109, v109
	v_rcp_f32_e32 v110, v110
	v_rcp_f32_e32 v111, v111
	s_nop 0
	v_mul_f32_e32 v108, 0x3f1b4598, v108
	v_mul_f32_e32 v109, 0x3f1b4598, v109
	v_mul_f32_e32 v110, 0x3f1b4598, v110
	v_mul_f32_e32 v111, 0x3f1b4598, v111
	v_cvt_pk_bf16_f32 v150, v108, v109
	v_cvt_pk_bf16_f32 v151, v110, v111
	ds_write_b64 v236, v[150:151] offset:13920
	v_add_f32_e32 v112, v112, v192
	v_add_f32_e32 v113, v113, v193
	v_add_f32_e32 v114, v114, v194
	v_add_f32_e32 v115, v115, v195
	v_mul_f32_e32 v112, 0xbfb8aa3b, v112
	v_mul_f32_e32 v113, 0xbfb8aa3b, v113
	v_mul_f32_e32 v114, 0xbfb8aa3b, v114
	v_mul_f32_e32 v115, 0xbfb8aa3b, v115
	v_exp_f32_e32 v112, v112
	v_exp_f32_e32 v113, v113
	v_exp_f32_e32 v114, v114
	v_exp_f32_e32 v115, v115
	s_nop 0
	v_add_f32_e32 v112, 1.0, v112
	v_add_f32_e32 v113, 1.0, v113
	v_add_f32_e32 v114, 1.0, v114
	v_add_f32_e32 v115, 1.0, v115
	v_rcp_f32_e32 v112, v112
	v_rcp_f32_e32 v113, v113
	v_rcp_f32_e32 v114, v114
	v_rcp_f32_e32 v115, v115
	s_nop 0
	v_mul_f32_e32 v112, 0x3f1b4598, v112
	v_mul_f32_e32 v113, 0x3f1b4598, v113
	v_mul_f32_e32 v114, 0x3f1b4598, v114
	v_mul_f32_e32 v115, 0x3f1b4598, v115
	v_cvt_pk_bf16_f32 v152, v112, v113
	v_cvt_pk_bf16_f32 v153, v114, v115
	ds_write_b64 v236, v[152:153] offset:16128
	v_add_f32_e32 v116, v116, v196
	v_add_f32_e32 v117, v117, v197
	v_add_f32_e32 v118, v118, v198
	v_add_f32_e32 v119, v119, v199
	v_mul_f32_e32 v116, 0xbfb8aa3b, v116
	v_mul_f32_e32 v117, 0xbfb8aa3b, v117
	v_mul_f32_e32 v118, 0xbfb8aa3b, v118
	v_mul_f32_e32 v119, 0xbfb8aa3b, v119
	v_exp_f32_e32 v116, v116
	v_exp_f32_e32 v117, v117
	v_exp_f32_e32 v118, v118
	v_exp_f32_e32 v119, v119
	s_nop 0
	v_add_f32_e32 v116, 1.0, v116
	v_add_f32_e32 v117, 1.0, v117
	v_add_f32_e32 v118, 1.0, v118
	v_add_f32_e32 v119, 1.0, v119
	v_rcp_f32_e32 v116, v116
	v_rcp_f32_e32 v117, v117
	v_rcp_f32_e32 v118, v118
	v_rcp_f32_e32 v119, v119
	s_nop 0
	v_mul_f32_e32 v116, 0x3f1b4598, v116
	v_mul_f32_e32 v117, 0x3f1b4598, v117
	v_mul_f32_e32 v118, 0x3f1b4598, v118
	v_mul_f32_e32 v119, 0x3f1b4598, v119
	v_cvt_pk_bf16_f32 v154, v116, v117
	v_cvt_pk_bf16_f32 v155, v118, v119
	ds_write_b64 v236, v[154:155] offset:16160
	v_add_f32_e32 v120, v120, v200
	v_add_f32_e32 v121, v121, v201
	v_add_f32_e32 v122, v122, v202
	v_add_f32_e32 v123, v123, v203
	v_mul_f32_e32 v120, 0xbfb8aa3b, v120
	v_mul_f32_e32 v121, 0xbfb8aa3b, v121
	v_mul_f32_e32 v122, 0xbfb8aa3b, v122
	v_mul_f32_e32 v123, 0xbfb8aa3b, v123
	v_exp_f32_e32 v120, v120
	v_exp_f32_e32 v121, v121
	v_exp_f32_e32 v122, v122
	v_exp_f32_e32 v123, v123
	s_nop 0
	v_add_f32_e32 v120, 1.0, v120
	v_add_f32_e32 v121, 1.0, v121
	v_add_f32_e32 v122, 1.0, v122
	v_add_f32_e32 v123, 1.0, v123
	v_rcp_f32_e32 v120, v120
	v_rcp_f32_e32 v121, v121
	v_rcp_f32_e32 v122, v122
	v_rcp_f32_e32 v123, v123
	s_nop 0
	v_mul_f32_e32 v120, 0x3f1b4598, v120
	v_mul_f32_e32 v121, 0x3f1b4598, v121
	v_mul_f32_e32 v122, 0x3f1b4598, v122
	v_mul_f32_e32 v123, 0x3f1b4598, v123
	v_cvt_pk_bf16_f32 v156, v120, v121
	v_cvt_pk_bf16_f32 v157, v122, v123
	ds_write_b64 v236, v[156:157] offset:16192
	v_add_f32_e32 v124, v124, v204
	v_add_f32_e32 v125, v125, v205
	v_add_f32_e32 v126, v126, v206
	v_add_f32_e32 v127, v127, v207
	v_mul_f32_e32 v124, 0xbfb8aa3b, v124
	v_mul_f32_e32 v125, 0xbfb8aa3b, v125
	v_mul_f32_e32 v126, 0xbfb8aa3b, v126
	v_mul_f32_e32 v127, 0xbfb8aa3b, v127
	v_exp_f32_e32 v124, v124
	v_exp_f32_e32 v125, v125
	v_exp_f32_e32 v126, v126
	v_exp_f32_e32 v127, v127
	s_nop 0
	v_add_f32_e32 v124, 1.0, v124
	v_add_f32_e32 v125, 1.0, v125
	v_add_f32_e32 v126, 1.0, v126
	v_add_f32_e32 v127, 1.0, v127
	v_rcp_f32_e32 v124, v124
	v_rcp_f32_e32 v125, v125
	v_rcp_f32_e32 v126, v126
	v_rcp_f32_e32 v127, v127
	s_nop 0
	v_mul_f32_e32 v124, 0x3f1b4598, v124
	v_mul_f32_e32 v125, 0x3f1b4598, v125
	v_mul_f32_e32 v126, 0x3f1b4598, v126
	v_mul_f32_e32 v127, 0x3f1b4598, v127
	v_cvt_pk_bf16_f32 v158, v124, v125
	v_cvt_pk_bf16_f32 v159, v126, v127
	ds_write_b64 v236, v[158:159] offset:16224
	s_waitcnt lgkmcnt(0)
; DI unsigned pack2(float lo, float hi) { const f32x2c v = {lo, hi}; return __builtin_bit_cast(unsigned, __builtin_convertvector(v, bf16x2c)); }
; template <class Epi>
; DI void gemm_tile(char* smem, const bf16_t* __restrict__ A0, int lda0, int ksplit, const bf16_t* __restrict__ A1, int lda1,
;                   const bf16_t* __restrict__ Bt, int K, int row0, int col0, const Epi& epi, int tid) {
;     ...
; #pragma unroll
;   for (int m = 0; m < 8; ++m)
; #pragma unroll
;     for (int n = 0; n < 4; ++n) epi(row0 + wr * 128 + m * 16 + fr, col0 + wc * 64 + n * 16 + fq * 4, acc[m][n]);
; }
; DI void st_bf16x4(bf16_t* o, f32x4 v) { u32x2 q; q.x = pack2(v[0], v[1]); q.y = pack2(v[2], v[3]); *(u32x2*)o = q; }
	ds_read_b128 v[128:131], v237
	ds_read_b128 v[132:135], v237 offset:1152
	ds_read_b128 v[136:139], v237 offset:2304
	ds_read_b128 v[140:143], v237 offset:3456
	ds_read_b128 v[144:147], v237 offset:4608
	ds_read_b128 v[148:151], v237 offset:5760
	ds_read_b128 v[152:155], v237 offset:6912
	ds_read_b128 v[156:159], v237 offset:8064
	ds_read_b128 v[160:163], v237 offset:9216
	ds_read_b128 v[164:167], v237 offset:10368
	ds_read_b128 v[168:171], v237 offset:11520
	ds_read_b128 v[172:175], v237 offset:12672
	ds_read_b128 v[176:179], v237 offset:13824
	ds_read_b128 v[180:183], v237 offset:14976
	ds_read_b128 v[184:187], v237 offset:16128
	ds_read_b128 v[188:191], v237 offset:17280
	s_waitcnt lgkmcnt(15)
	global_store_dwordx4 v238, v[128:131], s[4:5] nt
	s_add_u32 s4, s4, 0x2000
	s_addc_u32 s5, s5, 0
	s_waitcnt lgkmcnt(14)
	global_store_dwordx4 v238, v[132:135], s[4:5] nt
	s_add_u32 s4, s4, 0x2000
	s_addc_u32 s5, s5, 0
	s_waitcnt lgkmcnt(13)
	global_store_dwordx4 v238, v[136:139], s[4:5] nt
	s_add_u32 s4, s4, 0x2000
	s_addc_u32 s5, s5, 0
	s_waitcnt lgkmcnt(12)
	global_store_dwordx4 v238, v[140:143], s[4:5] nt
	s_add_u32 s4, s4, 0x2000
	s_addc_u32 s5, s5, 0
	s_waitcnt lgkmcnt(11)
	global_store_dwordx4 v238, v[144:147], s[4:5] nt
	s_add_u32 s4, s4, 0x2000
	s_addc_u32 s5, s5, 0
	s_waitcnt lgkmcnt(10)
	global_store_dwordx4 v238, v[148:151], s[4:5] nt
	s_add_u32 s4, s4, 0x2000
	s_addc_u32 s5, s5, 0
	s_waitcnt lgkmcnt(9)
	global_store_dwordx4 v238, v[152:155], s[4:5] nt
	s_add_u32 s4, s4, 0x2000
	s_addc_u32 s5, s5, 0
	s_waitcnt lgkmcnt(8)
	global_store_dwordx4 v238, v[156:159], s[4:5] nt
	s_add_u32 s4, s4, 0x2000
	s_addc_u32 s5, s5, 0
	s_waitcnt lgkmcnt(7)
	global_store_dwordx4 v238, v[160:163], s[4:5] nt
	s_add_u32 s4, s4, 0x2000
	s_addc_u32 s5, s5, 0
	s_waitcnt lgkmcnt(6)
	global_store_dwordx4 v238, v[164:167], s[4:5] nt
	s_add_u32 s4, s4, 0x2000
	s_addc_u32 s5, s5, 0
	s_waitcnt lgkmcnt(5)
	global_store_dwordx4 v238, v[168:171], s[4:5] nt
	s_add_u32 s4, s4, 0x2000
	s_addc_u32 s5, s5, 0
	s_waitcnt lgkmcnt(4)
	global_store_dwordx4 v238, v[172:175], s[4:5] nt
	s_add_u32 s4, s4, 0x2000
	s_addc_u32 s5, s5, 0
	s_waitcnt lgkmcnt(3)
	global_store_dwordx4 v238, v[176:179], s[4:5] nt
	s_add_u32 s4, s4, 0x2000
	s_addc_u32 s5, s5, 0
	s_waitcnt lgkmcnt(2)
	global_store_dwordx4 v238, v[180:183], s[4:5] nt
	s_add_u32 s4, s4, 0x2000
	s_addc_u32 s5, s5, 0
	s_waitcnt lgkmcnt(1)
	global_store_dwordx4 v238, v[184:187], s[4:5] nt
	s_add_u32 s4, s4, 0x2000
	s_addc_u32 s5, s5, 0
	s_waitcnt lgkmcnt(0)
	global_store_dwordx4 v238, v[188:191], s[4:5] nt
	s_nop 1
	s_add_u32 s15, s15, 64
	s_branch .Lg3b_tile

; DI unsigned pack2(float lo, float hi) { const f32x2c v = {lo, hi}; return __builtin_bit_cast(unsigned, __builtin_convertvector(v, bf16x2c)); }
; template <class Epi>
; DI void gemm_tile(char* smem, const bf16_t* __restrict__ A0, int lda0, int ksplit, const bf16_t* __restrict__ A1, int lda1,
;                   const bf16_t* __restrict__ Bt, int K, int row0, int col0, const Epi& epi, int tid) {
;     ...
; #pragma unroll
;   for (int m = 0; m < 8; ++m)
; #pragma unroll
;     for (int n = 0; n < 4; ++n) epi(row0 + wr * 128 + m * 16 + fr, col0 + wc * 64 + n * 16 + fq * 4, acc[m][n]);
; }
; DI void st_bf16x4(bf16_t* o, f32x4 v) { u32x2 q; q.x = pack2(v[0], v[1]); q.y = pack2(v[2], v[3]); *(u32x2*)o = q; }
.Lg3c_epi:
	s_nop 7
	s_nop 7
	s_mul_i32 s27, s29, 1024
	s_lshl_b32 s26, s28, 1
	s_add_u32 s27, s27, s26
	s_add_u32 s27, s27, 0xb800000
	s_add_u32 s4, s92, s27
	s_addc_u32 s5, s93, 0
	s_lshl_b32 s27, s28, 2
	s_add_u32 s27, s27, 0x0
	s_add_u32 s2, s6, s27
	s_addc_u32 s3, s7, 0
	global_load_dwordx4 v[192:195], v235, s[2:3] offset:0
	global_load_dwordx4 v[196:199], v235, s[2:3] offset:64
	global_load_dwordx4 v[200:203], v235, s[2:3] offset:128
	global_load_dwordx4 v[204:207], v235, s[2:3] offset:192
	s_waitcnt vmcnt(0)
	v_add_f32_e32 v0, v0, v192
	v_add_f32_e32 v1, v1, v193
	v_add_f32_e32 v2, v2, v194
	v_add_f32_e32 v3, v3, v195
	v_mul_f32_e32 v0, 0xbfb8aa3b, v0
	v_mul_f32_e32 v1, 0xbfb8aa3b, v1
	v_mul_f32_e32 v2, 0xbfb8aa3b, v2
	v_mul_f32_e32 v3, 0xbfb8aa3b, v3
	v_exp_f32_e32 v0, v0
	v_exp_f32_e32 v1, v1
	v_exp_f32_e32 v2, v2
	v_exp_f32_e32 v3, v3
	s_nop 0
	v_add_f32_e32 v0, 1.0, v0
	v_add_f32_e32 v1, 1.0, v1
	v_add_f32_e32 v2, 1.0, v2
	v_add_f32_e32 v3, 1.0, v3
	v_rcp_f32_e32 v0, v0
	v_rcp_f32_e32 v1, v1
	v_rcp_f32_e32 v2, v2
	v_rcp_f32_e32 v3, v3
	s_nop 0
	v_cvt_pk_bf16_f32 v128, v0, v1
	v_cvt_pk_bf16_f32 v129, v2, v3
	ds_write_b64 v236, v[128:129]
	v_add_f32_e32 v4, v4, v196
	v_add_f32_e32 v5, v5, v197
	v_add_f32_e32 v6, v6, v198
	v_add_f32_e32 v7, v7, v199
	v_mul_f32_e32 v4, 0xbfb8aa3b, v4
	v_mul_f32_e32 v5, 0xbfb8aa3b, v5
	v_mul_f32_e32 v6, 0xbfb8aa3b, v6
	v_mul_f32_e32 v7, 0xbfb8aa3b, v7
	v_exp_f32_e32 v4, v4
	v_exp_f32_e32 v5, v5
	v_exp_f32_e32 v6, v6
	v_exp_f32_e32 v7, v7
	s_nop 0
	v_add_f32_e32 v4, 1.0, v4
	v_add_f32_e32 v5, 1.0, v5
	v_add_f32_e32 v6, 1.0, v6
	v_add_f32_e32 v7, 1.0, v7
	v_rcp_f32_e32 v4, v4
	v_rcp_f32_e32 v5, v5
	v_rcp_f32_e32 v6, v6
	v_rcp_f32_e32 v7, v7
	s_nop 0
	v_cvt_pk_bf16_f32 v130, v4, v5
	v_cvt_pk_bf16_f32 v131, v6, v7
	ds_write_b64 v236, v[130:131] offset:32
	v_add_f32_e32 v8, v8, v200
	v_add_f32_e32 v9, v9, v201
	v_add_f32_e32 v10, v10, v202
	v_add_f32_e32 v11, v11, v203
	v_mul_f32_e32 v8, 0xbfb8aa3b, v8
	v_mul_f32_e32 v9, 0xbfb8aa3b, v9
	v_mul_f32_e32 v10, 0xbfb8aa3b, v10
	v_mul_f32_e32 v11, 0xbfb8aa3b, v11
	v_exp_f32_e32 v8, v8
	v_exp_f32_e32 v9, v9
	v_exp_f32_e32 v10, v10
	v_exp_f32_e32 v11, v11
	s_nop 0
	v_add_f32_e32 v8, 1.0, v8
	v_add_f32_e32 v9, 1.0, v9
	v_add_f32_e32 v10, 1.0, v10
	v_add_f32_e32 v11, 1.0, v11
	v_rcp_f32_e32 v8, v8
	v_rcp_f32_e32 v9, v9
	v_rcp_f32_e32 v10, v10
	v_rcp_f32_e32 v11, v11
	s_nop 0
	v_cvt_pk_bf16_f32 v132, v8, v9
	v_cvt_pk_bf16_f32 v133, v10, v11
	ds_write_b64 v236, v[132:133] offset:64
	v_add_f32_e32 v12, v12, v204
	v_add_f32_e32 v13, v13, v205
	v_add_f32_e32 v14, v14, v206
	v_add_f32_e32 v15, v15, v207
	v_mul_f32_e32 v12, 0xbfb8aa3b, v12
	v_mul_f32_e32 v13, 0xbfb8aa3b, v13
	v_mul_f32_e32 v14, 0xbfb8aa3b, v14
	v_mul_f32_e32 v15, 0xbfb8aa3b, v15
	v_exp_f32_e32 v12, v12
	v_exp_f32_e32 v13, v13
	v_exp_f32_e32 v14, v14
	v_exp_f32_e32 v15, v15
	s_nop 0
	v_add_f32_e32 v12, 1.0, v12
	v_add_f32_e32 v13, 1.0, v13
	v_add_f32_e32 v14, 1.0, v14
	v_add_f32_e32 v15, 1.0, v15
	v_rcp_f32_e32 v12, v12
	v_rcp_f32_e32 v13, v13
	v_rcp_f32_e32 v14, v14
	v_rcp_f32_e32 v15, v15
	s_nop 0
	v_cvt_pk_bf16_f32 v134, v12, v13
	v_cvt_pk_bf16_f32 v135, v14, v15
	ds_write_b64 v236, v[134:135] offset:96
	v_add_f32_e32 v16, v16, v192
	v_add_f32_e32 v17, v17, v193
	v_add_f32_e32 v18, v18, v194
	v_add_f32_e32 v19, v19, v195
	v_mul_f32_e32 v16, 0xbfb8aa3b, v16
	v_mul_f32_e32 v17, 0xbfb8aa3b, v17
	v_mul_f32_e32 v18, 0xbfb8aa3b, v18
	v_mul_f32_e32 v19, 0xbfb8aa3b, v19
	v_exp_f32_e32 v16, v16
	v_exp_f32_e32 v17, v17
	v_exp_f32_e32 v18, v18
	v_exp_f32_e32 v19, v19
	s_nop 0
	v_add_f32_e32 v16, 1.0, v16
	v_add_f32_e32 v17, 1.0, v17
	v_add_f32_e32 v18, 1.0, v18
	v_add_f32_e32 v19, 1.0, v19
	v_rcp_f32_e32 v16, v16
	v_rcp_f32_e32 v17, v17
	v_rcp_f32_e32 v18, v18
	v_rcp_f32_e32 v19, v19
	s_nop 0
	v_cvt_pk_bf16_f32 v136, v16, v17
	v_cvt_pk_bf16_f32 v137, v18, v19
	ds_write_b64 v236, v[136:137] offset:2304
	v_add_f32_e32 v20, v20, v196
	v_add_f32_e32 v21, v21, v197
	v_add_f32_e32 v22, v22, v198
	v_add_f32_e32 v23, v23, v199
	v_mul_f32_e32 v20, 0xbfb8aa3b, v20
	v_mul_f32_e32 v21, 0xbfb8aa3b, v21
	v_mul_f32_e32 v22, 0xbfb8aa3b, v22
	v_mul_f32_e32 v23, 0xbfb8aa3b, v23
	v_exp_f32_e32 v20, v20
	v_exp_f32_e32 v21, v21
	v_exp_f32_e32 v22, v22
	v_exp_f32_e32 v23, v23
	s_nop 0
	v_add_f32_e32 v20, 1.0, v20
	v_add_f32_e32 v21, 1.0, v21
	v_add_f32_e32 v22, 1.0, v22
	v_add_f32_e32 v23, 1.0, v23
	v_rcp_f32_e32 v20, v20
	v_rcp_f32_e32 v21, v21
	v_rcp_f32_e32 v22, v22
	v_rcp_f32_e32 v23, v23
	s_nop 0
	v_cvt_pk_bf16_f32 v138, v20, v21
	v_cvt_pk_bf16_f32 v139, v22, v23
	ds_write_b64 v236, v[138:139] offset:2336
	v_add_f32_e32 v24, v24, v200
	v_add_f32_e32 v25, v25, v201
	v_add_f32_e32 v26, v26, v202
	v_add_f32_e32 v27, v27, v203
	v_mul_f32_e32 v24, 0xbfb8aa3b, v24
	v_mul_f32_e32 v25, 0xbfb8aa3b, v25
	v_mul_f32_e32 v26, 0xbfb8aa3b, v26
	v_mul_f32_e32 v27, 0xbfb8aa3b, v27
	v_exp_f32_e32 v24, v24
	v_exp_f32_e32 v25, v25
	v_exp_f32_e32 v26, v26
	v_exp_f32_e32 v27, v27
	s_nop 0
	v_add_f32_e32 v24, 1.0, v24
	v_add_f32_e32 v25, 1.0, v25
	v_add_f32_e32 v26, 1.0, v26
	v_add_f32_e32 v27, 1.0, v27
	v_rcp_f32_e32 v24, v24
	v_rcp_f32_e32 v25, v25
	v_rcp_f32_e32 v26, v26
	v_rcp_f32_e32 v27, v27
	s_nop 0
	v_cvt_pk_bf16_f32 v140, v24, v25
	v_cvt_pk_bf16_f32 v141, v26, v27
	ds_write_b64 v236, v[140:141] offset:2368
	v_add_f32_e32 v28, v28, v204
	v_add_f32_e32 v29, v29, v205
	v_add_f32_e32 v30, v30, v206
	v_add_f32_e32 v31, v31, v207
	v_mul_f32_e32 v28, 0xbfb8aa3b, v28
	v_mul_f32_e32 v29, 0xbfb8aa3b, v29
	v_mul_f32_e32 v30, 0xbfb8aa3b, v30
	v_mul_f32_e32 v31, 0xbfb8aa3b, v31
	v_exp_f32_e32 v28, v28
	v_exp_f32_e32 v29, v29
	v_exp_f32_e32 v30, v30
; DI unsigned pack2(float lo, float hi) { const f32x2c v = {lo, hi}; return __builtin_bit_cast(unsigned, __builtin_convertvector(v, bf16x2c)); }
; template <class Epi>
; DI void gemm_tile(char* smem, const bf16_t* __restrict__ A0, int lda0, int ksplit, const bf16_t* __restrict__ A1, int lda1,
;                   const bf16_t* __restrict__ Bt, int K, int row0, int col0, const Epi& epi, int tid) {
;     ...
; #pragma unroll
;   for (int m = 0; m < 8; ++m)
; #pragma unroll
;     for (int n = 0; n < 4; ++n) epi(row0 + wr * 128 + m * 16 + fr, col0 + wc * 64 + n * 16 + fq * 4, acc[m][n]);
; }
; DI void st_bf16x4(bf16_t* o, f32x4 v) { u32x2 q; q.x = pack2(v[0], v[1]); q.y = pack2(v[2], v[3]); *(u32x2*)o = q; }
	v_exp_f32_e32 v31, v31
	s_nop 0
	v_add_f32_e32 v28, 1.0, v28
	v_add_f32_e32 v29, 1.0, v29
	v_add_f32_e32 v30, 1.0, v30
	v_add_f32_e32 v31, 1.0, v31
	v_rcp_f32_e32 v28, v28
	v_rcp_f32_e32 v29, v29
	v_rcp_f32_e32 v30, v30
	v_rcp_f32_e32 v31, v31
	s_nop 0
	v_cvt_pk_bf16_f32 v142, v28, v29
	v_cvt_pk_bf16_f32 v143, v30, v31
	ds_write_b64 v236, v[142:143] offset:2400
	v_add_f32_e32 v32, v32, v192
	v_add_f32_e32 v33, v33, v193
	v_add_f32_e32 v34, v34, v194
	v_add_f32_e32 v35, v35, v195
	v_mul_f32_e32 v32, 0xbfb8aa3b, v32
	v_mul_f32_e32 v33, 0xbfb8aa3b, v33
	v_mul_f32_e32 v34, 0xbfb8aa3b, v34
	v_mul_f32_e32 v35, 0xbfb8aa3b, v35
	v_exp_f32_e32 v32, v32
	v_exp_f32_e32 v33, v33
	v_exp_f32_e32 v34, v34
	v_exp_f32_e32 v35, v35
	s_nop 0
	v_add_f32_e32 v32, 1.0, v32
	v_add_f32_e32 v33, 1.0, v33
	v_add_f32_e32 v34, 1.0, v34
	v_add_f32_e32 v35, 1.0, v35
	v_rcp_f32_e32 v32, v32
	v_rcp_f32_e32 v33, v33
	v_rcp_f32_e32 v34, v34
	v_rcp_f32_e32 v35, v35
	s_nop 0
	v_cvt_pk_bf16_f32 v144, v32, v33
	v_cvt_pk_bf16_f32 v145, v34, v35
	ds_write_b64 v236, v[144:145] offset:4608
	v_add_f32_e32 v36, v36, v196
	v_add_f32_e32 v37, v37, v197
	v_add_f32_e32 v38, v38, v198
	v_add_f32_e32 v39, v39, v199
	v_mul_f32_e32 v36, 0xbfb8aa3b, v36
	v_mul_f32_e32 v37, 0xbfb8aa3b, v37
	v_mul_f32_e32 v38, 0xbfb8aa3b, v38
	v_mul_f32_e32 v39, 0xbfb8aa3b, v39
	v_exp_f32_e32 v36, v36
	v_exp_f32_e32 v37, v37
	v_exp_f32_e32 v38, v38
	v_exp_f32_e32 v39, v39
	s_nop 0
	v_add_f32_e32 v36, 1.0, v36
	v_add_f32_e32 v37, 1.0, v37
	v_add_f32_e32 v38, 1.0, v38
	v_add_f32_e32 v39, 1.0, v39
	v_rcp_f32_e32 v36, v36
	v_rcp_f32_e32 v37, v37
	v_rcp_f32_e32 v38, v38
	v_rcp_f32_e32 v39, v39
	s_nop 0
	v_cvt_pk_bf16_f32 v146, v36, v37
	v_cvt_pk_bf16_f32 v147, v38, v39
	ds_write_b64 v236, v[146:147] offset:4640
	v_add_f32_e32 v40, v40, v200
	v_add_f32_e32 v41, v41, v201
	v_add_f32_e32 v42, v42, v202
	v_add_f32_e32 v43, v43, v203
	v_mul_f32_e32 v40, 0xbfb8aa3b, v40
	v_mul_f32_e32 v41, 0xbfb8aa3b, v41
	v_mul_f32_e32 v42, 0xbfb8aa3b, v42
	v_mul_f32_e32 v43, 0xbfb8aa3b, v43
	v_exp_f32_e32 v40, v40
	v_exp_f32_e32 v41, v41
	v_exp_f32_e32 v42, v42
	v_exp_f32_e32 v43, v43
	s_nop 0
	v_add_f32_e32 v40, 1.0, v40
	v_add_f32_e32 v41, 1.0, v41
	v_add_f32_e32 v42, 1.0, v42
	v_add_f32_e32 v43, 1.0, v43
	v_rcp_f32_e32 v40, v40
	v_rcp_f32_e32 v41, v41
	v_rcp_f32_e32 v42, v42
	v_rcp_f32_e32 v43, v43
	s_nop 0
	v_cvt_pk_bf16_f32 v148, v40, v41
	v_cvt_pk_bf16_f32 v149, v42, v43
	ds_write_b64 v236, v[148:149] offset:4672
	v_add_f32_e32 v44, v44, v204
	v_add_f32_e32 v45, v45, v205
	v_add_f32_e32 v46, v46, v206
	v_add_f32_e32 v47, v47, v207
	v_mul_f32_e32 v44, 0xbfb8aa3b, v44
	v_mul_f32_e32 v45, 0xbfb8aa3b, v45
	v_mul_f32_e32 v46, 0xbfb8aa3b, v46
	v_mul_f32_e32 v47, 0xbfb8aa3b, v47
	v_exp_f32_e32 v44, v44
	v_exp_f32_e32 v45, v45
	v_exp_f32_e32 v46, v46
	v_exp_f32_e32 v47, v47
	s_nop 0
	v_add_f32_e32 v44, 1.0, v44
	v_add_f32_e32 v45, 1.0, v45
	v_add_f32_e32 v46, 1.0, v46
	v_add_f32_e32 v47, 1.0, v47
	v_rcp_f32_e32 v44, v44
	v_rcp_f32_e32 v45, v45
	v_rcp_f32_e32 v46, v46
	v_rcp_f32_e32 v47, v47
	s_nop 0
	v_cvt_pk_bf16_f32 v150, v44, v45
	v_cvt_pk_bf16_f32 v151, v46, v47
	ds_write_b64 v236, v[150:151] offset:4704
	v_add_f32_e32 v48, v48, v192
	v_add_f32_e32 v49, v49, v193
	v_add_f32_e32 v50, v50, v194
	v_add_f32_e32 v51, v51, v195
	v_mul_f32_e32 v48, 0xbfb8aa3b, v48
	v_mul_f32_e32 v49, 0xbfb8aa3b, v49
	v_mul_f32_e32 v50, 0xbfb8aa3b, v50
	v_mul_f32_e32 v51, 0xbfb8aa3b, v51
	v_exp_f32_e32 v48, v48
	v_exp_f32_e32 v49, v49
	v_exp_f32_e32 v50, v50
	v_exp_f32_e32 v51, v51
	s_nop 0
	v_add_f32_e32 v48, 1.0, v48
	v_add_f32_e32 v49, 1.0, v49
	v_add_f32_e32 v50, 1.0, v50
	v_add_f32_e32 v51, 1.0, v51
	v_rcp_f32_e32 v48, v48
	v_rcp_f32_e32 v49, v49
	v_rcp_f32_e32 v50, v50
	v_rcp_f32_e32 v51, v51
	s_nop 0
	v_cvt_pk_bf16_f32 v152, v48, v49
	v_cvt_pk_bf16_f32 v153, v50, v51
	ds_write_b64 v236, v[152:153] offset:6912
	v_add_f32_e32 v52, v52, v196
	v_add_f32_e32 v53, v53, v197
	v_add_f32_e32 v54, v54, v198
	v_add_f32_e32 v55, v55, v199
	v_mul_f32_e32 v52, 0xbfb8aa3b, v52
	v_mul_f32_e32 v53, 0xbfb8aa3b, v53
	v_mul_f32_e32 v54, 0xbfb8aa3b, v54
	v_mul_f32_e32 v55, 0xbfb8aa3b, v55
	v_exp_f32_e32 v52, v52
	v_exp_f32_e32 v53, v53
	v_exp_f32_e32 v54, v54
	v_exp_f32_e32 v55, v55
	s_nop 0
	v_add_f32_e32 v52, 1.0, v52
	v_add_f32_e32 v53, 1.0, v53
	v_add_f32_e32 v54, 1.0, v54
	v_add_f32_e32 v55, 1.0, v55
	v_rcp_f32_e32 v52, v52
	v_rcp_f32_e32 v53, v53
	v_rcp_f32_e32 v54, v54
	v_rcp_f32_e32 v55, v55
	s_nop 0
	v_cvt_pk_bf16_f32 v154, v52, v53
	v_cvt_pk_bf16_f32 v155, v54, v55
	ds_write_b64 v236, v[154:155] offset:6944
	v_add_f32_e32 v56, v56, v200
	v_add_f32_e32 v57, v57, v201
	v_add_f32_e32 v58, v58, v202
	v_add_f32_e32 v59, v59, v203
	v_mul_f32_e32 v56, 0xbfb8aa3b, v56
	v_mul_f32_e32 v57, 0xbfb8aa3b, v57
	v_mul_f32_e32 v58, 0xbfb8aa3b, v58
	v_mul_f32_e32 v59, 0xbfb8aa3b, v59
	v_exp_f32_e32 v56, v56
	v_exp_f32_e32 v57, v57
	v_exp_f32_e32 v58, v58
	v_exp_f32_e32 v59, v59
	s_nop 0
	v_add_f32_e32 v56, 1.0, v56
	v_add_f32_e32 v57, 1.0, v57
	v_add_f32_e32 v58, 1.0, v58
	v_add_f32_e32 v59, 1.0, v59
	v_rcp_f32_e32 v56, v56
	v_rcp_f32_e32 v57, v57
	v_rcp_f32_e32 v58, v58
	v_rcp_f32_e32 v59, v59
	s_nop 0
	v_cvt_pk_bf16_f32 v156, v56, v57
	v_cvt_pk_bf16_f32 v157, v58, v59
	ds_write_b64 v236, v[156:157] offset:6976
	v_add_f32_e32 v60, v60, v204
	v_add_f32_e32 v61, v61, v205
	v_add_f32_e32 v62, v62, v206
	v_add_f32_e32 v63, v63, v207
	v_mul_f32_e32 v60, 0xbfb8aa3b, v60
	v_mul_f32_e32 v61, 0xbfb8aa3b, v61
	v_mul_f32_e32 v62, 0xbfb8aa3b, v62
	v_mul_f32_e32 v63, 0xbfb8aa3b, v63
	v_exp_f32_e32 v60, v60
	v_exp_f32_e32 v61, v61
	v_exp_f32_e32 v62, v62
	v_exp_f32_e32 v63, v63
	s_nop 0
; DI unsigned pack2(float lo, float hi) { const f32x2c v = {lo, hi}; return __builtin_bit_cast(unsigned, __builtin_convertvector(v, bf16x2c)); }
; template <class Epi>
; DI void gemm_tile(char* smem, const bf16_t* __restrict__ A0, int lda0, int ksplit, const bf16_t* __restrict__ A1, int lda1,
;                   const bf16_t* __restrict__ Bt, int K, int row0, int col0, const Epi& epi, int tid) {
;     ...
; #pragma unroll
;   for (int m = 0; m < 8; ++m)
; #pragma unroll
;     for (int n = 0; n < 4; ++n) epi(row0 + wr * 128 + m * 16 + fr, col0 + wc * 64 + n * 16 + fq * 4, acc[m][n]);
; }
; DI void st_bf16x4(bf16_t* o, f32x4 v) { u32x2 q; q.x = pack2(v[0], v[1]); q.y = pack2(v[2], v[3]); *(u32x2*)o = q; }
	v_add_f32_e32 v60, 1.0, v60
	v_add_f32_e32 v61, 1.0, v61
	v_add_f32_e32 v62, 1.0, v62
	v_add_f32_e32 v63, 1.0, v63
	v_rcp_f32_e32 v60, v60
	v_rcp_f32_e32 v61, v61
	v_rcp_f32_e32 v62, v62
	v_rcp_f32_e32 v63, v63
	s_nop 0
	v_cvt_pk_bf16_f32 v158, v60, v61
	v_cvt_pk_bf16_f32 v159, v62, v63
	ds_write_b64 v236, v[158:159] offset:7008
	v_add_f32_e32 v64, v64, v192
	v_add_f32_e32 v65, v65, v193
	v_add_f32_e32 v66, v66, v194
	v_add_f32_e32 v67, v67, v195
	v_mul_f32_e32 v64, 0xbfb8aa3b, v64
	v_mul_f32_e32 v65, 0xbfb8aa3b, v65
	v_mul_f32_e32 v66, 0xbfb8aa3b, v66
	v_mul_f32_e32 v67, 0xbfb8aa3b, v67
	v_exp_f32_e32 v64, v64
	v_exp_f32_e32 v65, v65
	v_exp_f32_e32 v66, v66
	v_exp_f32_e32 v67, v67
	s_nop 0
	v_add_f32_e32 v64, 1.0, v64
	v_add_f32_e32 v65, 1.0, v65
	v_add_f32_e32 v66, 1.0, v66
	v_add_f32_e32 v67, 1.0, v67
	v_rcp_f32_e32 v64, v64
	v_rcp_f32_e32 v65, v65
	v_rcp_f32_e32 v66, v66
	v_rcp_f32_e32 v67, v67
	s_nop 0
	v_cvt_pk_bf16_f32 v128, v64, v65
	v_cvt_pk_bf16_f32 v129, v66, v67
	ds_write_b64 v236, v[128:129] offset:9216
	v_add_f32_e32 v68, v68, v196
	v_add_f32_e32 v69, v69, v197
	v_add_f32_e32 v70, v70, v198
	v_add_f32_e32 v71, v71, v199
	v_mul_f32_e32 v68, 0xbfb8aa3b, v68
	v_mul_f32_e32 v69, 0xbfb8aa3b, v69
	v_mul_f32_e32 v70, 0xbfb8aa3b, v70
	v_mul_f32_e32 v71, 0xbfb8aa3b, v71
	v_exp_f32_e32 v68, v68
	v_exp_f32_e32 v69, v69
	v_exp_f32_e32 v70, v70
	v_exp_f32_e32 v71, v71
	s_nop 0
	v_add_f32_e32 v68, 1.0, v68
	v_add_f32_e32 v69, 1.0, v69
	v_add_f32_e32 v70, 1.0, v70
	v_add_f32_e32 v71, 1.0, v71
	v_rcp_f32_e32 v68, v68
	v_rcp_f32_e32 v69, v69
	v_rcp_f32_e32 v70, v70
	v_rcp_f32_e32 v71, v71
	s_nop 0
	v_cvt_pk_bf16_f32 v130, v68, v69
	v_cvt_pk_bf16_f32 v131, v70, v71
	ds_write_b64 v236, v[130:131] offset:9248
	v_add_f32_e32 v72, v72, v200
	v_add_f32_e32 v73, v73, v201
	v_add_f32_e32 v74, v74, v202
	v_add_f32_e32 v75, v75, v203
	v_mul_f32_e32 v72, 0xbfb8aa3b, v72
	v_mul_f32_e32 v73, 0xbfb8aa3b, v73
	v_mul_f32_e32 v74, 0xbfb8aa3b, v74
	v_mul_f32_e32 v75, 0xbfb8aa3b, v75
	v_exp_f32_e32 v72, v72
	v_exp_f32_e32 v73, v73
	v_exp_f32_e32 v74, v74
	v_exp_f32_e32 v75, v75
	s_nop 0
	v_add_f32_e32 v72, 1.0, v72
	v_add_f32_e32 v73, 1.0, v73
	v_add_f32_e32 v74, 1.0, v74
	v_add_f32_e32 v75, 1.0, v75
	v_rcp_f32_e32 v72, v72
	v_rcp_f32_e32 v73, v73
	v_rcp_f32_e32 v74, v74
	v_rcp_f32_e32 v75, v75
	s_nop 0
	v_cvt_pk_bf16_f32 v132, v72, v73
	v_cvt_pk_bf16_f32 v133, v74, v75
	ds_write_b64 v236, v[132:133] offset:9280
	v_add_f32_e32 v76, v76, v204
	v_add_f32_e32 v77, v77, v205
	v_add_f32_e32 v78, v78, v206
	v_add_f32_e32 v79, v79, v207
	v_mul_f32_e32 v76, 0xbfb8aa3b, v76
	v_mul_f32_e32 v77, 0xbfb8aa3b, v77
	v_mul_f32_e32 v78, 0xbfb8aa3b, v78
	v_mul_f32_e32 v79, 0xbfb8aa3b, v79
	v_exp_f32_e32 v76, v76
	v_exp_f32_e32 v77, v77
	v_exp_f32_e32 v78, v78
	v_exp_f32_e32 v79, v79
	s_nop 0
	v_add_f32_e32 v76, 1.0, v76
	v_add_f32_e32 v77, 1.0, v77
	v_add_f32_e32 v78, 1.0, v78
	v_add_f32_e32 v79, 1.0, v79
	v_rcp_f32_e32 v76, v76
	v_rcp_f32_e32 v77, v77
	v_rcp_f32_e32 v78, v78
	v_rcp_f32_e32 v79, v79
	s_nop 0
	v_cvt_pk_bf16_f32 v134, v76, v77
	v_cvt_pk_bf16_f32 v135, v78, v79
	ds_write_b64 v236, v[134:135] offset:9312
	v_add_f32_e32 v80, v80, v192
	v_add_f32_e32 v81, v81, v193
	v_add_f32_e32 v82, v82, v194
	v_add_f32_e32 v83, v83, v195
	v_mul_f32_e32 v80, 0xbfb8aa3b, v80
	v_mul_f32_e32 v81, 0xbfb8aa3b, v81
	v_mul_f32_e32 v82, 0xbfb8aa3b, v82
	v_mul_f32_e32 v83, 0xbfb8aa3b, v83
	v_exp_f32_e32 v80, v80
	v_exp_f32_e32 v81, v81
	v_exp_f32_e32 v82, v82
	v_exp_f32_e32 v83, v83
	s_nop 0
	v_add_f32_e32 v80, 1.0, v80
	v_add_f32_e32 v81, 1.0, v81
	v_add_f32_e32 v82, 1.0, v82
	v_add_f32_e32 v83, 1.0, v83
	v_rcp_f32_e32 v80, v80
	v_rcp_f32_e32 v81, v81
	v_rcp_f32_e32 v82, v82
	v_rcp_f32_e32 v83, v83
	s_nop 0
	v_cvt_pk_bf16_f32 v136, v80, v81
	v_cvt_pk_bf16_f32 v137, v82, v83
	ds_write_b64 v236, v[136:137] offset:11520
	v_add_f32_e32 v84, v84, v196
	v_add_f32_e32 v85, v85, v197
	v_add_f32_e32 v86, v86, v198
	v_add_f32_e32 v87, v87, v199
	v_mul_f32_e32 v84, 0xbfb8aa3b, v84
	v_mul_f32_e32 v85, 0xbfb8aa3b, v85
	v_mul_f32_e32 v86, 0xbfb8aa3b, v86
	v_mul_f32_e32 v87, 0xbfb8aa3b, v87
	v_exp_f32_e32 v84, v84
	v_exp_f32_e32 v85, v85
	v_exp_f32_e32 v86, v86
	v_exp_f32_e32 v87, v87
	s_nop 0
	v_add_f32_e32 v84, 1.0, v84
	v_add_f32_e32 v85, 1.0, v85
	v_add_f32_e32 v86, 1.0, v86
	v_add_f32_e32 v87, 1.0, v87
	v_rcp_f32_e32 v84, v84
	v_rcp_f32_e32 v85, v85
	v_rcp_f32_e32 v86, v86
	v_rcp_f32_e32 v87, v87
	s_nop 0
	v_cvt_pk_bf16_f32 v138, v84, v85
	v_cvt_pk_bf16_f32 v139, v86, v87
	ds_write_b64 v236, v[138:139] offset:11552
	v_add_f32_e32 v88, v88, v200
	v_add_f32_e32 v89, v89, v201
	v_add_f32_e32 v90, v90, v202
	v_add_f32_e32 v91, v91, v203
	v_mul_f32_e32 v88, 0xbfb8aa3b, v88
	v_mul_f32_e32 v89, 0xbfb8aa3b, v89
	v_mul_f32_e32 v90, 0xbfb8aa3b, v90
	v_mul_f32_e32 v91, 0xbfb8aa3b, v91
	v_exp_f32_e32 v88, v88
	v_exp_f32_e32 v89, v89
	v_exp_f32_e32 v90, v90
	v_exp_f32_e32 v91, v91
	s_nop 0
	v_add_f32_e32 v88, 1.0, v88
	v_add_f32_e32 v89, 1.0, v89
	v_add_f32_e32 v90, 1.0, v90
	v_add_f32_e32 v91, 1.0, v91
	v_rcp_f32_e32 v88, v88
	v_rcp_f32_e32 v89, v89
	v_rcp_f32_e32 v90, v90
	v_rcp_f32_e32 v91, v91
	s_nop 0
	v_cvt_pk_bf16_f32 v140, v88, v89
	v_cvt_pk_bf16_f32 v141, v90, v91
	ds_write_b64 v236, v[140:141] offset:11584
	v_add_f32_e32 v92, v92, v204
	v_add_f32_e32 v93, v93, v205
	v_add_f32_e32 v94, v94, v206
	v_add_f32_e32 v95, v95, v207
	v_mul_f32_e32 v92, 0xbfb8aa3b, v92
	v_mul_f32_e32 v93, 0xbfb8aa3b, v93
	v_mul_f32_e32 v94, 0xbfb8aa3b, v94
	v_mul_f32_e32 v95, 0xbfb8aa3b, v95
	v_exp_f32_e32 v92, v92
	v_exp_f32_e32 v93, v93
	v_exp_f32_e32 v94, v94
	v_exp_f32_e32 v95, v95
	s_nop 0
	v_add_f32_e32 v92, 1.0, v92
; DI unsigned pack2(float lo, float hi) { const f32x2c v = {lo, hi}; return __builtin_bit_cast(unsigned, __builtin_convertvector(v, bf16x2c)); }
; template <class Epi>
; DI void gemm_tile(char* smem, const bf16_t* __restrict__ A0, int lda0, int ksplit, const bf16_t* __restrict__ A1, int lda1,
;                   const bf16_t* __restrict__ Bt, int K, int row0, int col0, const Epi& epi, int tid) {
;     ...
; #pragma unroll
;   for (int m = 0; m < 8; ++m)
; #pragma unroll
;     for (int n = 0; n < 4; ++n) epi(row0 + wr * 128 + m * 16 + fr, col0 + wc * 64 + n * 16 + fq * 4, acc[m][n]);
; }
; DI void st_bf16x4(bf16_t* o, f32x4 v) { u32x2 q; q.x = pack2(v[0], v[1]); q.y = pack2(v[2], v[3]); *(u32x2*)o = q; }
	v_add_f32_e32 v93, 1.0, v93
	v_add_f32_e32 v94, 1.0, v94
	v_add_f32_e32 v95, 1.0, v95
	v_rcp_f32_e32 v92, v92
	v_rcp_f32_e32 v93, v93
	v_rcp_f32_e32 v94, v94
	v_rcp_f32_e32 v95, v95
	s_nop 0
	v_cvt_pk_bf16_f32 v142, v92, v93
	v_cvt_pk_bf16_f32 v143, v94, v95
	ds_write_b64 v236, v[142:143] offset:11616
	v_add_f32_e32 v96, v96, v192
	v_add_f32_e32 v97, v97, v193
	v_add_f32_e32 v98, v98, v194
	v_add_f32_e32 v99, v99, v195
	v_mul_f32_e32 v96, 0xbfb8aa3b, v96
	v_mul_f32_e32 v97, 0xbfb8aa3b, v97
	v_mul_f32_e32 v98, 0xbfb8aa3b, v98
	v_mul_f32_e32 v99, 0xbfb8aa3b, v99
	v_exp_f32_e32 v96, v96
	v_exp_f32_e32 v97, v97
	v_exp_f32_e32 v98, v98
	v_exp_f32_e32 v99, v99
	s_nop 0
	v_add_f32_e32 v96, 1.0, v96
	v_add_f32_e32 v97, 1.0, v97
	v_add_f32_e32 v98, 1.0, v98
	v_add_f32_e32 v99, 1.0, v99
	v_rcp_f32_e32 v96, v96
	v_rcp_f32_e32 v97, v97
	v_rcp_f32_e32 v98, v98
	v_rcp_f32_e32 v99, v99
	s_nop 0
	v_cvt_pk_bf16_f32 v144, v96, v97
	v_cvt_pk_bf16_f32 v145, v98, v99
	ds_write_b64 v236, v[144:145] offset:13824
	v_add_f32_e32 v100, v100, v196
	v_add_f32_e32 v101, v101, v197
	v_add_f32_e32 v102, v102, v198
	v_add_f32_e32 v103, v103, v199
	v_mul_f32_e32 v100, 0xbfb8aa3b, v100
	v_mul_f32_e32 v101, 0xbfb8aa3b, v101
	v_mul_f32_e32 v102, 0xbfb8aa3b, v102
	v_mul_f32_e32 v103, 0xbfb8aa3b, v103
	v_exp_f32_e32 v100, v100
	v_exp_f32_e32 v101, v101
	v_exp_f32_e32 v102, v102
	v_exp_f32_e32 v103, v103
	s_nop 0
	v_add_f32_e32 v100, 1.0, v100
	v_add_f32_e32 v101, 1.0, v101
	v_add_f32_e32 v102, 1.0, v102
	v_add_f32_e32 v103, 1.0, v103
	v_rcp_f32_e32 v100, v100
	v_rcp_f32_e32 v101, v101
	v_rcp_f32_e32 v102, v102
	v_rcp_f32_e32 v103, v103
	s_nop 0
	v_cvt_pk_bf16_f32 v146, v100, v101
	v_cvt_pk_bf16_f32 v147, v102, v103
	ds_write_b64 v236, v[146:147] offset:13856
	v_add_f32_e32 v104, v104, v200
	v_add_f32_e32 v105, v105, v201
	v_add_f32_e32 v106, v106, v202
	v_add_f32_e32 v107, v107, v203
	v_mul_f32_e32 v104, 0xbfb8aa3b, v104
	v_mul_f32_e32 v105, 0xbfb8aa3b, v105
	v_mul_f32_e32 v106, 0xbfb8aa3b, v106
	v_mul_f32_e32 v107, 0xbfb8aa3b, v107
	v_exp_f32_e32 v104, v104
	v_exp_f32_e32 v105, v105
	v_exp_f32_e32 v106, v106
	v_exp_f32_e32 v107, v107
	s_nop 0
	v_add_f32_e32 v104, 1.0, v104
	v_add_f32_e32 v105, 1.0, v105
	v_add_f32_e32 v106, 1.0, v106
	v_add_f32_e32 v107, 1.0, v107
	v_rcp_f32_e32 v104, v104
	v_rcp_f32_e32 v105, v105
	v_rcp_f32_e32 v106, v106
	v_rcp_f32_e32 v107, v107
	s_nop 0
	v_cvt_pk_bf16_f32 v148, v104, v105
	v_cvt_pk_bf16_f32 v149, v106, v107
	ds_write_b64 v236, v[148:149] offset:13888
	v_add_f32_e32 v108, v108, v204
	v_add_f32_e32 v109, v109, v205
	v_add_f32_e32 v110, v110, v206
	v_add_f32_e32 v111, v111, v207
	v_mul_f32_e32 v108, 0xbfb8aa3b, v108
	v_mul_f32_e32 v109, 0xbfb8aa3b, v109
	v_mul_f32_e32 v110, 0xbfb8aa3b, v110
	v_mul_f32_e32 v111, 0xbfb8aa3b, v111
	v_exp_f32_e32 v108, v108
	v_exp_f32_e32 v109, v109
	v_exp_f32_e32 v110, v110
	v_exp_f32_e32 v111, v111
	s_nop 0
	v_add_f32_e32 v108, 1.0, v108
	v_add_f32_e32 v109, 1.0, v109
	v_add_f32_e32 v110, 1.0, v110
	v_add_f32_e32 v111, 1.0, v111
	v_rcp_f32_e32 v108, v108
	v_rcp_f32_e32 v109, v109
	v_rcp_f32_e32 v110, v110
	v_rcp_f32_e32 v111, v111
	s_nop 0
	v_cvt_pk_bf16_f32 v150, v108, v109
	v_cvt_pk_bf16_f32 v151, v110, v111
	ds_write_b64 v236, v[150:151] offset:13920
	v_add_f32_e32 v112, v112, v192
	v_add_f32_e32 v113, v113, v193
	v_add_f32_e32 v114, v114, v194
	v_add_f32_e32 v115, v115, v195
	v_mul_f32_e32 v112, 0xbfb8aa3b, v112
	v_mul_f32_e32 v113, 0xbfb8aa3b, v113
	v_mul_f32_e32 v114, 0xbfb8aa3b, v114
	v_mul_f32_e32 v115, 0xbfb8aa3b, v115
	v_exp_f32_e32 v112, v112
	v_exp_f32_e32 v113, v113
	v_exp_f32_e32 v114, v114
	v_exp_f32_e32 v115, v115
	s_nop 0
	v_add_f32_e32 v112, 1.0, v112
	v_add_f32_e32 v113, 1.0, v113
	v_add_f32_e32 v114, 1.0, v114
	v_add_f32_e32 v115, 1.0, v115
	v_rcp_f32_e32 v112, v112
	v_rcp_f32_e32 v113, v113
	v_rcp_f32_e32 v114, v114
	v_rcp_f32_e32 v115, v115
	s_nop 0
	v_cvt_pk_bf16_f32 v152, v112, v113
	v_cvt_pk_bf16_f32 v153, v114, v115
	ds_write_b64 v236, v[152:153] offset:16128
	v_add_f32_e32 v116, v116, v196
	v_add_f32_e32 v117, v117, v197
	v_add_f32_e32 v118, v118, v198
	v_add_f32_e32 v119, v119, v199
	v_mul_f32_e32 v116, 0xbfb8aa3b, v116
	v_mul_f32_e32 v117, 0xbfb8aa3b, v117
	v_mul_f32_e32 v118, 0xbfb8aa3b, v118
	v_mul_f32_e32 v119, 0xbfb8aa3b, v119
	v_exp_f32_e32 v116, v116
	v_exp_f32_e32 v117, v117
	v_exp_f32_e32 v118, v118
	v_exp_f32_e32 v119, v119
	s_nop 0
	v_add_f32_e32 v116, 1.0, v116
	v_add_f32_e32 v117, 1.0, v117
	v_add_f32_e32 v118, 1.0, v118
	v_add_f32_e32 v119, 1.0, v119
	v_rcp_f32_e32 v116, v116
	v_rcp_f32_e32 v117, v117
	v_rcp_f32_e32 v118, v118
	v_rcp_f32_e32 v119, v119
	s_nop 0
	v_cvt_pk_bf16_f32 v154, v116, v117
	v_cvt_pk_bf16_f32 v155, v118, v119
	ds_write_b64 v236, v[154:155] offset:16160
	v_add_f32_e32 v120, v120, v200
	v_add_f32_e32 v121, v121, v201
	v_add_f32_e32 v122, v122, v202
	v_add_f32_e32 v123, v123, v203
	v_mul_f32_e32 v120, 0xbfb8aa3b, v120
	v_mul_f32_e32 v121, 0xbfb8aa3b, v121
	v_mul_f32_e32 v122, 0xbfb8aa3b, v122
	v_mul_f32_e32 v123, 0xbfb8aa3b, v123
	v_exp_f32_e32 v120, v120
	v_exp_f32_e32 v121, v121
	v_exp_f32_e32 v122, v122
	v_exp_f32_e32 v123, v123
	s_nop 0
	v_add_f32_e32 v120, 1.0, v120
	v_add_f32_e32 v121, 1.0, v121
	v_add_f32_e32 v122, 1.0, v122
	v_add_f32_e32 v123, 1.0, v123
	v_rcp_f32_e32 v120, v120
	v_rcp_f32_e32 v121, v121
	v_rcp_f32_e32 v122, v122
	v_rcp_f32_e32 v123, v123
	s_nop 0
	v_cvt_pk_bf16_f32 v156, v120, v121
	v_cvt_pk_bf16_f32 v157, v122, v123
	ds_write_b64 v236, v[156:157] offset:16192
	v_add_f32_e32 v124, v124, v204
	v_add_f32_e32 v125, v125, v205
	v_add_f32_e32 v126, v126, v206
	v_add_f32_e32 v127, v127, v207
	v_mul_f32_e32 v124, 0xbfb8aa3b, v124
	v_mul_f32_e32 v125, 0xbfb8aa3b, v125
	v_mul_f32_e32 v126, 0xbfb8aa3b, v126
	v_mul_f32_e32 v127, 0xbfb8aa3b, v127
	v_exp_f32_e32 v124, v124
	v_exp_f32_e32 v125, v125
	v_exp_f32_e32 v126, v126
	v_exp_f32_e32 v127, v127
	s_nop 0
	v_add_f32_e32 v124, 1.0, v124
	v_add_f32_e32 v125, 1.0, v125
	v_add_f32_e32 v126, 1.0, v126
	v_add_f32_e32 v127, 1.0, v127
	v_rcp_f32_e32 v124, v124
	v_rcp_f32_e32 v125, v125
	v_rcp_f32_e32 v126, v126
	v_rcp_f32_e32 v127, v127
	s_nop 0
	v_cvt_pk_bf16_f32 v158, v124, v125
	v_cvt_pk_bf16_f32 v159, v126, v127
	ds_write_b64 v236, v[158:159] offset:16224
	s_waitcnt lgkmcnt(0)
; DI unsigned pack2(float lo, float hi) { const f32x2c v = {lo, hi}; return __builtin_bit_cast(unsigned, __builtin_convertvector(v, bf16x2c)); }
; template <class Epi>
; DI void gemm_tile(char* smem, const bf16_t* __restrict__ A0, int lda0, int ksplit, const bf16_t* __restrict__ A1, int lda1,
;                   const bf16_t* __restrict__ Bt, int K, int row0, int col0, const Epi& epi, int tid) {
;     ...
; #pragma unroll
;   for (int m = 0; m < 8; ++m)
; #pragma unroll
;     for (int n = 0; n < 4; ++n) epi(row0 + wr * 128 + m * 16 + fr, col0 + wc * 64 + n * 16 + fq * 4, acc[m][n]);
; }
; DI void st_bf16x4(bf16_t* o, f32x4 v) { u32x2 q; q.x = pack2(v[0], v[1]); q.y = pack2(v[2], v[3]); *(u32x2*)o = q; }
	ds_read_b128 v[128:131], v237
	ds_read_b128 v[132:135], v237 offset:1152
	ds_read_b128 v[136:139], v237 offset:2304
	ds_read_b128 v[140:143], v237 offset:3456
	ds_read_b128 v[144:147], v237 offset:4608
	ds_read_b128 v[148:151], v237 offset:5760
	ds_read_b128 v[152:155], v237 offset:6912
	ds_read_b128 v[156:159], v237 offset:8064
	ds_read_b128 v[160:163], v237 offset:9216
	ds_read_b128 v[164:167], v237 offset:10368
	ds_read_b128 v[168:171], v237 offset:11520
	ds_read_b128 v[172:175], v237 offset:12672
	ds_read_b128 v[176:179], v237 offset:13824
	ds_read_b128 v[180:183], v237 offset:14976
	ds_read_b128 v[184:187], v237 offset:16128
	ds_read_b128 v[188:191], v237 offset:17280
	s_waitcnt lgkmcnt(15)
	global_store_dwordx4 v238, v[128:131], s[4:5] nt
	s_add_u32 s4, s4, 0x2000
	s_addc_u32 s5, s5, 0
	s_waitcnt lgkmcnt(14)
	global_store_dwordx4 v238, v[132:135], s[4:5] nt
	s_add_u32 s4, s4, 0x2000
	s_addc_u32 s5, s5, 0
	s_waitcnt lgkmcnt(13)
	global_store_dwordx4 v238, v[136:139], s[4:5] nt
	s_add_u32 s4, s4, 0x2000
	s_addc_u32 s5, s5, 0
	s_waitcnt lgkmcnt(12)
	global_store_dwordx4 v238, v[140:143], s[4:5] nt
	s_add_u32 s4, s4, 0x2000
	s_addc_u32 s5, s5, 0
	s_waitcnt lgkmcnt(11)
	global_store_dwordx4 v238, v[144:147], s[4:5] nt
	s_add_u32 s4, s4, 0x2000
	s_addc_u32 s5, s5, 0
	s_waitcnt lgkmcnt(10)
	global_store_dwordx4 v238, v[148:151], s[4:5] nt
	s_add_u32 s4, s4, 0x2000
	s_addc_u32 s5, s5, 0
	s_waitcnt lgkmcnt(9)
	global_store_dwordx4 v238, v[152:155], s[4:5] nt
	s_add_u32 s4, s4, 0x2000
	s_addc_u32 s5, s5, 0
	s_waitcnt lgkmcnt(8)
	global_store_dwordx4 v238, v[156:159], s[4:5] nt
	s_add_u32 s4, s4, 0x2000
	s_addc_u32 s5, s5, 0
	s_waitcnt lgkmcnt(7)
	global_store_dwordx4 v238, v[160:163], s[4:5] nt
	s_add_u32 s4, s4, 0x2000
	s_addc_u32 s5, s5, 0
	s_waitcnt lgkmcnt(6)
	global_store_dwordx4 v238, v[164:167], s[4:5] nt
	s_add_u32 s4, s4, 0x2000
	s_addc_u32 s5, s5, 0
	s_waitcnt lgkmcnt(5)
	global_store_dwordx4 v238, v[168:171], s[4:5] nt
	s_add_u32 s4, s4, 0x2000
	s_addc_u32 s5, s5, 0
	s_waitcnt lgkmcnt(4)
	global_store_dwordx4 v238, v[172:175], s[4:5] nt
	s_add_u32 s4, s4, 0x2000
	s_addc_u32 s5, s5, 0
	s_waitcnt lgkmcnt(3)
	global_store_dwordx4 v238, v[176:179], s[4:5] nt
	s_add_u32 s4, s4, 0x2000
	s_addc_u32 s5, s5, 0
	s_waitcnt lgkmcnt(2)
	global_store_dwordx4 v238, v[180:183], s[4:5] nt
	s_add_u32 s4, s4, 0x2000
	s_addc_u32 s5, s5, 0
	s_waitcnt lgkmcnt(1)
	global_store_dwordx4 v238, v[184:187], s[4:5] nt
	s_add_u32 s4, s4, 0x2000
	s_addc_u32 s5, s5, 0
	s_waitcnt lgkmcnt(0)
	global_store_dwordx4 v238, v[188:191], s[4:5] nt
	s_nop 1
	s_add_u32 s15, s15, 64
	s_branch .Lg3c_tile

; DI unsigned pack2(float lo, float hi) { const f32x2c v = {lo, hi}; return __builtin_bit_cast(unsigned, __builtin_convertvector(v, bf16x2c)); }
; template <class Epi>
; DI void gemm_tile(char* smem, const bf16_t* __restrict__ A0, int lda0, int ksplit, const bf16_t* __restrict__ A1, int lda1,
;                   const bf16_t* __restrict__ Bt, int K, int row0, int col0, const Epi& epi, int tid) {
;     ...
; #pragma unroll
;   for (int m = 0; m < 8; ++m)
; #pragma unroll
;     for (int n = 0; n < 4; ++n) epi(row0 + wr * 128 + m * 16 + fr, col0 + wc * 64 + n * 16 + fq * 4, acc[m][n]);
; }
; DI void st_bf16x4(bf16_t* o, f32x4 v) { u32x2 q; q.x = pack2(v[0], v[1]); q.y = pack2(v[2], v[3]); *(u32x2*)o = q; }
.Lg3d_epi:
	s_nop 7
	s_nop 7
	s_mul_i32 s27, s29, 1024
	s_lshl_b32 s26, s28, 1
	s_add_u32 s27, s27, s26
	s_add_u32 s27, s27, 0x3800000
	s_add_u32 s4, s92, s27
	s_addc_u32 s5, s93, 0
	v_cvt_pk_bf16_f32 v128, v0, v1
	v_cvt_pk_bf16_f32 v129, v2, v3
	ds_write_b64 v236, v[128:129]
	v_cvt_pk_bf16_f32 v130, v4, v5
	v_cvt_pk_bf16_f32 v131, v6, v7
	ds_write_b64 v236, v[130:131] offset:32
	v_cvt_pk_bf16_f32 v132, v8, v9
	v_cvt_pk_bf16_f32 v133, v10, v11
	ds_write_b64 v236, v[132:133] offset:64
	v_cvt_pk_bf16_f32 v134, v12, v13
	v_cvt_pk_bf16_f32 v135, v14, v15
	ds_write_b64 v236, v[134:135] offset:96
	v_cvt_pk_bf16_f32 v136, v16, v17
	v_cvt_pk_bf16_f32 v137, v18, v19
	ds_write_b64 v236, v[136:137] offset:2304
	v_cvt_pk_bf16_f32 v138, v20, v21
	v_cvt_pk_bf16_f32 v139, v22, v23
	ds_write_b64 v236, v[138:139] offset:2336
	v_cvt_pk_bf16_f32 v140, v24, v25
	v_cvt_pk_bf16_f32 v141, v26, v27
	ds_write_b64 v236, v[140:141] offset:2368
	v_cvt_pk_bf16_f32 v142, v28, v29
	v_cvt_pk_bf16_f32 v143, v30, v31
	ds_write_b64 v236, v[142:143] offset:2400
	v_cvt_pk_bf16_f32 v144, v32, v33
	v_cvt_pk_bf16_f32 v145, v34, v35
	ds_write_b64 v236, v[144:145] offset:4608
	v_cvt_pk_bf16_f32 v146, v36, v37
	v_cvt_pk_bf16_f32 v147, v38, v39
	ds_write_b64 v236, v[146:147] offset:4640
	v_cvt_pk_bf16_f32 v148, v40, v41
	v_cvt_pk_bf16_f32 v149, v42, v43
	ds_write_b64 v236, v[148:149] offset:4672
	v_cvt_pk_bf16_f32 v150, v44, v45
	v_cvt_pk_bf16_f32 v151, v46, v47
	ds_write_b64 v236, v[150:151] offset:4704
	v_cvt_pk_bf16_f32 v152, v48, v49
	v_cvt_pk_bf16_f32 v153, v50, v51
	ds_write_b64 v236, v[152:153] offset:6912
	v_cvt_pk_bf16_f32 v154, v52, v53
	v_cvt_pk_bf16_f32 v155, v54, v55
	ds_write_b64 v236, v[154:155] offset:6944
	v_cvt_pk_bf16_f32 v156, v56, v57
	v_cvt_pk_bf16_f32 v157, v58, v59
	ds_write_b64 v236, v[156:157] offset:6976
	v_cvt_pk_bf16_f32 v158, v60, v61
	v_cvt_pk_bf16_f32 v159, v62, v63
	ds_write_b64 v236, v[158:159] offset:7008
	v_cvt_pk_bf16_f32 v128, v64, v65
	v_cvt_pk_bf16_f32 v129, v66, v67
	ds_write_b64 v236, v[128:129] offset:9216
	v_cvt_pk_bf16_f32 v130, v68, v69
	v_cvt_pk_bf16_f32 v131, v70, v71
	ds_write_b64 v236, v[130:131] offset:9248
	v_cvt_pk_bf16_f32 v132, v72, v73
	v_cvt_pk_bf16_f32 v133, v74, v75
	ds_write_b64 v236, v[132:133] offset:9280
	v_cvt_pk_bf16_f32 v134, v76, v77
	v_cvt_pk_bf16_f32 v135, v78, v79
	ds_write_b64 v236, v[134:135] offset:9312
	v_cvt_pk_bf16_f32 v136, v80, v81
	v_cvt_pk_bf16_f32 v137, v82, v83
	ds_write_b64 v236, v[136:137] offset:11520
	v_cvt_pk_bf16_f32 v138, v84, v85
	v_cvt_pk_bf16_f32 v139, v86, v87
	ds_write_b64 v236, v[138:139] offset:11552
	v_cvt_pk_bf16_f32 v140, v88, v89
	v_cvt_pk_bf16_f32 v141, v90, v91
	ds_write_b64 v236, v[140:141] offset:11584
	v_cvt_pk_bf16_f32 v142, v92, v93
	v_cvt_pk_bf16_f32 v143, v94, v95
	ds_write_b64 v236, v[142:143] offset:11616
	v_cvt_pk_bf16_f32 v144, v96, v97
	v_cvt_pk_bf16_f32 v145, v98, v99
	ds_write_b64 v236, v[144:145] offset:13824
	v_cvt_pk_bf16_f32 v146, v100, v101
	v_cvt_pk_bf16_f32 v147, v102, v103
	ds_write_b64 v236, v[146:147] offset:13856
	v_cvt_pk_bf16_f32 v148, v104, v105
	v_cvt_pk_bf16_f32 v149, v106, v107
	ds_write_b64 v236, v[148:149] offset:13888
	v_cvt_pk_bf16_f32 v150, v108, v109
	v_cvt_pk_bf16_f32 v151, v110, v111
	ds_write_b64 v236, v[150:151] offset:13920
	v_cvt_pk_bf16_f32 v152, v112, v113
	v_cvt_pk_bf16_f32 v153, v114, v115
	ds_write_b64 v236, v[152:153] offset:16128
	v_cvt_pk_bf16_f32 v154, v116, v117
	v_cvt_pk_bf16_f32 v155, v118, v119
	ds_write_b64 v236, v[154:155] offset:16160
	v_cvt_pk_bf16_f32 v156, v120, v121
	v_cvt_pk_bf16_f32 v157, v122, v123
	ds_write_b64 v236, v[156:157] offset:16192
	v_cvt_pk_bf16_f32 v158, v124, v125
	v_cvt_pk_bf16_f32 v159, v126, v127
	ds_write_b64 v236, v[158:159] offset:16224
	s_waitcnt lgkmcnt(0)
	ds_read_b128 v[128:131], v237
	ds_read_b128 v[132:135], v237 offset:1152
	ds_read_b128 v[136:139], v237 offset:2304
	ds_read_b128 v[140:143], v237 offset:3456
	ds_read_b128 v[144:147], v237 offset:4608
	ds_read_b128 v[148:151], v237 offset:5760
	ds_read_b128 v[152:155], v237 offset:6912
	ds_read_b128 v[156:159], v237 offset:8064
	ds_read_b128 v[160:163], v237 offset:9216
	ds_read_b128 v[164:167], v237 offset:10368
	ds_read_b128 v[168:171], v237 offset:11520
	ds_read_b128 v[172:175], v237 offset:12672
	ds_read_b128 v[176:179], v237 offset:13824
	ds_read_b128 v[180:183], v237 offset:14976
	ds_read_b128 v[184:187], v237 offset:16128
	ds_read_b128 v[188:191], v237 offset:17280
	s_waitcnt lgkmcnt(15)
	global_store_dwordx4 v238, v[128:131], s[4:5] nt
	s_add_u32 s4, s4, 0x2000
	s_addc_u32 s5, s5, 0
	s_waitcnt lgkmcnt(14)
	global_store_dwordx4 v238, v[132:135], s[4:5] nt
	s_add_u32 s4, s4, 0x2000
	s_addc_u32 s5, s5, 0
	s_waitcnt lgkmcnt(13)
	global_store_dwordx4 v238, v[136:139], s[4:5] nt
	s_add_u32 s4, s4, 0x2000
	s_addc_u32 s5, s5, 0
	s_waitcnt lgkmcnt(12)
	global_store_dwordx4 v238, v[140:143], s[4:5] nt
	s_add_u32 s4, s4, 0x2000
	s_addc_u32 s5, s5, 0
	s_waitcnt lgkmcnt(11)
	global_store_dwordx4 v238, v[144:147], s[4:5] nt
	s_add_u32 s4, s4, 0x2000
	s_addc_u32 s5, s5, 0
	s_waitcnt lgkmcnt(10)
	global_store_dwordx4 v238, v[148:151], s[4:5] nt
	s_add_u32 s4, s4, 0x2000
	s_addc_u32 s5, s5, 0
	s_waitcnt lgkmcnt(9)
	global_store_dwordx4 v238, v[152:155], s[4:5] nt
	s_add_u32 s4, s4, 0x2000
	s_addc_u32 s5, s5, 0
	s_waitcnt lgkmcnt(8)
	global_store_dwordx4 v238, v[156:159], s[4:5] nt
	s_add_u32 s4, s4, 0x2000
	s_addc_u32 s5, s5, 0
	s_waitcnt lgkmcnt(7)
	global_store_dwordx4 v238, v[160:163], s[4:5] nt
	s_add_u32 s4, s4, 0x2000
	s_addc_u32 s5, s5, 0
	s_waitcnt lgkmcnt(6)
	global_store_dwordx4 v238, v[164:167], s[4:5] nt
	s_add_u32 s4, s4, 0x2000
	s_addc_u32 s5, s5, 0
	s_waitcnt lgkmcnt(5)
	global_store_dwordx4 v238, v[168:171], s[4:5] nt
	s_add_u32 s4, s4, 0x2000
	s_addc_u32 s5, s5, 0
	s_waitcnt lgkmcnt(4)
	global_store_dwordx4 v238, v[172:175], s[4:5] nt
	s_add_u32 s4, s4, 0x2000
	s_addc_u32 s5, s5, 0
	s_waitcnt lgkmcnt(3)
	global_store_dwordx4 v238, v[176:179], s[4:5] nt
	s_add_u32 s4, s4, 0x2000
	s_addc_u32 s5, s5, 0
	s_waitcnt lgkmcnt(2)
	global_store_dwordx4 v238, v[180:183], s[4:5] nt
	s_add_u32 s4, s4, 0x2000
	s_addc_u32 s5, s5, 0
	s_waitcnt lgkmcnt(1)
	global_store_dwordx4 v238, v[184:187], s[4:5] nt
	s_add_u32 s4, s4, 0x2000
	s_addc_u32 s5, s5, 0
	s_waitcnt lgkmcnt(0)
	global_store_dwordx4 v238, v[188:191], s[4:5] nt
	s_nop 1
	s_add_u32 s15, s15, 64
	s_branch .Lg3d_tile

; template <class Epi>
; DI void gemm_tile(char* smem, const bf16_t* __restrict__ A0, int lda0, int ksplit, const bf16_t* __restrict__ A1, int lda1,
;                   const bf16_t* __restrict__ Bt, int K, int row0, int col0, const Epi& epi, int tid) {
;     ...
; #pragma unroll
;   for (int m = 0; m < 8; ++m)
; #pragma unroll
;     for (int n = 0; n < 4; ++n) epi(row0 + wr * 128 + m * 16 + fr, col0 + wc * 64 + n * 16 + fq * 4, acc[m][n]);
.Lg8_epi:
	s_nop 7
	s_nop 7
	s_mul_i32 s12, s18, 8192
	s_lshl_b32 s11, s13, 1
	s_add_u32 s12, s12, s11
	s_add_u32 s12, s12, 0x7800000
	s_add_u32 s4, s92, s12
	s_addc_u32 s5, s93, 0
	v_max_f32_e32 v0, 0, v0
	v_max_f32_e32 v1, 0, v1
	v_max_f32_e32 v2, 0, v2
	v_max_f32_e32 v3, 0, v3
	v_pk_mul_f32 v[0:1], v[0:1], v[0:1]
	v_pk_mul_f32 v[2:3], v[2:3], v[2:3]
	v_cvt_pk_bf16_f32 v128, v0, v1
	v_cvt_pk_bf16_f32 v129, v2, v3
	ds_write_b64 v236, v[128:129]
	v_max_f32_e32 v4, 0, v4
	v_max_f32_e32 v5, 0, v5
	v_max_f32_e32 v6, 0, v6
	v_max_f32_e32 v7, 0, v7
	v_pk_mul_f32 v[4:5], v[4:5], v[4:5]
	v_pk_mul_f32 v[6:7], v[6:7], v[6:7]
	v_cvt_pk_bf16_f32 v130, v4, v5
	v_cvt_pk_bf16_f32 v131, v6, v7
	ds_write_b64 v236, v[130:131] offset:32
	v_max_f32_e32 v8, 0, v8
	v_max_f32_e32 v9, 0, v9
	v_max_f32_e32 v10, 0, v10
	v_max_f32_e32 v11, 0, v11
	v_pk_mul_f32 v[8:9], v[8:9], v[8:9]
	v_pk_mul_f32 v[10:11], v[10:11], v[10:11]
	v_cvt_pk_bf16_f32 v132, v8, v9
	v_cvt_pk_bf16_f32 v133, v10, v11
	ds_write_b64 v236, v[132:133] offset:64
	v_max_f32_e32 v12, 0, v12
	v_max_f32_e32 v13, 0, v13
	v_max_f32_e32 v14, 0, v14
	v_max_f32_e32 v15, 0, v15
	v_pk_mul_f32 v[12:13], v[12:13], v[12:13]
	v_pk_mul_f32 v[14:15], v[14:15], v[14:15]
	v_cvt_pk_bf16_f32 v134, v12, v13
	v_cvt_pk_bf16_f32 v135, v14, v15
	ds_write_b64 v236, v[134:135] offset:96
	v_max_f32_e32 v16, 0, v16
	v_max_f32_e32 v17, 0, v17
	v_max_f32_e32 v18, 0, v18
	v_max_f32_e32 v19, 0, v19
	v_pk_mul_f32 v[16:17], v[16:17], v[16:17]
	v_pk_mul_f32 v[18:19], v[18:19], v[18:19]
	v_cvt_pk_bf16_f32 v136, v16, v17
	v_cvt_pk_bf16_f32 v137, v18, v19
	ds_write_b64 v236, v[136:137] offset:2304
	v_max_f32_e32 v20, 0, v20
	v_max_f32_e32 v21, 0, v21
	v_max_f32_e32 v22, 0, v22
	v_max_f32_e32 v23, 0, v23
	v_pk_mul_f32 v[20:21], v[20:21], v[20:21]
	v_pk_mul_f32 v[22:23], v[22:23], v[22:23]
	v_cvt_pk_bf16_f32 v138, v20, v21
	v_cvt_pk_bf16_f32 v139, v22, v23
	ds_write_b64 v236, v[138:139] offset:2336
	v_max_f32_e32 v24, 0, v24
	v_max_f32_e32 v25, 0, v25
	v_max_f32_e32 v26, 0, v26
	v_max_f32_e32 v27, 0, v27
	v_pk_mul_f32 v[24:25], v[24:25], v[24:25]
	v_pk_mul_f32 v[26:27], v[26:27], v[26:27]
	v_cvt_pk_bf16_f32 v140, v24, v25
	v_cvt_pk_bf16_f32 v141, v26, v27
	ds_write_b64 v236, v[140:141] offset:2368
	v_max_f32_e32 v28, 0, v28
	v_max_f32_e32 v29, 0, v29
	v_max_f32_e32 v30, 0, v30
	v_max_f32_e32 v31, 0, v31
	v_pk_mul_f32 v[28:29], v[28:29], v[28:29]
	v_pk_mul_f32 v[30:31], v[30:31], v[30:31]
	v_cvt_pk_bf16_f32 v142, v28, v29
	v_cvt_pk_bf16_f32 v143, v30, v31
	ds_write_b64 v236, v[142:143] offset:2400
	v_max_f32_e32 v32, 0, v32
	v_max_f32_e32 v33, 0, v33
	v_max_f32_e32 v34, 0, v34
	v_max_f32_e32 v35, 0, v35
	v_pk_mul_f32 v[32:33], v[32:33], v[32:33]
	v_pk_mul_f32 v[34:35], v[34:35], v[34:35]
	v_cvt_pk_bf16_f32 v144, v32, v33
	v_cvt_pk_bf16_f32 v145, v34, v35
	ds_write_b64 v236, v[144:145] offset:4608
	v_max_f32_e32 v36, 0, v36
	v_max_f32_e32 v37, 0, v37
	v_max_f32_e32 v38, 0, v38
	v_max_f32_e32 v39, 0, v39
	v_pk_mul_f32 v[36:37], v[36:37], v[36:37]
	v_pk_mul_f32 v[38:39], v[38:39], v[38:39]
	v_cvt_pk_bf16_f32 v146, v36, v37
	v_cvt_pk_bf16_f32 v147, v38, v39
	ds_write_b64 v236, v[146:147] offset:4640
	v_max_f32_e32 v40, 0, v40
	v_max_f32_e32 v41, 0, v41
	v_max_f32_e32 v42, 0, v42
	v_max_f32_e32 v43, 0, v43
	v_pk_mul_f32 v[40:41], v[40:41], v[40:41]
	v_pk_mul_f32 v[42:43], v[42:43], v[42:43]
	v_cvt_pk_bf16_f32 v148, v40, v41
	v_cvt_pk_bf16_f32 v149, v42, v43
	ds_write_b64 v236, v[148:149] offset:4672
	v_max_f32_e32 v44, 0, v44
	v_max_f32_e32 v45, 0, v45
	v_max_f32_e32 v46, 0, v46
	v_max_f32_e32 v47, 0, v47
	v_pk_mul_f32 v[44:45], v[44:45], v[44:45]
	v_pk_mul_f32 v[46:47], v[46:47], v[46:47]
	v_cvt_pk_bf16_f32 v150, v44, v45
	v_cvt_pk_bf16_f32 v151, v46, v47
	ds_write_b64 v236, v[150:151] offset:4704
	v_max_f32_e32 v48, 0, v48
	v_max_f32_e32 v49, 0, v49
	v_max_f32_e32 v50, 0, v50
	v_max_f32_e32 v51, 0, v51
	v_pk_mul_f32 v[48:49], v[48:49], v[48:49]
	v_pk_mul_f32 v[50:51], v[50:51], v[50:51]
	v_cvt_pk_bf16_f32 v152, v48, v49
	v_cvt_pk_bf16_f32 v153, v50, v51
	ds_write_b64 v236, v[152:153] offset:6912
	v_max_f32_e32 v52, 0, v52
	v_max_f32_e32 v53, 0, v53
	v_max_f32_e32 v54, 0, v54
	v_max_f32_e32 v55, 0, v55
	v_pk_mul_f32 v[52:53], v[52:53], v[52:53]
	v_pk_mul_f32 v[54:55], v[54:55], v[54:55]
	v_cvt_pk_bf16_f32 v154, v52, v53
	v_cvt_pk_bf16_f32 v155, v54, v55
	ds_write_b64 v236, v[154:155] offset:6944
	v_max_f32_e32 v56, 0, v56
	v_max_f32_e32 v57, 0, v57
	v_max_f32_e32 v58, 0, v58
	v_max_f32_e32 v59, 0, v59
	v_pk_mul_f32 v[56:57], v[56:57], v[56:57]
	v_pk_mul_f32 v[58:59], v[58:59], v[58:59]
	v_cvt_pk_bf16_f32 v156, v56, v57
	v_cvt_pk_bf16_f32 v157, v58, v59
	ds_write_b64 v236, v[156:157] offset:6976
	v_max_f32_e32 v60, 0, v60
	v_max_f32_e32 v61, 0, v61
	v_max_f32_e32 v62, 0, v62
	v_max_f32_e32 v63, 0, v63
	v_pk_mul_f32 v[60:61], v[60:61], v[60:61]
	v_pk_mul_f32 v[62:63], v[62:63], v[62:63]
	v_cvt_pk_bf16_f32 v158, v60, v61
	v_cvt_pk_bf16_f32 v159, v62, v63
	ds_write_b64 v236, v[158:159] offset:7008
	v_max_f32_e32 v64, 0, v64
	v_max_f32_e32 v65, 0, v65
	v_max_f32_e32 v66, 0, v66
	v_max_f32_e32 v67, 0, v67
	v_pk_mul_f32 v[64:65], v[64:65], v[64:65]
	v_pk_mul_f32 v[66:67], v[66:67], v[66:67]
	v_cvt_pk_bf16_f32 v128, v64, v65
	v_cvt_pk_bf16_f32 v129, v66, v67
	ds_write_b64 v236, v[128:129] offset:9216
	v_max_f32_e32 v68, 0, v68
	v_max_f32_e32 v69, 0, v69
	v_max_f32_e32 v70, 0, v70
	v_max_f32_e32 v71, 0, v71
	v_pk_mul_f32 v[68:69], v[68:69], v[68:69]
	v_pk_mul_f32 v[70:71], v[70:71], v[70:71]
	v_cvt_pk_bf16_f32 v130, v68, v69
	v_cvt_pk_bf16_f32 v131, v70, v71
	ds_write_b64 v236, v[130:131] offset:9248
	v_max_f32_e32 v72, 0, v72
	v_max_f32_e32 v73, 0, v73
; DI unsigned pack2(float lo, float hi) { const f32x2c v = {lo, hi}; return __builtin_bit_cast(unsigned, __builtin_convertvector(v, bf16x2c)); }
; template <class Epi>
; DI void gemm_tile(char* smem, const bf16_t* __restrict__ A0, int lda0, int ksplit, const bf16_t* __restrict__ A1, int lda1,
;                   const bf16_t* __restrict__ Bt, int K, int row0, int col0, const Epi& epi, int tid) {
;     ...
; #pragma unroll
;   for (int m = 0; m < 8; ++m)
; #pragma unroll
;     for (int n = 0; n < 4; ++n) epi(row0 + wr * 128 + m * 16 + fr, col0 + wc * 64 + n * 16 + fq * 4, acc[m][n]);
; }
; DI void st_bf16x4(bf16_t* o, f32x4 v) { u32x2 q; q.x = pack2(v[0], v[1]); q.y = pack2(v[2], v[3]); *(u32x2*)o = q; }
	v_max_f32_e32 v74, 0, v74
	v_max_f32_e32 v75, 0, v75
	v_pk_mul_f32 v[72:73], v[72:73], v[72:73]
	v_pk_mul_f32 v[74:75], v[74:75], v[74:75]
	v_cvt_pk_bf16_f32 v132, v72, v73
	v_cvt_pk_bf16_f32 v133, v74, v75
	ds_write_b64 v236, v[132:133] offset:9280
	v_max_f32_e32 v76, 0, v76
	v_max_f32_e32 v77, 0, v77
	v_max_f32_e32 v78, 0, v78
	v_max_f32_e32 v79, 0, v79
	v_pk_mul_f32 v[76:77], v[76:77], v[76:77]
	v_pk_mul_f32 v[78:79], v[78:79], v[78:79]
	v_cvt_pk_bf16_f32 v134, v76, v77
	v_cvt_pk_bf16_f32 v135, v78, v79
	ds_write_b64 v236, v[134:135] offset:9312
	v_max_f32_e32 v80, 0, v80
	v_max_f32_e32 v81, 0, v81
	v_max_f32_e32 v82, 0, v82
	v_max_f32_e32 v83, 0, v83
	v_pk_mul_f32 v[80:81], v[80:81], v[80:81]
	v_pk_mul_f32 v[82:83], v[82:83], v[82:83]
	v_cvt_pk_bf16_f32 v136, v80, v81
	v_cvt_pk_bf16_f32 v137, v82, v83
	ds_write_b64 v236, v[136:137] offset:11520
	v_max_f32_e32 v84, 0, v84
	v_max_f32_e32 v85, 0, v85
	v_max_f32_e32 v86, 0, v86
	v_max_f32_e32 v87, 0, v87
	v_pk_mul_f32 v[84:85], v[84:85], v[84:85]
	v_pk_mul_f32 v[86:87], v[86:87], v[86:87]
	v_cvt_pk_bf16_f32 v138, v84, v85
	v_cvt_pk_bf16_f32 v139, v86, v87
	ds_write_b64 v236, v[138:139] offset:11552
	v_max_f32_e32 v88, 0, v88
	v_max_f32_e32 v89, 0, v89
	v_max_f32_e32 v90, 0, v90
	v_max_f32_e32 v91, 0, v91
	v_pk_mul_f32 v[88:89], v[88:89], v[88:89]
	v_pk_mul_f32 v[90:91], v[90:91], v[90:91]
	v_cvt_pk_bf16_f32 v140, v88, v89
	v_cvt_pk_bf16_f32 v141, v90, v91
	ds_write_b64 v236, v[140:141] offset:11584
	v_max_f32_e32 v92, 0, v92
	v_max_f32_e32 v93, 0, v93
	v_max_f32_e32 v94, 0, v94
	v_max_f32_e32 v95, 0, v95
	v_pk_mul_f32 v[92:93], v[92:93], v[92:93]
	v_pk_mul_f32 v[94:95], v[94:95], v[94:95]
	v_cvt_pk_bf16_f32 v142, v92, v93
	v_cvt_pk_bf16_f32 v143, v94, v95
	ds_write_b64 v236, v[142:143] offset:11616
	v_max_f32_e32 v96, 0, v96
	v_max_f32_e32 v97, 0, v97
	v_max_f32_e32 v98, 0, v98
	v_max_f32_e32 v99, 0, v99
	v_pk_mul_f32 v[96:97], v[96:97], v[96:97]
	v_pk_mul_f32 v[98:99], v[98:99], v[98:99]
	v_cvt_pk_bf16_f32 v144, v96, v97
	v_cvt_pk_bf16_f32 v145, v98, v99
	ds_write_b64 v236, v[144:145] offset:13824
	v_max_f32_e32 v100, 0, v100
	v_max_f32_e32 v101, 0, v101
	v_max_f32_e32 v102, 0, v102
	v_max_f32_e32 v103, 0, v103
	v_pk_mul_f32 v[100:101], v[100:101], v[100:101]
	v_pk_mul_f32 v[102:103], v[102:103], v[102:103]
	v_cvt_pk_bf16_f32 v146, v100, v101
	v_cvt_pk_bf16_f32 v147, v102, v103
	ds_write_b64 v236, v[146:147] offset:13856
	v_max_f32_e32 v104, 0, v104
	v_max_f32_e32 v105, 0, v105
	v_max_f32_e32 v106, 0, v106
	v_max_f32_e32 v107, 0, v107
	v_pk_mul_f32 v[104:105], v[104:105], v[104:105]
	v_pk_mul_f32 v[106:107], v[106:107], v[106:107]
	v_cvt_pk_bf16_f32 v148, v104, v105
	v_cvt_pk_bf16_f32 v149, v106, v107
	ds_write_b64 v236, v[148:149] offset:13888
	v_max_f32_e32 v108, 0, v108
	v_max_f32_e32 v109, 0, v109
	v_max_f32_e32 v110, 0, v110
	v_max_f32_e32 v111, 0, v111
	v_pk_mul_f32 v[108:109], v[108:109], v[108:109]
	v_pk_mul_f32 v[110:111], v[110:111], v[110:111]
	v_cvt_pk_bf16_f32 v150, v108, v109
	v_cvt_pk_bf16_f32 v151, v110, v111
	ds_write_b64 v236, v[150:151] offset:13920
	v_max_f32_e32 v112, 0, v112
	v_max_f32_e32 v113, 0, v113
	v_max_f32_e32 v114, 0, v114
	v_max_f32_e32 v115, 0, v115
	v_pk_mul_f32 v[112:113], v[112:113], v[112:113]
	v_pk_mul_f32 v[114:115], v[114:115], v[114:115]
	v_cvt_pk_bf16_f32 v152, v112, v113
	v_cvt_pk_bf16_f32 v153, v114, v115
	ds_write_b64 v236, v[152:153] offset:16128
	v_max_f32_e32 v116, 0, v116
	v_max_f32_e32 v117, 0, v117
	v_max_f32_e32 v118, 0, v118
	v_max_f32_e32 v119, 0, v119
	v_pk_mul_f32 v[116:117], v[116:117], v[116:117]
	v_pk_mul_f32 v[118:119], v[118:119], v[118:119]
	v_cvt_pk_bf16_f32 v154, v116, v117
	v_cvt_pk_bf16_f32 v155, v118, v119
	ds_write_b64 v236, v[154:155] offset:16160
	v_max_f32_e32 v120, 0, v120
	v_max_f32_e32 v121, 0, v121
	v_max_f32_e32 v122, 0, v122
	v_max_f32_e32 v123, 0, v123
	v_pk_mul_f32 v[120:121], v[120:121], v[120:121]
	v_pk_mul_f32 v[122:123], v[122:123], v[122:123]
	v_cvt_pk_bf16_f32 v156, v120, v121
	v_cvt_pk_bf16_f32 v157, v122, v123
	ds_write_b64 v236, v[156:157] offset:16192
	v_max_f32_e32 v124, 0, v124
	v_max_f32_e32 v125, 0, v125
	v_max_f32_e32 v126, 0, v126
	v_max_f32_e32 v127, 0, v127
	v_pk_mul_f32 v[124:125], v[124:125], v[124:125]
	v_pk_mul_f32 v[126:127], v[126:127], v[126:127]
	v_cvt_pk_bf16_f32 v158, v124, v125
	v_cvt_pk_bf16_f32 v159, v126, v127
	ds_write_b64 v236, v[158:159] offset:16224
	s_waitcnt lgkmcnt(0)
	ds_read_b128 v[128:131], v237
	ds_read_b128 v[132:135], v237 offset:1152
	ds_read_b128 v[136:139], v237 offset:2304
	ds_read_b128 v[140:143], v237 offset:3456
	ds_read_b128 v[144:147], v237 offset:4608
	ds_read_b128 v[148:151], v237 offset:5760
	ds_read_b128 v[152:155], v237 offset:6912
	ds_read_b128 v[156:159], v237 offset:8064
	ds_read_b128 v[160:163], v237 offset:9216
	ds_read_b128 v[164:167], v237 offset:10368
	ds_read_b128 v[168:171], v237 offset:11520
	ds_read_b128 v[172:175], v237 offset:12672
	ds_read_b128 v[176:179], v237 offset:13824
	ds_read_b128 v[180:183], v237 offset:14976
	ds_read_b128 v[184:187], v237 offset:16128
	ds_read_b128 v[188:191], v237 offset:17280
	s_waitcnt lgkmcnt(15)
	global_store_dwordx4 v238, v[128:131], s[4:5] nt
	s_add_u32 s4, s4, 0x10000
	s_addc_u32 s5, s5, 0
	s_waitcnt lgkmcnt(14)
	global_store_dwordx4 v238, v[132:135], s[4:5] nt
	s_add_u32 s4, s4, 0x10000
	s_addc_u32 s5, s5, 0
	s_waitcnt lgkmcnt(13)
	global_store_dwordx4 v238, v[136:139], s[4:5] nt
	s_add_u32 s4, s4, 0x10000
	s_addc_u32 s5, s5, 0
	s_waitcnt lgkmcnt(12)
	global_store_dwordx4 v238, v[140:143], s[4:5] nt
	s_add_u32 s4, s4, 0x10000
	s_addc_u32 s5, s5, 0
	s_waitcnt lgkmcnt(11)
	global_store_dwordx4 v238, v[144:147], s[4:5] nt
	s_add_u32 s4, s4, 0x10000
	s_addc_u32 s5, s5, 0
	s_waitcnt lgkmcnt(10)
	global_store_dwordx4 v238, v[148:151], s[4:5] nt
	s_add_u32 s4, s4, 0x10000
	s_addc_u32 s5, s5, 0
	s_waitcnt lgkmcnt(9)
	global_store_dwordx4 v238, v[152:155], s[4:5] nt
	s_add_u32 s4, s4, 0x10000
	s_addc_u32 s5, s5, 0
	s_waitcnt lgkmcnt(8)
	global_store_dwordx4 v238, v[156:159], s[4:5] nt
	s_add_u32 s4, s4, 0x10000
	s_addc_u32 s5, s5, 0
	s_waitcnt lgkmcnt(7)
	global_store_dwordx4 v238, v[160:163], s[4:5] nt
	s_add_u32 s4, s4, 0x10000
	s_addc_u32 s5, s5, 0
	s_waitcnt lgkmcnt(6)
	global_store_dwordx4 v238, v[164:167], s[4:5] nt
	s_add_u32 s4, s4, 0x10000
	s_addc_u32 s5, s5, 0
	s_waitcnt lgkmcnt(5)
	global_store_dwordx4 v238, v[168:171], s[4:5] nt
	s_add_u32 s4, s4, 0x10000
	s_addc_u32 s5, s5, 0
	s_waitcnt lgkmcnt(4)
	global_store_dwordx4 v238, v[172:175], s[4:5] nt
	s_add_u32 s4, s4, 0x10000
	s_addc_u32 s5, s5, 0
	s_waitcnt lgkmcnt(3)
	global_store_dwordx4 v238, v[176:179], s[4:5] nt
	s_add_u32 s4, s4, 0x10000
	s_addc_u32 s5, s5, 0
	s_waitcnt lgkmcnt(2)
	global_store_dwordx4 v238, v[180:183], s[4:5] nt
	s_add_u32 s4, s4, 0x10000
	s_addc_u32 s5, s5, 0
	s_waitcnt lgkmcnt(1)
	global_store_dwordx4 v238, v[184:187], s[4:5] nt
	s_add_u32 s4, s4, 0x10000
	s_addc_u32 s5, s5, 0
	s_waitcnt lgkmcnt(0)
	global_store_dwordx4 v238, v[188:191], s[4:5] nt
	s_nop 1
	s_add_u32 s17, s17, 64
	s_branch .Lg8_tile

; DI unsigned pack2(float lo, float hi) { const f32x2c v = {lo, hi}; return __builtin_bit_cast(unsigned, __builtin_convertvector(v, bf16x2c)); }
; template <class Epi>
; DI void gemm_tile(char* smem, const bf16_t* __restrict__ A0, int lda0, int ksplit, const bf16_t* __restrict__ A1, int lda1,
;                   const bf16_t* __restrict__ Bt, int K, int row0, int col0, const Epi& epi, int tid) {
;     ...
; #pragma unroll
;   for (int m = 0; m < 8; ++m)
; #pragma unroll
;     for (int n = 0; n < 4; ++n) epi(row0 + wr * 128 + m * 16 + fr, col0 + wc * 64 + n * 16 + fq * 4, acc[m][n]);
; }
; DI void st_bf16x4(bf16_t* o, f32x4 v) { u32x2 q; q.x = pack2(v[0], v[1]); q.y = pack2(v[2], v[3]); *(u32x2*)o = q; }
;   DI void operator()(int row, int col, f32x4 v) const {
;     if (col < n0) st_bf16x4(o0 + (size_t)row * ld0 + col, v);
;     else { const int c = col - n0; if (c < n1) st_bf16x4(o1 + (size_t)row * ld1 + c, v); }
;   }
.Lg11_epi:
	s_nop 7
	s_nop 7
	s_cmpk_ge_u32 s27, 512
	s_cbranch_scc1 .Lg11_eo1
	s_mul_i32 s26, s28, 1024
	s_lshl_b32 s25, s27, 1
	s_add_u32 s26, s26, s25
	s_add_u32 s26, s26, 0x7800000
	s_add_u32 s4, s92, s26
	s_addc_u32 s5, s93, 0
	v_cvt_pk_bf16_f32 v128, v0, v1
	v_cvt_pk_bf16_f32 v129, v2, v3
	ds_write_b64 v236, v[128:129]
	v_cvt_pk_bf16_f32 v130, v4, v5
	v_cvt_pk_bf16_f32 v131, v6, v7
	ds_write_b64 v236, v[130:131] offset:32
	v_cvt_pk_bf16_f32 v132, v8, v9
	v_cvt_pk_bf16_f32 v133, v10, v11
	ds_write_b64 v236, v[132:133] offset:64
	v_cvt_pk_bf16_f32 v134, v12, v13
	v_cvt_pk_bf16_f32 v135, v14, v15
	ds_write_b64 v236, v[134:135] offset:96
	v_cvt_pk_bf16_f32 v136, v16, v17
	v_cvt_pk_bf16_f32 v137, v18, v19
	ds_write_b64 v236, v[136:137] offset:2304
	v_cvt_pk_bf16_f32 v138, v20, v21
	v_cvt_pk_bf16_f32 v139, v22, v23
	ds_write_b64 v236, v[138:139] offset:2336
	v_cvt_pk_bf16_f32 v140, v24, v25
	v_cvt_pk_bf16_f32 v141, v26, v27
	ds_write_b64 v236, v[140:141] offset:2368
	v_cvt_pk_bf16_f32 v142, v28, v29
	v_cvt_pk_bf16_f32 v143, v30, v31
	ds_write_b64 v236, v[142:143] offset:2400
	v_cvt_pk_bf16_f32 v144, v32, v33
	v_cvt_pk_bf16_f32 v145, v34, v35
	ds_write_b64 v236, v[144:145] offset:4608
	v_cvt_pk_bf16_f32 v146, v36, v37
	v_cvt_pk_bf16_f32 v147, v38, v39
	ds_write_b64 v236, v[146:147] offset:4640
	v_cvt_pk_bf16_f32 v148, v40, v41
	v_cvt_pk_bf16_f32 v149, v42, v43
	ds_write_b64 v236, v[148:149] offset:4672
	v_cvt_pk_bf16_f32 v150, v44, v45
	v_cvt_pk_bf16_f32 v151, v46, v47
	ds_write_b64 v236, v[150:151] offset:4704
	v_cvt_pk_bf16_f32 v152, v48, v49
	v_cvt_pk_bf16_f32 v153, v50, v51
	ds_write_b64 v236, v[152:153] offset:6912
	v_cvt_pk_bf16_f32 v154, v52, v53
	v_cvt_pk_bf16_f32 v155, v54, v55
	ds_write_b64 v236, v[154:155] offset:6944
	v_cvt_pk_bf16_f32 v156, v56, v57
	v_cvt_pk_bf16_f32 v157, v58, v59
	ds_write_b64 v236, v[156:157] offset:6976
	v_cvt_pk_bf16_f32 v158, v60, v61
	v_cvt_pk_bf16_f32 v159, v62, v63
	ds_write_b64 v236, v[158:159] offset:7008
	v_cvt_pk_bf16_f32 v128, v64, v65
	v_cvt_pk_bf16_f32 v129, v66, v67
	ds_write_b64 v236, v[128:129] offset:9216
	v_cvt_pk_bf16_f32 v130, v68, v69
	v_cvt_pk_bf16_f32 v131, v70, v71
	ds_write_b64 v236, v[130:131] offset:9248
	v_cvt_pk_bf16_f32 v132, v72, v73
	v_cvt_pk_bf16_f32 v133, v74, v75
	ds_write_b64 v236, v[132:133] offset:9280
	v_cvt_pk_bf16_f32 v134, v76, v77
	v_cvt_pk_bf16_f32 v135, v78, v79
	ds_write_b64 v236, v[134:135] offset:9312
	v_cvt_pk_bf16_f32 v136, v80, v81
	v_cvt_pk_bf16_f32 v137, v82, v83
	ds_write_b64 v236, v[136:137] offset:11520
	v_cvt_pk_bf16_f32 v138, v84, v85
	v_cvt_pk_bf16_f32 v139, v86, v87
	ds_write_b64 v236, v[138:139] offset:11552
	v_cvt_pk_bf16_f32 v140, v88, v89
	v_cvt_pk_bf16_f32 v141, v90, v91
	ds_write_b64 v236, v[140:141] offset:11584
	v_cvt_pk_bf16_f32 v142, v92, v93
	v_cvt_pk_bf16_f32 v143, v94, v95
	ds_write_b64 v236, v[142:143] offset:11616
	v_cvt_pk_bf16_f32 v144, v96, v97
	v_cvt_pk_bf16_f32 v145, v98, v99
	ds_write_b64 v236, v[144:145] offset:13824
	v_cvt_pk_bf16_f32 v146, v100, v101
	v_cvt_pk_bf16_f32 v147, v102, v103
	ds_write_b64 v236, v[146:147] offset:13856
	v_cvt_pk_bf16_f32 v148, v104, v105
	v_cvt_pk_bf16_f32 v149, v106, v107
	ds_write_b64 v236, v[148:149] offset:13888
	v_cvt_pk_bf16_f32 v150, v108, v109
	v_cvt_pk_bf16_f32 v151, v110, v111
	ds_write_b64 v236, v[150:151] offset:13920
	v_cvt_pk_bf16_f32 v152, v112, v113
	v_cvt_pk_bf16_f32 v153, v114, v115
	ds_write_b64 v236, v[152:153] offset:16128
	v_cvt_pk_bf16_f32 v154, v116, v117
	v_cvt_pk_bf16_f32 v155, v118, v119
	ds_write_b64 v236, v[154:155] offset:16160
	v_cvt_pk_bf16_f32 v156, v120, v121
	v_cvt_pk_bf16_f32 v157, v122, v123
	ds_write_b64 v236, v[156:157] offset:16192
	v_cvt_pk_bf16_f32 v158, v124, v125
	v_cvt_pk_bf16_f32 v159, v126, v127
	ds_write_b64 v236, v[158:159] offset:16224
	s_waitcnt lgkmcnt(0)
	ds_read_b128 v[128:131], v237
	ds_read_b128 v[132:135], v237 offset:1152
	ds_read_b128 v[136:139], v237 offset:2304
	ds_read_b128 v[140:143], v237 offset:3456
	ds_read_b128 v[144:147], v237 offset:4608
	ds_read_b128 v[148:151], v237 offset:5760
	ds_read_b128 v[152:155], v237 offset:6912
	ds_read_b128 v[156:159], v237 offset:8064
	ds_read_b128 v[160:163], v237 offset:9216
	ds_read_b128 v[164:167], v237 offset:10368
	ds_read_b128 v[168:171], v237 offset:11520
	ds_read_b128 v[172:175], v237 offset:12672
	ds_read_b128 v[176:179], v237 offset:13824
	ds_read_b128 v[180:183], v237 offset:14976
	ds_read_b128 v[184:187], v237 offset:16128
	ds_read_b128 v[188:191], v237 offset:17280
	s_waitcnt lgkmcnt(15)
	global_store_dwordx4 v238, v[128:131], s[4:5] nt
	s_add_u32 s4, s4, 0x2000
	s_addc_u32 s5, s5, 0
	s_waitcnt lgkmcnt(14)
	global_store_dwordx4 v238, v[132:135], s[4:5] nt
	s_add_u32 s4, s4, 0x2000
	s_addc_u32 s5, s5, 0
	s_waitcnt lgkmcnt(13)
	global_store_dwordx4 v238, v[136:139], s[4:5] nt
	s_add_u32 s4, s4, 0x2000
	s_addc_u32 s5, s5, 0
	s_waitcnt lgkmcnt(12)
	global_store_dwordx4 v238, v[140:143], s[4:5] nt
	s_add_u32 s4, s4, 0x2000
	s_addc_u32 s5, s5, 0
	s_waitcnt lgkmcnt(11)
	global_store_dwordx4 v238, v[144:147], s[4:5] nt
	s_add_u32 s4, s4, 0x2000
	s_addc_u32 s5, s5, 0
	s_waitcnt lgkmcnt(10)
	global_store_dwordx4 v238, v[148:151], s[4:5] nt
	s_add_u32 s4, s4, 0x2000
	s_addc_u32 s5, s5, 0
	s_waitcnt lgkmcnt(9)
	global_store_dwordx4 v238, v[152:155], s[4:5] nt
	s_add_u32 s4, s4, 0x2000
	s_addc_u32 s5, s5, 0
	s_waitcnt lgkmcnt(8)
	global_store_dwordx4 v238, v[156:159], s[4:5] nt
	s_add_u32 s4, s4, 0x2000
	s_addc_u32 s5, s5, 0
	s_waitcnt lgkmcnt(7)
	global_store_dwordx4 v238, v[160:163], s[4:5] nt
	s_add_u32 s4, s4, 0x2000
	s_addc_u32 s5, s5, 0
	s_waitcnt lgkmcnt(6)
	global_store_dwordx4 v238, v[164:167], s[4:5] nt
	s_add_u32 s4, s4, 0x2000
	s_addc_u32 s5, s5, 0
	s_waitcnt lgkmcnt(5)
	global_store_dwordx4 v238, v[168:171], s[4:5] nt
	s_add_u32 s4, s4, 0x2000
	s_addc_u32 s5, s5, 0
	s_waitcnt lgkmcnt(4)
	global_store_dwordx4 v238, v[172:175], s[4:5] nt
	s_add_u32 s4, s4, 0x2000
	s_addc_u32 s5, s5, 0
	s_waitcnt lgkmcnt(3)
	global_store_dwordx4 v238, v[176:179], s[4:5] nt
	s_add_u32 s4, s4, 0x2000
	s_addc_u32 s5, s5, 0
	s_waitcnt lgkmcnt(2)
	global_store_dwordx4 v238, v[180:183], s[4:5] nt
	s_add_u32 s4, s4, 0x2000
	s_addc_u32 s5, s5, 0
	s_waitcnt lgkmcnt(1)
	global_store_dwordx4 v238, v[184:187], s[4:5] nt
	s_add_u32 s4, s4, 0x2000
	s_addc_u32 s5, s5, 0
	s_waitcnt lgkmcnt(0)
	global_store_dwordx4 v238, v[188:191], s[4:5] nt
	s_nop 1
	s_branch .Lg11_enext
; DI unsigned pack2(float lo, float hi) { const f32x2c v = {lo, hi}; return __builtin_bit_cast(unsigned, __builtin_convertvector(v, bf16x2c)); }
; template <class Epi>
; DI void gemm_tile(char* smem, const bf16_t* __restrict__ A0, int lda0, int ksplit, const bf16_t* __restrict__ A1, int lda1,
;                   const bf16_t* __restrict__ Bt, int K, int row0, int col0, const Epi& epi, int tid) {
;     ...
; #pragma unroll
;   for (int m = 0; m < 8; ++m)
; #pragma unroll
;     for (int n = 0; n < 4; ++n) epi(row0 + wr * 128 + m * 16 + fr, col0 + wc * 64 + n * 16 + fq * 4, acc[m][n]);
; }
; DI void st_bf16x4(bf16_t* o, f32x4 v) { u32x2 q; q.x = pack2(v[0], v[1]); q.y = pack2(v[2], v[3]); *(u32x2*)o = q; }
;   DI void operator()(int row, int col, f32x4 v) const {
;     if (col < n0) st_bf16x4(o0 + (size_t)row * ld0 + col, v);
;     else { const int c = col - n0; if (c < n1) st_bf16x4(o1 + (size_t)row * ld1 + c, v); }
;   }
.Lg11_eo1:
	s_mul_i32 s26, s28, 4160
	s_sub_u32 s25, s27, 512
	s_lshl_b32 s25, s25, 1
	s_add_u32 s26, s26, s25
	s_add_u32 s26, s26, 0x9800000
	s_add_u32 s4, s92, s26
	s_addc_u32 s5, s93, 0
	v_cvt_pk_bf16_f32 v128, v0, v1
	v_cvt_pk_bf16_f32 v129, v2, v3
	ds_write_b64 v236, v[128:129]
	v_cvt_pk_bf16_f32 v130, v4, v5
	v_cvt_pk_bf16_f32 v131, v6, v7
	ds_write_b64 v236, v[130:131] offset:32
	v_cvt_pk_bf16_f32 v132, v8, v9
	v_cvt_pk_bf16_f32 v133, v10, v11
	ds_write_b64 v236, v[132:133] offset:64
	v_cvt_pk_bf16_f32 v134, v12, v13
	v_cvt_pk_bf16_f32 v135, v14, v15
	ds_write_b64 v236, v[134:135] offset:96
	v_cvt_pk_bf16_f32 v136, v16, v17
	v_cvt_pk_bf16_f32 v137, v18, v19
	ds_write_b64 v236, v[136:137] offset:2304
	v_cvt_pk_bf16_f32 v138, v20, v21
	v_cvt_pk_bf16_f32 v139, v22, v23
	ds_write_b64 v236, v[138:139] offset:2336
	v_cvt_pk_bf16_f32 v140, v24, v25
	v_cvt_pk_bf16_f32 v141, v26, v27
	ds_write_b64 v236, v[140:141] offset:2368
	v_cvt_pk_bf16_f32 v142, v28, v29
	v_cvt_pk_bf16_f32 v143, v30, v31
	ds_write_b64 v236, v[142:143] offset:2400
	v_cvt_pk_bf16_f32 v144, v32, v33
	v_cvt_pk_bf16_f32 v145, v34, v35
	ds_write_b64 v236, v[144:145] offset:4608
	v_cvt_pk_bf16_f32 v146, v36, v37
	v_cvt_pk_bf16_f32 v147, v38, v39
	ds_write_b64 v236, v[146:147] offset:4640
	v_cvt_pk_bf16_f32 v148, v40, v41
	v_cvt_pk_bf16_f32 v149, v42, v43
	ds_write_b64 v236, v[148:149] offset:4672
	v_cvt_pk_bf16_f32 v150, v44, v45
	v_cvt_pk_bf16_f32 v151, v46, v47
	ds_write_b64 v236, v[150:151] offset:4704
	v_cvt_pk_bf16_f32 v152, v48, v49
	v_cvt_pk_bf16_f32 v153, v50, v51
	ds_write_b64 v236, v[152:153] offset:6912
	v_cvt_pk_bf16_f32 v154, v52, v53
	v_cvt_pk_bf16_f32 v155, v54, v55
	ds_write_b64 v236, v[154:155] offset:6944
	v_cvt_pk_bf16_f32 v156, v56, v57
	v_cvt_pk_bf16_f32 v157, v58, v59
	ds_write_b64 v236, v[156:157] offset:6976
	v_cvt_pk_bf16_f32 v158, v60, v61
	v_cvt_pk_bf16_f32 v159, v62, v63
	ds_write_b64 v236, v[158:159] offset:7008
	v_cvt_pk_bf16_f32 v128, v64, v65
	v_cvt_pk_bf16_f32 v129, v66, v67
	ds_write_b64 v236, v[128:129] offset:9216
	v_cvt_pk_bf16_f32 v130, v68, v69
	v_cvt_pk_bf16_f32 v131, v70, v71
	ds_write_b64 v236, v[130:131] offset:9248
	v_cvt_pk_bf16_f32 v132, v72, v73
	v_cvt_pk_bf16_f32 v133, v74, v75
	ds_write_b64 v236, v[132:133] offset:9280
	v_cvt_pk_bf16_f32 v134, v76, v77
	v_cvt_pk_bf16_f32 v135, v78, v79
	ds_write_b64 v236, v[134:135] offset:9312
	v_cvt_pk_bf16_f32 v136, v80, v81
	v_cvt_pk_bf16_f32 v137, v82, v83
	ds_write_b64 v236, v[136:137] offset:11520
	v_cvt_pk_bf16_f32 v138, v84, v85
	v_cvt_pk_bf16_f32 v139, v86, v87
	ds_write_b64 v236, v[138:139] offset:11552
	v_cvt_pk_bf16_f32 v140, v88, v89
	v_cvt_pk_bf16_f32 v141, v90, v91
	ds_write_b64 v236, v[140:141] offset:11584
	v_cvt_pk_bf16_f32 v142, v92, v93
	v_cvt_pk_bf16_f32 v143, v94, v95
	ds_write_b64 v236, v[142:143] offset:11616
	v_cvt_pk_bf16_f32 v144, v96, v97
	v_cvt_pk_bf16_f32 v145, v98, v99
	ds_write_b64 v236, v[144:145] offset:13824
	v_cvt_pk_bf16_f32 v146, v100, v101
	v_cvt_pk_bf16_f32 v147, v102, v103
	ds_write_b64 v236, v[146:147] offset:13856
	v_cvt_pk_bf16_f32 v148, v104, v105
	v_cvt_pk_bf16_f32 v149, v106, v107
	ds_write_b64 v236, v[148:149] offset:13888
	v_cvt_pk_bf16_f32 v150, v108, v109
	v_cvt_pk_bf16_f32 v151, v110, v111
	ds_write_b64 v236, v[150:151] offset:13920
	v_cvt_pk_bf16_f32 v152, v112, v113
	v_cvt_pk_bf16_f32 v153, v114, v115
	ds_write_b64 v236, v[152:153] offset:16128
	v_cvt_pk_bf16_f32 v154, v116, v117
	v_cvt_pk_bf16_f32 v155, v118, v119
	ds_write_b64 v236, v[154:155] offset:16160
	v_cvt_pk_bf16_f32 v156, v120, v121
	v_cvt_pk_bf16_f32 v157, v122, v123
	ds_write_b64 v236, v[156:157] offset:16192
	v_cvt_pk_bf16_f32 v158, v124, v125
	v_cvt_pk_bf16_f32 v159, v126, v127
	ds_write_b64 v236, v[158:159] offset:16224
	s_waitcnt lgkmcnt(0)
	ds_read_b128 v[128:131], v237
	ds_read_b128 v[132:135], v237 offset:1152
	ds_read_b128 v[136:139], v237 offset:2304
	ds_read_b128 v[140:143], v237 offset:3456
	ds_read_b128 v[144:147], v237 offset:4608
	ds_read_b128 v[148:151], v237 offset:5760
	ds_read_b128 v[152:155], v237 offset:6912
	ds_read_b128 v[156:159], v237 offset:8064
	ds_read_b128 v[160:163], v237 offset:9216
	ds_read_b128 v[164:167], v237 offset:10368
	ds_read_b128 v[168:171], v237 offset:11520
	ds_read_b128 v[172:175], v237 offset:12672
	ds_read_b128 v[176:179], v237 offset:13824
	ds_read_b128 v[180:183], v237 offset:14976
	ds_read_b128 v[184:187], v237 offset:16128
	ds_read_b128 v[188:191], v237 offset:17280
	s_sub_u32 s25, s27, 512
	s_sub_u32 s25, 2080, s25
	v_cmp_gt_i32_e32 vcc, s25, v248
	s_and_saveexec_b64 s[2:3], vcc
	s_waitcnt lgkmcnt(15)
	global_store_dwordx4 v239, v[128:131], s[4:5] nt
	s_add_u32 s4, s4, 0x8200
	s_addc_u32 s5, s5, 0
	s_waitcnt lgkmcnt(14)
	global_store_dwordx4 v239, v[132:135], s[4:5] nt
	s_add_u32 s4, s4, 0x8200
	s_addc_u32 s5, s5, 0
	s_waitcnt lgkmcnt(13)
	global_store_dwordx4 v239, v[136:139], s[4:5] nt
	s_add_u32 s4, s4, 0x8200
	s_addc_u32 s5, s5, 0
	s_waitcnt lgkmcnt(12)
	global_store_dwordx4 v239, v[140:143], s[4:5] nt
	s_add_u32 s4, s4, 0x8200
	s_addc_u32 s5, s5, 0
	s_waitcnt lgkmcnt(11)
	global_store_dwordx4 v239, v[144:147], s[4:5] nt
	s_add_u32 s4, s4, 0x8200
	s_addc_u32 s5, s5, 0
	s_waitcnt lgkmcnt(10)
	global_store_dwordx4 v239, v[148:151], s[4:5] nt
	s_add_u32 s4, s4, 0x8200
	s_addc_u32 s5, s5, 0
	s_waitcnt lgkmcnt(9)
	global_store_dwordx4 v239, v[152:155], s[4:5] nt
	s_add_u32 s4, s4, 0x8200
	s_addc_u32 s5, s5, 0
	s_waitcnt lgkmcnt(8)
	global_store_dwordx4 v239, v[156:159], s[4:5] nt
	s_add_u32 s4, s4, 0x8200
	s_addc_u32 s5, s5, 0
	s_waitcnt lgkmcnt(7)
	global_store_dwordx4 v239, v[160:163], s[4:5] nt
	s_add_u32 s4, s4, 0x8200
	s_addc_u32 s5, s5, 0
	s_waitcnt lgkmcnt(6)
	global_store_dwordx4 v239, v[164:167], s[4:5] nt
	s_add_u32 s4, s4, 0x8200
	s_addc_u32 s5, s5, 0
	s_waitcnt lgkmcnt(5)
	global_store_dwordx4 v239, v[168:171], s[4:5] nt
	s_add_u32 s4, s4, 0x8200
	s_addc_u32 s5, s5, 0
	s_waitcnt lgkmcnt(4)
	global_store_dwordx4 v239, v[172:175], s[4:5] nt
	s_add_u32 s4, s4, 0x8200
	s_addc_u32 s5, s5, 0
	s_waitcnt lgkmcnt(3)
	global_store_dwordx4 v239, v[176:179], s[4:5] nt
	s_add_u32 s4, s4, 0x8200
	s_addc_u32 s5, s5, 0
	s_waitcnt lgkmcnt(2)
	global_store_dwordx4 v239, v[180:183], s[4:5] nt
	s_add_u32 s4, s4, 0x8200
	s_addc_u32 s5, s5, 0
	s_waitcnt lgkmcnt(1)
	global_store_dwordx4 v239, v[184:187], s[4:5] nt
	s_add_u32 s4, s4, 0x8200
	s_addc_u32 s5, s5, 0
	s_waitcnt lgkmcnt(0)
	global_store_dwordx4 v239, v[188:191], s[4:5] nt
	s_or_b64 exec, exec, s[2:3]
	s_nop 1
